# adds: epilogue / attention / combine stores whose consumers sit behind a grid barrier are issued write-through (sc0 sc1) so the barrier's L2 write-back has little left to flush
# baseline (speedup 1.0000x reference)
; __device__ __forceinline__ unsigned pk2(float lo, float hi) { f32x2_t v = {lo, hi}; bf16x2_t b = __builtin_convertvector(v, bf16x2_t); return __builtin_bit_cast(unsigned, b); }
;     __device__ __forceinline__ void operator()(AccRef acc, const pg8::Unit& u, int wr, int wc, int fr, int fq) const {
;     ...
;         for (int ai = 0; ai < 2; ++ai)
; #pragma unroll
;             for (int m = 0; m < 4; ++m) {
;                 const int row = row0 + ai * 128 + m * 16;
;                 const float rsr = rst[row & 255];
;                 f32x4 xv[2][2];
; #pragma unroll
;                 for (int bj = 0; bj < 2; ++bj)
; #pragma unroll
;                     for (int n = 0; n < 2; ++n) xv[bj][n] = acc[ai][bj][m][n] * rsr;
;                 float rs = 1.f;
;                 if (gain) {
;                     float ss = 0.f;
; #pragma unroll
;                     for (int bj = 0; bj < 2; ++bj)
; #pragma unroll
;                         for (int n = 0; n < 2; ++n) { const f32x4 x = xv[bj][n]; ss += (x[0] * x[0] + x[1] * x[1]) + (x[2] * x[2] + x[3] * x[3]); }
;                     ss += __shfl_xor(ss, 16); ss += __shfl_xor(ss, 32);
;                     rs = rsqrtf(ss * (1.0f / 64.0f) + RMS_EPS);
;                 }
; #pragma unroll
;                 for (int bj = 0; bj < 2; ++bj) {
;                     const f32x4 v0 = xv[bj][0] * rs * gv[bj][0], v1 = xv[bj][1] * rs * gv[bj][1];
;                     v4u w; w.x = pk2(v0[0], v0[1]); w.y = pk2(v0[2], v0[3]); w.z = pk2(v1[0], v1[1]); w.w = pk2(v1[2], v1[3]);
;                     *(v4u*)(dst + (size_t)row * pitch + 32 * bj) = w;
;                 }
.LBB0_238:
	s_lshl_b32 s22, s30, 6
	s_ashr_i32 s23, s22, 31
	v_readlane_b32 vcc_lo, v255, 23
	v_readlane_b32 vcc_hi, v255, 24
	s_add_u32 s3, vcc_lo, s12
	s_addc_u32 s30, vcc_hi, s13
	s_lshl_b64 s[12:13], s[22:23], 1
	s_add_u32 s12, s3, s12
	s_addc_u32 s13, s30, s13
	v_ashrrev_i32_e32 v23, 31, v18
	v_mul_lo_u32 v41, s11, v18
	v_lshl_add_u64 v[20:21], v[20:21], 1, s[12:13]
	s_waitcnt vmcnt(0)
	v_pk_mul_f32 v[8:9], s[14:15], v[8:9] op_sel_hi:[0,1]
	v_pk_mul_f32 v[6:7], s[14:15], v[6:7] op_sel_hi:[0,1]
	v_pk_mul_f32 v[4:5], s[14:15], v[4:5] op_sel_hi:[0,1]
	v_pk_mul_f32 v[2:3], s[14:15], v[2:3] op_sel_hi:[0,1]
	v_mul_lo_u32 v23, s10, v23
	v_mad_u64_u32 v[42:43], s[12:13], s10, v18, 0
	v_pk_mul_f32 v[34:35], v[34:35], v[40:41] op_sel_hi:[1,0]
	v_pk_mul_f32 v[38:39], v[38:39], v[40:41] op_sel_hi:[1,0]
	v_pk_mul_f32 v[32:33], v[32:33], v[40:41] op_sel_hi:[1,0]
	v_pk_mul_f32 v[36:37], v[36:37], v[40:41] op_sel_hi:[1,0]
	v_add3_u32 v43, v43, v23, v41
	v_pk_mul_f32 v[34:35], v[4:5], v[34:35]
	v_pk_mul_f32 v[38:39], v[2:3], v[38:39]
	v_pk_mul_f32 v[44:45], v[8:9], v[32:33]
	v_pk_mul_f32 v[36:37], v[6:7], v[36:37]
	v_pk_mul_f32 v[16:17], s[14:15], v[16:17] op_sel_hi:[0,1]
	v_lshl_add_u64 v[42:43], v[42:43], 1, v[20:21]
	v_cvt_pk_bf16_f32 v32, v38, v39
	v_cvt_pk_bf16_f32 v33, v34, v35
	v_cvt_pk_bf16_f32 v34, v36, v37
	v_cvt_pk_bf16_f32 v35, v44, v45
	v_pk_mul_f32 v[24:25], v[24:25], v[40:41] op_sel_hi:[1,0]
	v_add_u32_e32 v23, 16, v18
	global_store_dwordx4 v[42:43], v[32:35], off sc0 sc1
	v_pk_mul_f32 v[10:11], s[14:15], v[10:11] op_sel_hi:[0,1]
	v_pk_mul_f32 v[30:31], v[30:31], v[40:41] op_sel_hi:[1,0]
	v_pk_mul_f32 v[32:33], v[16:17], v[24:25]
	v_and_b32_e32 v25, 0xff, v23
	v_lshl_add_u32 v25, v25, 2, 0
	v_pk_mul_f32 v[30:31], v[10:11], v[30:31]
	v_add_u32_e32 v25, 0x20100, v25
	v_cvt_pk_bf16_f32 v24, v30, v31
	ds_read_b32 v30, v25
	v_pk_mul_f32 v[14:15], s[14:15], v[14:15] op_sel_hi:[0,1]
	v_pk_mul_f32 v[12:13], s[14:15], v[12:13] op_sel_hi:[0,1]
	v_pk_mul_f32 v[26:27], v[26:27], v[40:41] op_sel_hi:[1,0]
	v_pk_mul_f32 v[28:29], v[28:29], v[40:41] op_sel_hi:[1,0]
	v_pk_mul_f32 v[26:27], v[12:13], v[26:27]
	v_pk_mul_f32 v[28:29], v[14:15], v[28:29]
	v_cvt_pk_bf16_f32 v25, v26, v27
	v_cvt_pk_bf16_f32 v26, v28, v29
	v_cvt_pk_bf16_f32 v27, v32, v33
	global_store_dwordx4 v[42:43], v[24:27], off offset:64 sc0 sc1
	s_waitcnt lgkmcnt(0)
	v_pk_mul_f32 v[36:37], v[176:177], v[30:31] op_sel_hi:[1,0]
	v_pk_mul_f32 v[38:39], v[174:175], v[30:31] op_sel_hi:[1,0]
	v_pk_mul_f32 v[32:33], v[172:173], v[30:31] op_sel_hi:[1,0]
	v_pk_mul_f32 v[34:35], v[170:171], v[30:31] op_sel_hi:[1,0]
	v_pk_mul_f32 v[26:27], v[168:169], v[30:31] op_sel_hi:[1,0]
	v_pk_mul_f32 v[28:29], v[166:167], v[30:31] op_sel_hi:[1,0]
	v_pk_mul_f32 v[24:25], v[164:165], v[30:31] op_sel_hi:[1,0]
	s_and_b64 vcc, exec, s[6:7]
	v_pk_mul_f32 v[30:31], v[162:163], v[30:31] op_sel_hi:[1,0]
	s_cbranch_vccnz .LBB0_240
	v_pk_mul_f32 v[40:41], v[36:37], v[36:37]
	v_pk_mul_f32 v[42:43], v[38:39], v[38:39]
	v_mul_f32_e32 v22, v28, v28
	v_pk_mov_b32 v[44:45], v[42:43], v[40:41] op_sel:[1,0]
	v_mov_b32_e32 v43, v41
	v_pk_add_f32 v[40:41], v[44:45], v[42:43]
	v_pk_mul_f32 v[42:43], v[32:33], v[32:33]
	v_pk_mul_f32 v[44:45], v[34:35], v[34:35]
	v_pk_add_f32 v[40:41], v[40:41], v[40:41] op_sel_hi:[0,1]
	v_pk_mov_b32 v[46:47], v[44:45], v[42:43] op_sel:[1,0]
	v_mov_b32_e32 v45, v43
	v_pk_add_f32 v[42:43], v[46:47], v[44:45]
	v_pk_fma_f32 v[44:45], v[28:29], v[28:29], v[22:23] op_sel_hi:[1,1,0]
	v_mul_f32_e32 v22, v26, v26
	v_pk_add_f32 v[42:43], v[42:43], v[42:43] op_sel_hi:[0,1]
	v_pk_fma_f32 v[46:47], v[26:27], v[26:27], v[22:23] op_sel_hi:[1,1,0]
	v_mul_f32_e32 v44, v30, v30
	v_mul_f32_e32 v46, v31, v31
	v_mul_f32_e32 v40, v24, v24
	v_mul_f32_e32 v42, v25, v25
	v_pk_add_f32 v[44:45], v[44:45], v[46:47]
	v_pk_add_f32 v[40:41], v[40:41], v[42:43]
	s_mov_b32 s3, 0x800000
	v_pk_add_f32 v[40:41], v[44:45], v[40:41]
	s_nop 0
	v_add_f32_e32 v22, v40, v41
	v_and_b32_e32 v41, 64, v236
	v_xor_b32_e32 v40, 16, v236
	v_add_u32_e32 v41, 64, v41
	v_cmp_lt_i32_e32 vcc, v40, v41
	s_nop 1
	v_cndmask_b32_e32 v40, v236, v40, vcc
	v_lshlrev_b32_e32 v40, 2, v40
	ds_bpermute_b32 v40, v40, v22
	s_waitcnt lgkmcnt(0)
	v_add_f32_e32 v22, v22, v40
	v_xor_b32_e32 v40, 32, v236
	v_cmp_lt_i32_e32 vcc, v40, v41
	s_nop 1
	v_cndmask_b32_e32 v40, v236, v40, vcc
	v_lshlrev_b32_e32 v40, 2, v40
	ds_bpermute_b32 v40, v40, v22
	s_waitcnt lgkmcnt(0)
	v_add_f32_e32 v22, v22, v40
	v_fmamk_f32 v22, v22, 0x3c800000, v215
	v_mul_f32_e32 v40, 0x4b800000, v22
	v_cmp_gt_f32_e32 vcc, s3, v22
	s_nop 1
	v_cndmask_b32_e32 v22, v22, v40, vcc
	v_rsq_f32_e32 v22, v22
	s_nop 0
	v_mul_f32_e32 v40, 0x45800000, v22
	v_cndmask_b32_e32 v22, v22, v40, vcc
; __device__ __forceinline__ unsigned pk2(float lo, float hi) { f32x2_t v = {lo, hi}; bf16x2_t b = __builtin_convertvector(v, bf16x2_t); return __builtin_bit_cast(unsigned, b); }
;     __device__ __forceinline__ void operator()(AccRef acc, const pg8::Unit& u, int wr, int wc, int fr, int fq) const {
;     ...
;         for (int ai = 0; ai < 2; ++ai)
; #pragma unroll
;             for (int m = 0; m < 4; ++m) {
;                 const int row = row0 + ai * 128 + m * 16;
;                 const float rsr = rst[row & 255];
;                 f32x4 xv[2][2];
; #pragma unroll
;                 for (int bj = 0; bj < 2; ++bj)
; #pragma unroll
;                     for (int n = 0; n < 2; ++n) xv[bj][n] = acc[ai][bj][m][n] * rsr;
;                 float rs = 1.f;
;                 if (gain) {
;                     float ss = 0.f;
; #pragma unroll
;                     for (int bj = 0; bj < 2; ++bj)
; #pragma unroll
;                         for (int n = 0; n < 2; ++n) { const f32x4 x = xv[bj][n]; ss += (x[0] * x[0] + x[1] * x[1]) + (x[2] * x[2] + x[3] * x[3]); }
;                     ss += __shfl_xor(ss, 16); ss += __shfl_xor(ss, 32);
;                     rs = rsqrtf(ss * (1.0f / 64.0f) + RMS_EPS);
;                 }
; #pragma unroll
;                 for (int bj = 0; bj < 2; ++bj) {
;                     const f32x4 v0 = xv[bj][0] * rs * gv[bj][0], v1 = xv[bj][1] * rs * gv[bj][1];
;                     v4u w; w.x = pk2(v0[0], v0[1]); w.y = pk2(v0[2], v0[3]); w.z = pk2(v1[0], v1[1]); w.w = pk2(v1[2], v1[3]);
;                     *(v4u*)(dst + (size_t)row * pitch + 32 * bj) = w;
;                 }
.LBB0_240:
	v_ashrrev_i32_e32 v40, 31, v23
	v_mul_lo_u32 v42, s11, v23
	v_mul_lo_u32 v43, s10, v40
	v_mad_u64_u32 v[40:41], s[12:13], s10, v23, 0
	v_pk_mul_f32 v[36:37], v[36:37], v[22:23] op_sel_hi:[1,0]
	v_pk_mul_f32 v[38:39], v[38:39], v[22:23] op_sel_hi:[1,0]
	v_pk_mul_f32 v[32:33], v[32:33], v[22:23] op_sel_hi:[1,0]
	v_pk_mul_f32 v[34:35], v[34:35], v[22:23] op_sel_hi:[1,0]
	v_add3_u32 v41, v41, v43, v42
	v_pk_mul_f32 v[36:37], v[4:5], v[36:37]
	v_pk_mul_f32 v[38:39], v[2:3], v[38:39]
	v_pk_mul_f32 v[42:43], v[8:9], v[32:33]
	v_pk_mul_f32 v[34:35], v[6:7], v[34:35]
	v_lshl_add_u64 v[40:41], v[40:41], 1, v[20:21]
	v_cvt_pk_bf16_f32 v32, v38, v39
	v_cvt_pk_bf16_f32 v33, v36, v37
	v_cvt_pk_bf16_f32 v34, v34, v35
	v_cvt_pk_bf16_f32 v35, v42, v43
	v_pk_mul_f32 v[26:27], v[26:27], v[22:23] op_sel_hi:[1,0]
	v_pk_mul_f32 v[28:29], v[28:29], v[22:23] op_sel_hi:[1,0]
	v_pk_mul_f32 v[24:25], v[24:25], v[22:23] op_sel_hi:[1,0]
	v_pk_mul_f32 v[22:23], v[30:31], v[22:23] op_sel_hi:[1,0]
	global_store_dwordx4 v[40:41], v[32:35], off sc0 sc1
	v_pk_mul_f32 v[26:27], v[12:13], v[26:27]
	v_pk_mul_f32 v[28:29], v[10:11], v[28:29]
	v_pk_mul_f32 v[32:33], v[14:15], v[22:23]
	v_add_u32_e32 v23, 32, v18
	v_and_b32_e32 v22, 0xff, v23
	v_lshl_add_u32 v22, v22, 2, 0
	v_add_u32_e32 v22, 0x20100, v22
	ds_read_b32 v22, v22
	v_pk_mul_f32 v[30:31], v[16:17], v[24:25]
	v_cvt_pk_bf16_f32 v24, v28, v29
	v_cvt_pk_bf16_f32 v25, v26, v27
	v_cvt_pk_bf16_f32 v26, v32, v33
	v_cvt_pk_bf16_f32 v27, v30, v31
	global_store_dwordx4 v[40:41], v[24:27], off offset:64 sc0 sc1
	s_waitcnt lgkmcnt(0)
	v_pk_mul_f32 v[34:35], v[160:161], v[22:23] op_sel_hi:[1,0]
	v_pk_mul_f32 v[38:39], v[158:159], v[22:23] op_sel_hi:[1,0]
	v_pk_mul_f32 v[32:33], v[156:157], v[22:23] op_sel_hi:[1,0]
	v_pk_mul_f32 v[36:37], v[154:155], v[22:23] op_sel_hi:[1,0]
	v_pk_mul_f32 v[26:27], v[152:153], v[22:23] op_sel_hi:[1,0]
	v_pk_mul_f32 v[30:31], v[150:151], v[22:23] op_sel_hi:[1,0]
	v_pk_mul_f32 v[24:25], v[148:149], v[22:23] op_sel_hi:[1,0]
	v_pk_mul_f32 v[28:29], v[146:147], v[22:23] op_sel_hi:[1,0]
	v_mov_b32_e32 v22, 1.0
	s_and_b64 vcc, exec, s[6:7]
	v_mov_b32_e32 v40, 1.0
	s_cbranch_vccnz .LBB0_242
	v_pk_mul_f32 v[40:41], v[34:35], v[34:35]
	v_pk_mul_f32 v[42:43], v[38:39], v[38:39]
	s_mov_b32 s3, 0x800000
	v_pk_mov_b32 v[44:45], v[42:43], v[40:41] op_sel:[1,0]
	v_mov_b32_e32 v43, v41
	v_pk_add_f32 v[40:41], v[44:45], v[42:43]
	v_pk_mul_f32 v[42:43], v[32:33], v[32:33]
	v_pk_add_f32 v[40:41], v[40:41], v[40:41] op_sel_hi:[0,1]
	v_pk_mul_f32 v[44:45], v[36:37], v[36:37]
	v_mul_f32_e32 v40, v30, v30
	v_pk_mov_b32 v[46:47], v[44:45], v[42:43] op_sel:[1,0]
	v_mov_b32_e32 v45, v43
	v_pk_add_f32 v[42:43], v[46:47], v[44:45]
	v_pk_fma_f32 v[44:45], v[30:31], v[30:31], v[40:41] op_sel_hi:[1,1,0]
	v_mul_f32_e32 v40, v26, v26
	v_pk_add_f32 v[42:43], v[42:43], v[42:43] op_sel_hi:[0,1]
	v_pk_fma_f32 v[46:47], v[26:27], v[26:27], v[40:41] op_sel_hi:[1,1,0]
	v_mul_f32_e32 v44, v28, v28
	v_mul_f32_e32 v46, v29, v29
	v_mul_f32_e32 v40, v24, v24
	v_mul_f32_e32 v42, v25, v25
	v_pk_add_f32 v[44:45], v[44:45], v[46:47]
	v_pk_add_f32 v[40:41], v[40:41], v[42:43]
	v_and_b32_e32 v42, 64, v236
	v_pk_add_f32 v[40:41], v[44:45], v[40:41]
	v_add_u32_e32 v42, 64, v42
	v_add_f32_e32 v40, v40, v41
	v_xor_b32_e32 v41, 16, v236
	v_cmp_lt_i32_e32 vcc, v41, v42
	s_nop 1
	v_cndmask_b32_e32 v41, v236, v41, vcc
	v_lshlrev_b32_e32 v41, 2, v41
	ds_bpermute_b32 v41, v41, v40
	s_waitcnt lgkmcnt(0)
	v_add_f32_e32 v40, v40, v41
	v_xor_b32_e32 v41, 32, v236
	v_cmp_lt_i32_e32 vcc, v41, v42
	s_nop 1
	v_cndmask_b32_e32 v41, v236, v41, vcc
	v_lshlrev_b32_e32 v41, 2, v41
	ds_bpermute_b32 v41, v41, v40
	s_waitcnt lgkmcnt(0)
	v_add_f32_e32 v40, v40, v41
	v_fmamk_f32 v40, v40, 0x3c800000, v215
	v_mul_f32_e32 v41, 0x4b800000, v40
	v_cmp_gt_f32_e32 vcc, s3, v40
	s_nop 1
	v_cndmask_b32_e32 v40, v40, v41, vcc
	v_rsq_f32_e32 v40, v40
	s_nop 0
	v_mul_f32_e32 v41, 0x45800000, v40
	v_cndmask_b32_e32 v40, v40, v41, vcc
.LBB0_242:
	v_ashrrev_i32_e32 v41, 31, v23
	v_mul_lo_u32 v41, s10, v41
	v_mul_lo_u32 v44, s11, v23
	v_mad_u64_u32 v[42:43], s[12:13], s10, v23, 0
	v_pk_mul_f32 v[34:35], v[34:35], v[40:41] op_sel_hi:[1,0]
	v_pk_mul_f32 v[38:39], v[38:39], v[40:41] op_sel_hi:[1,0]
	v_pk_mul_f32 v[32:33], v[32:33], v[40:41] op_sel_hi:[1,0]
	v_pk_mul_f32 v[36:37], v[36:37], v[40:41] op_sel_hi:[1,0]
	v_add3_u32 v43, v43, v41, v44
	v_pk_mul_f32 v[34:35], v[4:5], v[34:35]
	v_pk_mul_f32 v[38:39], v[2:3], v[38:39]
	v_pk_mul_f32 v[44:45], v[8:9], v[32:33]
	v_pk_mul_f32 v[36:37], v[6:7], v[36:37]
	v_lshl_add_u64 v[42:43], v[42:43], 1, v[20:21]
	v_cvt_pk_bf16_f32 v32, v38, v39
	v_cvt_pk_bf16_f32 v33, v34, v35
	v_cvt_pk_bf16_f32 v34, v36, v37
	v_cvt_pk_bf16_f32 v35, v44, v45
	v_pk_mul_f32 v[24:25], v[24:25], v[40:41] op_sel_hi:[1,0]
	v_add_u32_e32 v23, 48, v18
	global_store_dwordx4 v[42:43], v[32:35], off sc0 sc1
	v_pk_mul_f32 v[30:31], v[30:31], v[40:41] op_sel_hi:[1,0]
	v_pk_mul_f32 v[26:27], v[26:27], v[40:41] op_sel_hi:[1,0]
	v_pk_mul_f32 v[32:33], v[16:17], v[24:25]
	v_and_b32_e32 v25, 0xff, v23
	v_lshl_add_u32 v25, v25, 2, 0
	v_pk_mul_f32 v[30:31], v[10:11], v[30:31]
	v_add_u32_e32 v25, 0x20100, v25
	v_cvt_pk_bf16_f32 v24, v30, v31
	ds_read_b32 v30, v25
	v_pk_mul_f32 v[28:29], v[28:29], v[40:41] op_sel_hi:[1,0]
	v_pk_mul_f32 v[26:27], v[12:13], v[26:27]
	v_pk_mul_f32 v[28:29], v[14:15], v[28:29]
	v_cvt_pk_bf16_f32 v25, v26, v27
	v_cvt_pk_bf16_f32 v26, v28, v29
	v_cvt_pk_bf16_f32 v27, v32, v33
	global_store_dwordx4 v[42:43], v[24:27], off offset:64 sc0 sc1
	s_waitcnt lgkmcnt(0)
	v_pk_mul_f32 v[36:37], v[144:145], v[30:31] op_sel_hi:[1,0]
	v_pk_mul_f32 v[38:39], v[142:143], v[30:31] op_sel_hi:[1,0]
	v_pk_mul_f32 v[32:33], v[140:141], v[30:31] op_sel_hi:[1,0]
	v_pk_mul_f32 v[34:35], v[138:139], v[30:31] op_sel_hi:[1,0]
	v_pk_mul_f32 v[26:27], v[136:137], v[30:31] op_sel_hi:[1,0]
	v_pk_mul_f32 v[28:29], v[134:135], v[30:31] op_sel_hi:[1,0]
	v_pk_mul_f32 v[24:25], v[132:133], v[30:31] op_sel_hi:[1,0]
	s_and_b64 vcc, exec, s[6:7]
	v_pk_mul_f32 v[30:31], v[130:131], v[30:31] op_sel_hi:[1,0]
	s_cbranch_vccnz .LBB0_244
; __device__ __forceinline__ unsigned pk2(float lo, float hi) { f32x2_t v = {lo, hi}; bf16x2_t b = __builtin_convertvector(v, bf16x2_t); return __builtin_bit_cast(unsigned, b); }
;     __device__ __forceinline__ void operator()(AccRef acc, const pg8::Unit& u, int wr, int wc, int fr, int fq) const {
;     ...
;         for (int ai = 0; ai < 2; ++ai)
; #pragma unroll
;             for (int m = 0; m < 4; ++m) {
;                 const int row = row0 + ai * 128 + m * 16;
;                 const float rsr = rst[row & 255];
;                 f32x4 xv[2][2];
; #pragma unroll
;                 for (int bj = 0; bj < 2; ++bj)
; #pragma unroll
;                     for (int n = 0; n < 2; ++n) xv[bj][n] = acc[ai][bj][m][n] * rsr;
;                 float rs = 1.f;
;                 if (gain) {
;                     float ss = 0.f;
; #pragma unroll
;                     for (int bj = 0; bj < 2; ++bj)
; #pragma unroll
;                         for (int n = 0; n < 2; ++n) { const f32x4 x = xv[bj][n]; ss += (x[0] * x[0] + x[1] * x[1]) + (x[2] * x[2] + x[3] * x[3]); }
;                     ss += __shfl_xor(ss, 16); ss += __shfl_xor(ss, 32);
;                     rs = rsqrtf(ss * (1.0f / 64.0f) + RMS_EPS);
;                 }
; #pragma unroll
;                 for (int bj = 0; bj < 2; ++bj) {
;                     const f32x4 v0 = xv[bj][0] * rs * gv[bj][0], v1 = xv[bj][1] * rs * gv[bj][1];
;                     v4u w; w.x = pk2(v0[0], v0[1]); w.y = pk2(v0[2], v0[3]); w.z = pk2(v1[0], v1[1]); w.w = pk2(v1[2], v1[3]);
;                     *(v4u*)(dst + (size_t)row * pitch + 32 * bj) = w;
;                 }
	v_pk_mul_f32 v[40:41], v[36:37], v[36:37]
	v_pk_mul_f32 v[42:43], v[38:39], v[38:39]
	v_mul_f32_e32 v22, v28, v28
	v_pk_mov_b32 v[44:45], v[42:43], v[40:41] op_sel:[1,0]
	v_mov_b32_e32 v43, v41
	v_pk_add_f32 v[40:41], v[44:45], v[42:43]
	v_pk_mul_f32 v[42:43], v[32:33], v[32:33]
	v_pk_mul_f32 v[44:45], v[34:35], v[34:35]
	v_pk_add_f32 v[40:41], v[40:41], v[40:41] op_sel_hi:[0,1]
	v_pk_mov_b32 v[46:47], v[44:45], v[42:43] op_sel:[1,0]
	v_mov_b32_e32 v45, v43
	v_pk_add_f32 v[42:43], v[46:47], v[44:45]
	v_pk_fma_f32 v[44:45], v[28:29], v[28:29], v[22:23] op_sel_hi:[1,1,0]
	v_mul_f32_e32 v22, v26, v26
	v_pk_add_f32 v[42:43], v[42:43], v[42:43] op_sel_hi:[0,1]
	v_pk_fma_f32 v[46:47], v[26:27], v[26:27], v[22:23] op_sel_hi:[1,1,0]
	v_mul_f32_e32 v44, v30, v30
	v_mul_f32_e32 v46, v31, v31
	v_mul_f32_e32 v40, v24, v24
	v_mul_f32_e32 v42, v25, v25
	v_pk_add_f32 v[44:45], v[44:45], v[46:47]
	v_pk_add_f32 v[40:41], v[40:41], v[42:43]
	s_mov_b32 s3, 0x800000
	v_pk_add_f32 v[40:41], v[44:45], v[40:41]
	s_nop 0
	v_add_f32_e32 v22, v40, v41
	v_and_b32_e32 v41, 64, v236
	v_xor_b32_e32 v40, 16, v236
	v_add_u32_e32 v41, 64, v41
	v_cmp_lt_i32_e32 vcc, v40, v41
	s_nop 1
	v_cndmask_b32_e32 v40, v236, v40, vcc
	v_lshlrev_b32_e32 v40, 2, v40
	ds_bpermute_b32 v40, v40, v22
	s_waitcnt lgkmcnt(0)
	v_add_f32_e32 v22, v22, v40
	v_xor_b32_e32 v40, 32, v236
	v_cmp_lt_i32_e32 vcc, v40, v41
	s_nop 1
	v_cndmask_b32_e32 v40, v236, v40, vcc
	v_lshlrev_b32_e32 v40, 2, v40
	ds_bpermute_b32 v40, v40, v22
	s_waitcnt lgkmcnt(0)
	v_add_f32_e32 v22, v22, v40
	v_fmamk_f32 v22, v22, 0x3c800000, v215
	v_mul_f32_e32 v40, 0x4b800000, v22
	v_cmp_gt_f32_e32 vcc, s3, v22
	s_nop 1
	v_cndmask_b32_e32 v22, v22, v40, vcc
	v_rsq_f32_e32 v22, v22
	s_nop 0
	v_mul_f32_e32 v40, 0x45800000, v22
	v_cndmask_b32_e32 v22, v22, v40, vcc
.LBB0_244:
	v_ashrrev_i32_e32 v40, 31, v23
	v_mul_lo_u32 v42, s11, v23
	v_mul_lo_u32 v43, s10, v40
	v_mad_u64_u32 v[40:41], s[12:13], s10, v23, 0
	v_pk_mul_f32 v[36:37], v[36:37], v[22:23] op_sel_hi:[1,0]
	v_pk_mul_f32 v[38:39], v[38:39], v[22:23] op_sel_hi:[1,0]
	v_pk_mul_f32 v[32:33], v[32:33], v[22:23] op_sel_hi:[1,0]
	v_pk_mul_f32 v[34:35], v[34:35], v[22:23] op_sel_hi:[1,0]
	v_add3_u32 v41, v41, v43, v42
	v_pk_mul_f32 v[36:37], v[4:5], v[36:37]
	v_pk_mul_f32 v[38:39], v[2:3], v[38:39]
	v_pk_mul_f32 v[42:43], v[8:9], v[32:33]
	v_pk_mul_f32 v[34:35], v[6:7], v[34:35]
	v_lshl_add_u64 v[40:41], v[40:41], 1, v[20:21]
	v_cvt_pk_bf16_f32 v32, v38, v39
	v_cvt_pk_bf16_f32 v33, v36, v37
	v_cvt_pk_bf16_f32 v34, v34, v35
	v_cvt_pk_bf16_f32 v35, v42, v43
	v_pk_mul_f32 v[26:27], v[26:27], v[22:23] op_sel_hi:[1,0]
	v_pk_mul_f32 v[28:29], v[28:29], v[22:23] op_sel_hi:[1,0]
	v_pk_mul_f32 v[24:25], v[24:25], v[22:23] op_sel_hi:[1,0]
	v_pk_mul_f32 v[22:23], v[30:31], v[22:23] op_sel_hi:[1,0]
	global_store_dwordx4 v[40:41], v[32:35], off sc0 sc1
	v_pk_mul_f32 v[26:27], v[12:13], v[26:27]
	v_pk_mul_f32 v[28:29], v[10:11], v[28:29]
	v_pk_mul_f32 v[32:33], v[14:15], v[22:23]
	v_add_u32_e32 v23, 0x80, v18
	v_and_b32_e32 v22, 0xff, v23
	v_lshl_add_u32 v22, v22, 2, 0
	v_add_u32_e32 v22, 0x20100, v22
	ds_read_b32 v22, v22
	v_pk_mul_f32 v[30:31], v[16:17], v[24:25]
	v_cvt_pk_bf16_f32 v24, v28, v29
	v_cvt_pk_bf16_f32 v25, v26, v27
	v_cvt_pk_bf16_f32 v26, v32, v33
	v_cvt_pk_bf16_f32 v27, v30, v31
	global_store_dwordx4 v[40:41], v[24:27], off offset:64 sc0 sc1
	s_waitcnt lgkmcnt(0)
	v_pk_mul_f32 v[34:35], v[128:129], v[22:23] op_sel_hi:[1,0]
	v_pk_mul_f32 v[38:39], v[126:127], v[22:23] op_sel_hi:[1,0]
	v_pk_mul_f32 v[32:33], v[124:125], v[22:23] op_sel_hi:[1,0]
	v_pk_mul_f32 v[36:37], v[122:123], v[22:23] op_sel_hi:[1,0]
	v_pk_mul_f32 v[26:27], v[120:121], v[22:23] op_sel_hi:[1,0]
	v_pk_mul_f32 v[30:31], v[118:119], v[22:23] op_sel_hi:[1,0]
	v_pk_mul_f32 v[24:25], v[116:117], v[22:23] op_sel_hi:[1,0]
	v_pk_mul_f32 v[28:29], v[114:115], v[22:23] op_sel_hi:[1,0]
	v_mov_b32_e32 v22, 1.0
	s_and_b64 vcc, exec, s[6:7]
	v_mov_b32_e32 v40, 1.0
	s_cbranch_vccnz .LBB0_246
	v_pk_mul_f32 v[40:41], v[34:35], v[34:35]
	v_pk_mul_f32 v[42:43], v[38:39], v[38:39]
	s_mov_b32 s3, 0x800000
	v_pk_mov_b32 v[44:45], v[42:43], v[40:41] op_sel:[1,0]
	v_mov_b32_e32 v43, v41
	v_pk_add_f32 v[40:41], v[44:45], v[42:43]
	v_pk_mul_f32 v[42:43], v[32:33], v[32:33]
	v_pk_add_f32 v[40:41], v[40:41], v[40:41] op_sel_hi:[0,1]
	v_pk_mul_f32 v[44:45], v[36:37], v[36:37]
	v_mul_f32_e32 v40, v30, v30
	v_pk_mov_b32 v[46:47], v[44:45], v[42:43] op_sel:[1,0]
	v_mov_b32_e32 v45, v43
	v_pk_add_f32 v[42:43], v[46:47], v[44:45]
	v_pk_fma_f32 v[44:45], v[30:31], v[30:31], v[40:41] op_sel_hi:[1,1,0]
	v_mul_f32_e32 v40, v26, v26
	v_pk_add_f32 v[42:43], v[42:43], v[42:43] op_sel_hi:[0,1]
	v_pk_fma_f32 v[46:47], v[26:27], v[26:27], v[40:41] op_sel_hi:[1,1,0]
	v_mul_f32_e32 v44, v28, v28
	v_mul_f32_e32 v46, v29, v29
	v_mul_f32_e32 v40, v24, v24
	v_mul_f32_e32 v42, v25, v25
	v_pk_add_f32 v[44:45], v[44:45], v[46:47]
	v_pk_add_f32 v[40:41], v[40:41], v[42:43]
	v_and_b32_e32 v42, 64, v236
	v_pk_add_f32 v[40:41], v[44:45], v[40:41]
	v_add_u32_e32 v42, 64, v42
	v_add_f32_e32 v40, v40, v41
	v_xor_b32_e32 v41, 16, v236
	v_cmp_lt_i32_e32 vcc, v41, v42
	s_nop 1
	v_cndmask_b32_e32 v41, v236, v41, vcc
	v_lshlrev_b32_e32 v41, 2, v41
	ds_bpermute_b32 v41, v41, v40
	s_waitcnt lgkmcnt(0)
	v_add_f32_e32 v40, v40, v41
	v_xor_b32_e32 v41, 32, v236
	v_cmp_lt_i32_e32 vcc, v41, v42
	s_nop 1
	v_cndmask_b32_e32 v41, v236, v41, vcc
	v_lshlrev_b32_e32 v41, 2, v41
	ds_bpermute_b32 v41, v41, v40
	s_waitcnt lgkmcnt(0)
	v_add_f32_e32 v40, v40, v41
	v_fmamk_f32 v40, v40, 0x3c800000, v215
	v_mul_f32_e32 v41, 0x4b800000, v40
	v_cmp_gt_f32_e32 vcc, s3, v40
	s_nop 1
	v_cndmask_b32_e32 v40, v40, v41, vcc
	v_rsq_f32_e32 v40, v40
	s_nop 0
	v_mul_f32_e32 v41, 0x45800000, v40
	v_cndmask_b32_e32 v40, v40, v41, vcc
; __device__ __forceinline__ unsigned pk2(float lo, float hi) { f32x2_t v = {lo, hi}; bf16x2_t b = __builtin_convertvector(v, bf16x2_t); return __builtin_bit_cast(unsigned, b); }
;     __device__ __forceinline__ void operator()(AccRef acc, const pg8::Unit& u, int wr, int wc, int fr, int fq) const {
;     ...
;         for (int ai = 0; ai < 2; ++ai)
; #pragma unroll
;             for (int m = 0; m < 4; ++m) {
;                 const int row = row0 + ai * 128 + m * 16;
;                 const float rsr = rst[row & 255];
;                 f32x4 xv[2][2];
; #pragma unroll
;                 for (int bj = 0; bj < 2; ++bj)
; #pragma unroll
;                     for (int n = 0; n < 2; ++n) xv[bj][n] = acc[ai][bj][m][n] * rsr;
;                 float rs = 1.f;
;                 if (gain) {
;                     float ss = 0.f;
; #pragma unroll
;                     for (int bj = 0; bj < 2; ++bj)
; #pragma unroll
;                         for (int n = 0; n < 2; ++n) { const f32x4 x = xv[bj][n]; ss += (x[0] * x[0] + x[1] * x[1]) + (x[2] * x[2] + x[3] * x[3]); }
;                     ss += __shfl_xor(ss, 16); ss += __shfl_xor(ss, 32);
;                     rs = rsqrtf(ss * (1.0f / 64.0f) + RMS_EPS);
;                 }
; #pragma unroll
;                 for (int bj = 0; bj < 2; ++bj) {
;                     const f32x4 v0 = xv[bj][0] * rs * gv[bj][0], v1 = xv[bj][1] * rs * gv[bj][1];
;                     v4u w; w.x = pk2(v0[0], v0[1]); w.y = pk2(v0[2], v0[3]); w.z = pk2(v1[0], v1[1]); w.w = pk2(v1[2], v1[3]);
;                     *(v4u*)(dst + (size_t)row * pitch + 32 * bj) = w;
;                 }
.LBB0_246:
	v_ashrrev_i32_e32 v41, 31, v23
	v_mul_lo_u32 v41, s10, v41
	v_mul_lo_u32 v44, s11, v23
	v_mad_u64_u32 v[42:43], s[12:13], s10, v23, 0
	v_pk_mul_f32 v[34:35], v[34:35], v[40:41] op_sel_hi:[1,0]
	v_pk_mul_f32 v[38:39], v[38:39], v[40:41] op_sel_hi:[1,0]
	v_pk_mul_f32 v[32:33], v[32:33], v[40:41] op_sel_hi:[1,0]
	v_pk_mul_f32 v[36:37], v[36:37], v[40:41] op_sel_hi:[1,0]
	v_add3_u32 v43, v43, v41, v44
	v_pk_mul_f32 v[34:35], v[4:5], v[34:35]
	v_pk_mul_f32 v[38:39], v[2:3], v[38:39]
	v_pk_mul_f32 v[44:45], v[8:9], v[32:33]
	v_pk_mul_f32 v[36:37], v[6:7], v[36:37]
	v_lshl_add_u64 v[42:43], v[42:43], 1, v[20:21]
	v_cvt_pk_bf16_f32 v32, v38, v39
	v_cvt_pk_bf16_f32 v33, v34, v35
	v_cvt_pk_bf16_f32 v34, v36, v37
	v_cvt_pk_bf16_f32 v35, v44, v45
	v_pk_mul_f32 v[24:25], v[24:25], v[40:41] op_sel_hi:[1,0]
	v_add_u32_e32 v23, 0x90, v18
	global_store_dwordx4 v[42:43], v[32:35], off sc0 sc1
	v_pk_mul_f32 v[30:31], v[30:31], v[40:41] op_sel_hi:[1,0]
	v_pk_mul_f32 v[26:27], v[26:27], v[40:41] op_sel_hi:[1,0]
	v_pk_mul_f32 v[32:33], v[16:17], v[24:25]
	v_and_b32_e32 v25, 0xff, v23
	v_lshl_add_u32 v25, v25, 2, 0
	v_pk_mul_f32 v[30:31], v[10:11], v[30:31]
	v_add_u32_e32 v25, 0x20100, v25
	v_cvt_pk_bf16_f32 v24, v30, v31
	ds_read_b32 v30, v25
	v_pk_mul_f32 v[28:29], v[28:29], v[40:41] op_sel_hi:[1,0]
	v_pk_mul_f32 v[26:27], v[12:13], v[26:27]
	v_pk_mul_f32 v[28:29], v[14:15], v[28:29]
	v_cvt_pk_bf16_f32 v25, v26, v27
	v_cvt_pk_bf16_f32 v26, v28, v29
	v_cvt_pk_bf16_f32 v27, v32, v33
	global_store_dwordx4 v[42:43], v[24:27], off offset:64 sc0 sc1
	s_waitcnt lgkmcnt(0)
	v_pk_mul_f32 v[36:37], v[112:113], v[30:31] op_sel_hi:[1,0]
	v_pk_mul_f32 v[38:39], v[110:111], v[30:31] op_sel_hi:[1,0]
	v_pk_mul_f32 v[32:33], v[108:109], v[30:31] op_sel_hi:[1,0]
	v_pk_mul_f32 v[34:35], v[106:107], v[30:31] op_sel_hi:[1,0]
	v_pk_mul_f32 v[26:27], v[104:105], v[30:31] op_sel_hi:[1,0]
	v_pk_mul_f32 v[28:29], v[102:103], v[30:31] op_sel_hi:[1,0]
	v_pk_mul_f32 v[24:25], v[100:101], v[30:31] op_sel_hi:[1,0]
	s_and_b64 vcc, exec, s[6:7]
	v_pk_mul_f32 v[30:31], v[98:99], v[30:31] op_sel_hi:[1,0]
	s_cbranch_vccnz .LBB0_248
	v_pk_mul_f32 v[40:41], v[36:37], v[36:37]
	v_pk_mul_f32 v[42:43], v[38:39], v[38:39]
	v_mul_f32_e32 v22, v28, v28
	v_pk_mov_b32 v[44:45], v[42:43], v[40:41] op_sel:[1,0]
	v_mov_b32_e32 v43, v41
	v_pk_add_f32 v[40:41], v[44:45], v[42:43]
	v_pk_mul_f32 v[42:43], v[32:33], v[32:33]
	v_pk_mul_f32 v[44:45], v[34:35], v[34:35]
	v_pk_add_f32 v[40:41], v[40:41], v[40:41] op_sel_hi:[0,1]
	v_pk_mov_b32 v[46:47], v[44:45], v[42:43] op_sel:[1,0]
	v_mov_b32_e32 v45, v43
	v_pk_add_f32 v[42:43], v[46:47], v[44:45]
	v_pk_fma_f32 v[44:45], v[28:29], v[28:29], v[22:23] op_sel_hi:[1,1,0]
	v_mul_f32_e32 v22, v26, v26
	v_pk_add_f32 v[42:43], v[42:43], v[42:43] op_sel_hi:[0,1]
	v_pk_fma_f32 v[46:47], v[26:27], v[26:27], v[22:23] op_sel_hi:[1,1,0]
	v_mul_f32_e32 v44, v30, v30
	v_mul_f32_e32 v46, v31, v31
	v_mul_f32_e32 v40, v24, v24
	v_mul_f32_e32 v42, v25, v25
	v_pk_add_f32 v[44:45], v[44:45], v[46:47]
	v_pk_add_f32 v[40:41], v[40:41], v[42:43]
	s_mov_b32 s3, 0x800000
	v_pk_add_f32 v[40:41], v[44:45], v[40:41]
	s_nop 0
	v_add_f32_e32 v22, v40, v41
	v_and_b32_e32 v41, 64, v236
	v_xor_b32_e32 v40, 16, v236
	v_add_u32_e32 v41, 64, v41
	v_cmp_lt_i32_e32 vcc, v40, v41
	s_nop 1
	v_cndmask_b32_e32 v40, v236, v40, vcc
	v_lshlrev_b32_e32 v40, 2, v40
	ds_bpermute_b32 v40, v40, v22
	s_waitcnt lgkmcnt(0)
	v_add_f32_e32 v22, v22, v40
	v_xor_b32_e32 v40, 32, v236
	v_cmp_lt_i32_e32 vcc, v40, v41
	s_nop 1
	v_cndmask_b32_e32 v40, v236, v40, vcc
	v_lshlrev_b32_e32 v40, 2, v40
	ds_bpermute_b32 v40, v40, v22
	s_waitcnt lgkmcnt(0)
	v_add_f32_e32 v22, v22, v40
	v_fmamk_f32 v22, v22, 0x3c800000, v215
	v_mul_f32_e32 v40, 0x4b800000, v22
	v_cmp_gt_f32_e32 vcc, s3, v22
	s_nop 1
	v_cndmask_b32_e32 v22, v22, v40, vcc
	v_rsq_f32_e32 v22, v22
	s_nop 0
	v_mul_f32_e32 v40, 0x45800000, v22
	v_cndmask_b32_e32 v22, v22, v40, vcc
.LBB0_248:
	v_ashrrev_i32_e32 v40, 31, v23
	v_mul_lo_u32 v42, s11, v23
	v_mul_lo_u32 v43, s10, v40
	v_mad_u64_u32 v[40:41], s[12:13], s10, v23, 0
	v_pk_mul_f32 v[36:37], v[36:37], v[22:23] op_sel_hi:[1,0]
	v_pk_mul_f32 v[38:39], v[38:39], v[22:23] op_sel_hi:[1,0]
	v_pk_mul_f32 v[32:33], v[32:33], v[22:23] op_sel_hi:[1,0]
	v_pk_mul_f32 v[34:35], v[34:35], v[22:23] op_sel_hi:[1,0]
	v_add3_u32 v41, v41, v43, v42
	v_pk_mul_f32 v[36:37], v[4:5], v[36:37]
	v_pk_mul_f32 v[38:39], v[2:3], v[38:39]
	v_pk_mul_f32 v[42:43], v[8:9], v[32:33]
	v_pk_mul_f32 v[34:35], v[6:7], v[34:35]
	v_lshl_add_u64 v[40:41], v[40:41], 1, v[20:21]
	v_cvt_pk_bf16_f32 v32, v38, v39
	v_cvt_pk_bf16_f32 v33, v36, v37
	v_cvt_pk_bf16_f32 v34, v34, v35
	v_cvt_pk_bf16_f32 v35, v42, v43
	v_pk_mul_f32 v[26:27], v[26:27], v[22:23] op_sel_hi:[1,0]
	v_pk_mul_f32 v[28:29], v[28:29], v[22:23] op_sel_hi:[1,0]
	v_pk_mul_f32 v[24:25], v[24:25], v[22:23] op_sel_hi:[1,0]
	v_pk_mul_f32 v[22:23], v[30:31], v[22:23] op_sel_hi:[1,0]
	global_store_dwordx4 v[40:41], v[32:35], off sc0 sc1
	v_pk_mul_f32 v[26:27], v[12:13], v[26:27]
	v_pk_mul_f32 v[28:29], v[10:11], v[28:29]
	v_pk_mul_f32 v[32:33], v[14:15], v[22:23]
	v_add_u32_e32 v23, 0xa0, v18
	v_and_b32_e32 v22, 0xff, v23
	v_lshl_add_u32 v22, v22, 2, 0
	v_add_u32_e32 v22, 0x20100, v22
	ds_read_b32 v22, v22
	v_pk_mul_f32 v[30:31], v[16:17], v[24:25]
	v_cvt_pk_bf16_f32 v24, v28, v29
	v_cvt_pk_bf16_f32 v25, v26, v27
	v_cvt_pk_bf16_f32 v26, v32, v33
	v_cvt_pk_bf16_f32 v27, v30, v31
	global_store_dwordx4 v[40:41], v[24:27], off offset:64 sc0 sc1
	s_waitcnt lgkmcnt(0)
	v_pk_mul_f32 v[34:35], v[96:97], v[22:23] op_sel_hi:[1,0]
	v_pk_mul_f32 v[38:39], v[94:95], v[22:23] op_sel_hi:[1,0]
	v_pk_mul_f32 v[32:33], v[92:93], v[22:23] op_sel_hi:[1,0]
	v_pk_mul_f32 v[36:37], v[90:91], v[22:23] op_sel_hi:[1,0]
	v_pk_mul_f32 v[26:27], v[88:89], v[22:23] op_sel_hi:[1,0]
	v_pk_mul_f32 v[30:31], v[86:87], v[22:23] op_sel_hi:[1,0]
	v_pk_mul_f32 v[24:25], v[84:85], v[22:23] op_sel_hi:[1,0]
	v_pk_mul_f32 v[28:29], v[82:83], v[22:23] op_sel_hi:[1,0]
	v_mov_b32_e32 v22, 1.0
	s_and_b64 vcc, exec, s[6:7]
	v_mov_b32_e32 v40, 1.0
	s_cbranch_vccnz .LBB0_250
; __device__ __forceinline__ unsigned pk2(float lo, float hi) { f32x2_t v = {lo, hi}; bf16x2_t b = __builtin_convertvector(v, bf16x2_t); return __builtin_bit_cast(unsigned, b); }
;     __device__ __forceinline__ void operator()(AccRef acc, const pg8::Unit& u, int wr, int wc, int fr, int fq) const {
;     ...
;         for (int ai = 0; ai < 2; ++ai)
; #pragma unroll
;             for (int m = 0; m < 4; ++m) {
;                 const int row = row0 + ai * 128 + m * 16;
;                 const float rsr = rst[row & 255];
;                 f32x4 xv[2][2];
; #pragma unroll
;                 for (int bj = 0; bj < 2; ++bj)
; #pragma unroll
;                     for (int n = 0; n < 2; ++n) xv[bj][n] = acc[ai][bj][m][n] * rsr;
;                 float rs = 1.f;
;                 if (gain) {
;                     float ss = 0.f;
; #pragma unroll
;                     for (int bj = 0; bj < 2; ++bj)
; #pragma unroll
;                         for (int n = 0; n < 2; ++n) { const f32x4 x = xv[bj][n]; ss += (x[0] * x[0] + x[1] * x[1]) + (x[2] * x[2] + x[3] * x[3]); }
;                     ss += __shfl_xor(ss, 16); ss += __shfl_xor(ss, 32);
;                     rs = rsqrtf(ss * (1.0f / 64.0f) + RMS_EPS);
;                 }
; #pragma unroll
;                 for (int bj = 0; bj < 2; ++bj) {
;                     const f32x4 v0 = xv[bj][0] * rs * gv[bj][0], v1 = xv[bj][1] * rs * gv[bj][1];
;                     v4u w; w.x = pk2(v0[0], v0[1]); w.y = pk2(v0[2], v0[3]); w.z = pk2(v1[0], v1[1]); w.w = pk2(v1[2], v1[3]);
;                     *(v4u*)(dst + (size_t)row * pitch + 32 * bj) = w;
;                 }
	v_pk_mul_f32 v[40:41], v[34:35], v[34:35]
	v_pk_mul_f32 v[42:43], v[38:39], v[38:39]
	s_mov_b32 s3, 0x800000
	v_pk_mov_b32 v[44:45], v[42:43], v[40:41] op_sel:[1,0]
	v_mov_b32_e32 v43, v41
	v_pk_add_f32 v[40:41], v[44:45], v[42:43]
	v_pk_mul_f32 v[42:43], v[32:33], v[32:33]
	v_pk_add_f32 v[40:41], v[40:41], v[40:41] op_sel_hi:[0,1]
	v_pk_mul_f32 v[44:45], v[36:37], v[36:37]
	v_mul_f32_e32 v40, v30, v30
	v_pk_mov_b32 v[46:47], v[44:45], v[42:43] op_sel:[1,0]
	v_mov_b32_e32 v45, v43
	v_pk_add_f32 v[42:43], v[46:47], v[44:45]
	v_pk_fma_f32 v[44:45], v[30:31], v[30:31], v[40:41] op_sel_hi:[1,1,0]
	v_mul_f32_e32 v40, v26, v26
	v_pk_add_f32 v[42:43], v[42:43], v[42:43] op_sel_hi:[0,1]
	v_pk_fma_f32 v[46:47], v[26:27], v[26:27], v[40:41] op_sel_hi:[1,1,0]
	v_mul_f32_e32 v44, v28, v28
	v_mul_f32_e32 v46, v29, v29
	v_mul_f32_e32 v40, v24, v24
	v_mul_f32_e32 v42, v25, v25
	v_pk_add_f32 v[44:45], v[44:45], v[46:47]
	v_pk_add_f32 v[40:41], v[40:41], v[42:43]
	v_and_b32_e32 v42, 64, v236
	v_pk_add_f32 v[40:41], v[44:45], v[40:41]
	v_add_u32_e32 v42, 64, v42
	v_add_f32_e32 v40, v40, v41
	v_xor_b32_e32 v41, 16, v236
	v_cmp_lt_i32_e32 vcc, v41, v42
	s_nop 1
	v_cndmask_b32_e32 v41, v236, v41, vcc
	v_lshlrev_b32_e32 v41, 2, v41
	ds_bpermute_b32 v41, v41, v40
	s_waitcnt lgkmcnt(0)
	v_add_f32_e32 v40, v40, v41
	v_xor_b32_e32 v41, 32, v236
	v_cmp_lt_i32_e32 vcc, v41, v42
	s_nop 1
	v_cndmask_b32_e32 v41, v236, v41, vcc
	v_lshlrev_b32_e32 v41, 2, v41
	ds_bpermute_b32 v41, v41, v40
	s_waitcnt lgkmcnt(0)
	v_add_f32_e32 v40, v40, v41
	v_fmamk_f32 v40, v40, 0x3c800000, v215
	v_mul_f32_e32 v41, 0x4b800000, v40
	v_cmp_gt_f32_e32 vcc, s3, v40
	s_nop 1
	v_cndmask_b32_e32 v40, v40, v41, vcc
	v_rsq_f32_e32 v40, v40
	s_nop 0
	v_mul_f32_e32 v41, 0x45800000, v40
	v_cndmask_b32_e32 v40, v40, v41, vcc
.LBB0_250:
	v_ashrrev_i32_e32 v41, 31, v23
	v_mul_lo_u32 v41, s10, v41
	v_mul_lo_u32 v44, s11, v23
	v_mad_u64_u32 v[42:43], s[12:13], s10, v23, 0
	v_pk_mul_f32 v[34:35], v[34:35], v[40:41] op_sel_hi:[1,0]
	v_pk_mul_f32 v[38:39], v[38:39], v[40:41] op_sel_hi:[1,0]
	v_pk_mul_f32 v[32:33], v[32:33], v[40:41] op_sel_hi:[1,0]
	v_pk_mul_f32 v[36:37], v[36:37], v[40:41] op_sel_hi:[1,0]
	v_add3_u32 v43, v43, v41, v44
	v_pk_mul_f32 v[34:35], v[4:5], v[34:35]
	v_pk_mul_f32 v[38:39], v[2:3], v[38:39]
	v_pk_mul_f32 v[44:45], v[8:9], v[32:33]
	v_pk_mul_f32 v[36:37], v[6:7], v[36:37]
	v_lshl_add_u64 v[42:43], v[42:43], 1, v[20:21]
	v_cvt_pk_bf16_f32 v32, v38, v39
	v_cvt_pk_bf16_f32 v33, v34, v35
	v_cvt_pk_bf16_f32 v34, v36, v37
	v_cvt_pk_bf16_f32 v35, v44, v45
	v_pk_mul_f32 v[24:25], v[24:25], v[40:41] op_sel_hi:[1,0]
	v_add_u32_e32 v23, 0xb0, v18
	global_store_dwordx4 v[42:43], v[32:35], off sc0 sc1
	v_pk_mul_f32 v[30:31], v[30:31], v[40:41] op_sel_hi:[1,0]
	v_pk_mul_f32 v[26:27], v[26:27], v[40:41] op_sel_hi:[1,0]
	v_pk_mul_f32 v[32:33], v[16:17], v[24:25]
	v_and_b32_e32 v25, 0xff, v23
	v_lshl_add_u32 v25, v25, 2, 0
	v_pk_mul_f32 v[30:31], v[10:11], v[30:31]
	v_add_u32_e32 v25, 0x20100, v25
	v_cvt_pk_bf16_f32 v24, v30, v31
	ds_read_b32 v30, v25
	v_pk_mul_f32 v[28:29], v[28:29], v[40:41] op_sel_hi:[1,0]
	v_pk_mul_f32 v[26:27], v[12:13], v[26:27]
	v_pk_mul_f32 v[28:29], v[14:15], v[28:29]
	v_cvt_pk_bf16_f32 v25, v26, v27
	v_cvt_pk_bf16_f32 v26, v28, v29
	v_cvt_pk_bf16_f32 v27, v32, v33
	global_store_dwordx4 v[42:43], v[24:27], off offset:64 sc0 sc1
	s_waitcnt lgkmcnt(0)
	v_pk_mul_f32 v[36:37], v[80:81], v[30:31] op_sel_hi:[1,0]
	v_pk_mul_f32 v[38:39], v[78:79], v[30:31] op_sel_hi:[1,0]
	v_pk_mul_f32 v[32:33], v[76:77], v[30:31] op_sel_hi:[1,0]
	v_pk_mul_f32 v[34:35], v[74:75], v[30:31] op_sel_hi:[1,0]
	v_pk_mul_f32 v[26:27], v[72:73], v[30:31] op_sel_hi:[1,0]
	v_pk_mul_f32 v[28:29], v[70:71], v[30:31] op_sel_hi:[1,0]
	v_pk_mul_f32 v[24:25], v[68:69], v[30:31] op_sel_hi:[1,0]
	s_and_b64 vcc, exec, s[6:7]
	v_pk_mul_f32 v[30:31], v[66:67], v[30:31] op_sel_hi:[1,0]
	s_cbranch_vccnz .LBB0_252
	v_pk_mul_f32 v[40:41], v[36:37], v[36:37]
	v_pk_mul_f32 v[42:43], v[38:39], v[38:39]
	v_mul_f32_e32 v22, v28, v28
	v_pk_mov_b32 v[44:45], v[42:43], v[40:41] op_sel:[1,0]
	v_mov_b32_e32 v43, v41
	v_pk_add_f32 v[40:41], v[44:45], v[42:43]
	v_pk_mul_f32 v[42:43], v[32:33], v[32:33]
	v_pk_mul_f32 v[44:45], v[34:35], v[34:35]
	v_pk_add_f32 v[40:41], v[40:41], v[40:41] op_sel_hi:[0,1]
	v_pk_mov_b32 v[46:47], v[44:45], v[42:43] op_sel:[1,0]
	v_mov_b32_e32 v45, v43
	v_pk_add_f32 v[42:43], v[46:47], v[44:45]
	v_pk_fma_f32 v[44:45], v[28:29], v[28:29], v[22:23] op_sel_hi:[1,1,0]
	v_mul_f32_e32 v22, v26, v26
	v_pk_add_f32 v[42:43], v[42:43], v[42:43] op_sel_hi:[0,1]
	v_pk_fma_f32 v[46:47], v[26:27], v[26:27], v[22:23] op_sel_hi:[1,1,0]
	v_mul_f32_e32 v44, v30, v30
	v_mul_f32_e32 v46, v31, v31
	v_mul_f32_e32 v40, v24, v24
	v_mul_f32_e32 v42, v25, v25
	v_pk_add_f32 v[44:45], v[44:45], v[46:47]
	v_pk_add_f32 v[40:41], v[40:41], v[42:43]
	s_mov_b32 s3, 0x800000
	v_pk_add_f32 v[40:41], v[44:45], v[40:41]
	s_nop 0
	v_add_f32_e32 v22, v40, v41
	v_and_b32_e32 v41, 64, v236
	v_xor_b32_e32 v40, 16, v236
	v_add_u32_e32 v41, 64, v41
	v_cmp_lt_i32_e32 vcc, v40, v41
	s_nop 1
	v_cndmask_b32_e32 v40, v236, v40, vcc
	v_lshlrev_b32_e32 v40, 2, v40
	ds_bpermute_b32 v40, v40, v22
	s_waitcnt lgkmcnt(0)
	v_add_f32_e32 v22, v22, v40
	v_xor_b32_e32 v40, 32, v236
	v_cmp_lt_i32_e32 vcc, v40, v41
	s_nop 1
	v_cndmask_b32_e32 v40, v236, v40, vcc
	v_lshlrev_b32_e32 v40, 2, v40
	ds_bpermute_b32 v40, v40, v22
	s_waitcnt lgkmcnt(0)
	v_add_f32_e32 v22, v22, v40
	v_fmamk_f32 v22, v22, 0x3c800000, v215
	v_mul_f32_e32 v40, 0x4b800000, v22
	v_cmp_gt_f32_e32 vcc, s3, v22
	s_nop 1
	v_cndmask_b32_e32 v22, v22, v40, vcc
	v_rsq_f32_e32 v22, v22
	s_nop 0
	v_mul_f32_e32 v40, 0x45800000, v22
	v_cndmask_b32_e32 v22, v22, v40, vcc
; __device__ __forceinline__ unsigned pk2(float lo, float hi) { f32x2_t v = {lo, hi}; bf16x2_t b = __builtin_convertvector(v, bf16x2_t); return __builtin_bit_cast(unsigned, b); }
; __device__ __forceinline__ float fexp2(float x) { return __builtin_amdgcn_exp2f(x); }
; __device__ __forceinline__ float flog2(float x) { return __builtin_amdgcn_logf(x); }
;     __device__ __forceinline__ void operator()(AccRef acc, const pg8::Unit& u, int wr, int wc, int fr, int fq) const {
;     ...
;         if (G == 78) {
;             if (fq == 0) {
; #pragma unroll
;                 for (int ai = 0; ai < 2; ++ai)
; #pragma unroll
;                     for (int m = 0; m < 4; ++m) {
;                         const int row = row0 + ai * 128 + m * 16;
;                         const float rsr = rst[row & 255];
; #pragma unroll
;                         for (int e = 0; e < 6; ++e) {
;                             const float x = acc[ai][0][m][e >> 2][e & 3] * rsr + fb[e];
;                             const float ls = fminf(x, 0.f) - LN2 * flog2(1.0f + fexp2(-fabsf(x) * LOG2E));
;                             logf[(size_t)row * 8 + e] = ls;
;                         }
;                     }
;     ...
;                 for (int bj = 0; bj < 2; ++bj) {
;                     const f32x4 v0 = xv[bj][0] * rs * gv[bj][0], v1 = xv[bj][1] * rs * gv[bj][1];
;                     v4u w; w.x = pk2(v0[0], v0[1]); w.y = pk2(v0[2], v0[3]); w.z = pk2(v1[0], v1[1]); w.w = pk2(v1[2], v1[3]);
;                     *(v4u*)(dst + (size_t)row * pitch + 32 * bj) = w;
.LBB0_252:
	v_ashrrev_i32_e32 v40, 31, v23
	v_mul_lo_u32 v42, s11, v23
	v_mul_lo_u32 v43, s10, v40
	v_mad_u64_u32 v[40:41], s[6:7], s10, v23, 0
	v_pk_mul_f32 v[36:37], v[36:37], v[22:23] op_sel_hi:[1,0]
	v_pk_mul_f32 v[38:39], v[38:39], v[22:23] op_sel_hi:[1,0]
	v_pk_mul_f32 v[32:33], v[32:33], v[22:23] op_sel_hi:[1,0]
	v_pk_mul_f32 v[34:35], v[34:35], v[22:23] op_sel_hi:[1,0]
	v_add3_u32 v41, v41, v43, v42
	v_pk_mul_f32 v[4:5], v[4:5], v[36:37]
	v_pk_mul_f32 v[2:3], v[2:3], v[38:39]
	v_pk_mul_f32 v[8:9], v[8:9], v[32:33]
	v_pk_mul_f32 v[6:7], v[6:7], v[34:35]
	v_lshl_add_u64 v[20:21], v[40:41], 1, v[20:21]
	v_cvt_pk_bf16_f32 v2, v2, v3
	v_cvt_pk_bf16_f32 v3, v4, v5
	v_cvt_pk_bf16_f32 v4, v6, v7
	v_cvt_pk_bf16_f32 v5, v8, v9
	global_store_dwordx4 v[20:21], v[2:5], off sc0 sc1
	v_pk_mul_f32 v[8:9], v[30:31], v[22:23] op_sel_hi:[1,0]
	s_mov_b64 s[10:11], 0
	v_pk_mul_f32 v[2:3], v[26:27], v[22:23] op_sel_hi:[1,0]
	v_pk_mul_f32 v[4:5], v[28:29], v[22:23] op_sel_hi:[1,0]
	v_pk_mul_f32 v[6:7], v[12:13], v[2:3]
	v_pk_mul_f32 v[2:3], v[10:11], v[4:5]
	v_pk_mul_f32 v[4:5], v[24:25], v[22:23] op_sel_hi:[1,0]
	v_cvt_pk_bf16_f32 v2, v2, v3
	v_pk_mul_f32 v[10:11], v[16:17], v[4:5]
	v_pk_mul_f32 v[4:5], v[14:15], v[8:9]
	v_cvt_pk_bf16_f32 v3, v6, v7
	v_cvt_pk_bf16_f32 v4, v4, v5
	v_cvt_pk_bf16_f32 v5, v10, v11
	global_store_dwordx4 v[20:21], v[2:5], off offset:64 sc0 sc1
.LBB0_253:
	s_and_b64 vcc, exec, s[10:11]
	v_readlane_b32 s22, v255, 18
	v_readlane_b32 s23, v255, 19
	s_mov_b64 s[24:25], s[74:75]
	s_mov_b64 s[74:75], s[50:51]
	s_mov_b64 s[50:51], s[46:47]
	s_mov_b64 s[46:47], s[16:17]
	s_mov_b64 s[16:17], s[48:49]
	s_mov_b64 s[48:49], s[68:69]
	s_mov_b64 s[68:69], s[38:39]
	s_mov_b32 s39, s77
	s_cbranch_vccz .LBB0_257
	v_cmp_eq_u32_e32 vcc, 0, v244
	s_and_saveexec_b64 s[6:7], vcc
	s_cbranch_execz .LBB0_256
	v_readlane_b32 s10, v255, 45
	v_readlane_b32 s76, v255, 49
	v_readlane_b32 s11, v255, 46
	v_readlane_b32 s77, v255, 50
	s_add_u32 s10, s76, s10
	s_addc_u32 s11, s77, s11
	v_and_b32_e32 v2, 0xff, v19
	s_add_i32 s12, 0, 0x20100
	global_load_dword v8, v1, s[10:11]
	global_load_dword v9, v1, s[10:11] offset:4
	global_load_dword v10, v1, s[10:11] offset:8
	global_load_dword v11, v1, s[10:11] offset:12
	global_load_dword v12, v1, s[10:11] offset:16
	global_load_dword v13, v1, s[10:11] offset:20
	v_lshl_add_u32 v2, v2, 2, s12
	ds_read_b32 v4, v2
	s_mov_b32 s14, 0xbfb8aa3b
	v_ashrrev_i32_e32 v19, 31, v18
	v_readlane_b32 s20, v255, 37
	v_lshlrev_b64 v[2:3], 5, v[18:19]
	v_readlane_b32 s21, v255, 38
	v_readlane_b32 s78, v255, 51
	v_readlane_b32 s79, v255, 52
	v_lshl_add_u64 v[2:3], s[20:21], 0, v[2:3]
	s_waitcnt vmcnt(0) lgkmcnt(0)
	v_mov_b32_e32 v5, v8
	v_fmac_f32_e32 v5, v190, v4
	v_min_f32_e32 v6, 0, v5
	v_mul_f32_e64 v5, |v5|, s14
	v_exp_f32_e32 v5, v5
	s_nop 0
	v_add_f32_e32 v5, 1.0, v5
	v_log_f32_e32 v5, v5
	s_nop 0
	v_fmac_f32_e32 v6, 0xbf317218, v5
	global_store_dword v[2:3], v6, off sc0 sc1
	v_mov_b32_e32 v5, v9
	v_fmac_f32_e32 v5, v191, v4
	v_min_f32_e32 v6, 0, v5
	v_mul_f32_e64 v5, |v5|, s14
	v_exp_f32_e32 v5, v5
	s_nop 0
	v_add_f32_e32 v5, 1.0, v5
	v_log_f32_e32 v5, v5
	s_nop 0
	v_fmac_f32_e32 v6, 0xbf317218, v5
	global_store_dword v[2:3], v6, off offset:4 sc0 sc1
	v_mov_b32_e32 v5, v10
	v_fmac_f32_e32 v5, v192, v4
	v_min_f32_e32 v6, 0, v5
	v_mul_f32_e64 v5, |v5|, s14
	v_exp_f32_e32 v5, v5
	s_nop 0
	v_add_f32_e32 v5, 1.0, v5
	v_log_f32_e32 v5, v5
	s_nop 0
	v_fmac_f32_e32 v6, 0xbf317218, v5
	global_store_dword v[2:3], v6, off offset:8 sc0 sc1
	v_mov_b32_e32 v5, v11
	v_fmac_f32_e32 v5, v193, v4
	v_min_f32_e32 v6, 0, v5
	v_mul_f32_e64 v5, |v5|, s14
	v_exp_f32_e32 v5, v5
	s_nop 0
	v_add_f32_e32 v5, 1.0, v5
	v_log_f32_e32 v5, v5
	s_nop 0
	v_fmac_f32_e32 v6, 0xbf317218, v5
	global_store_dword v[2:3], v6, off offset:12 sc0 sc1
	v_mov_b32_e32 v5, v12
	v_fmac_f32_e32 v5, v186, v4
	v_min_f32_e32 v6, 0, v5
	v_mul_f32_e64 v5, |v5|, s14
	v_exp_f32_e32 v5, v5
	s_nop 0
	v_add_f32_e32 v5, 1.0, v5
	v_log_f32_e32 v5, v5
	s_nop 0
	v_fmac_f32_e32 v6, 0xbf317218, v5
	global_store_dword v[2:3], v6, off offset:16 sc0 sc1
	v_mov_b32_e32 v5, v13
	v_fmac_f32_e32 v5, v187, v4
	v_min_f32_e32 v4, 0, v5
	v_mul_f32_e64 v5, |v5|, s14
	v_exp_f32_e32 v5, v5
	s_nop 0
	v_add_f32_e32 v5, 1.0, v5
	v_log_f32_e32 v5, v5
	s_nop 0
	v_fmac_f32_e32 v4, 0xbf317218, v5
	global_store_dword v[2:3], v4, off offset:20 sc0 sc1
	v_mov_b32_e32 v5, v8
	v_add_u32_e32 v2, 16, v18
	v_and_b32_e32 v3, 0xff, v2
	v_lshl_add_u32 v3, v3, 2, s12
	ds_read_b32 v4, v3
	v_ashrrev_i32_e32 v3, 31, v2
	v_lshlrev_b64 v[2:3], 5, v[2:3]
	v_lshl_add_u64 v[2:3], s[20:21], 0, v[2:3]
	s_waitcnt lgkmcnt(0)
	v_fmac_f32_e32 v5, v174, v4
	v_min_f32_e32 v6, 0, v5
	v_mul_f32_e64 v5, |v5|, s14
	v_exp_f32_e32 v5, v5
	s_nop 0
	v_add_f32_e32 v5, 1.0, v5
	v_log_f32_e32 v5, v5
	s_nop 0
	v_fmac_f32_e32 v6, 0xbf317218, v5
	global_store_dword v[2:3], v6, off sc0 sc1
	v_mov_b32_e32 v5, v9
	v_fmac_f32_e32 v5, v175, v4
	v_min_f32_e32 v6, 0, v5
	v_mul_f32_e64 v5, |v5|, s14
	v_exp_f32_e32 v5, v5
	s_nop 0
	v_add_f32_e32 v5, 1.0, v5
	v_log_f32_e32 v5, v5
	s_nop 0
	v_fmac_f32_e32 v6, 0xbf317218, v5
	global_store_dword v[2:3], v6, off offset:4 sc0 sc1
	v_mov_b32_e32 v5, v10
	v_fmac_f32_e32 v5, v176, v4
	v_min_f32_e32 v6, 0, v5
	v_mul_f32_e64 v5, |v5|, s14
	v_exp_f32_e32 v5, v5
	s_nop 0
	v_add_f32_e32 v5, 1.0, v5
	v_log_f32_e32 v5, v5
	s_nop 0
	v_fmac_f32_e32 v6, 0xbf317218, v5
	global_store_dword v[2:3], v6, off offset:8 sc0 sc1
	v_mov_b32_e32 v5, v11
	v_fmac_f32_e32 v5, v177, v4
	v_min_f32_e32 v6, 0, v5
	v_mul_f32_e64 v5, |v5|, s14
	v_exp_f32_e32 v5, v5
	s_nop 0
	v_add_f32_e32 v5, 1.0, v5
	v_log_f32_e32 v5, v5
	s_nop 0
	v_fmac_f32_e32 v6, 0xbf317218, v5
	global_store_dword v[2:3], v6, off offset:12 sc0 sc1
	v_mov_b32_e32 v5, v12
	v_fmac_f32_e32 v5, v170, v4
	v_min_f32_e32 v6, 0, v5
	v_mul_f32_e64 v5, |v5|, s14
	v_exp_f32_e32 v5, v5
	s_nop 0
	v_add_f32_e32 v5, 1.0, v5
	v_log_f32_e32 v5, v5
	s_nop 0
	v_fmac_f32_e32 v6, 0xbf317218, v5
	global_store_dword v[2:3], v6, off offset:16 sc0 sc1
	v_mov_b32_e32 v5, v13
	v_fmac_f32_e32 v5, v171, v4
	v_min_f32_e32 v4, 0, v5
	v_mul_f32_e64 v5, |v5|, s14
	v_exp_f32_e32 v5, v5
	s_nop 0
	v_add_f32_e32 v5, 1.0, v5
	v_log_f32_e32 v5, v5
	s_nop 0
	v_fmac_f32_e32 v4, 0xbf317218, v5
	global_store_dword v[2:3], v4, off offset:20 sc0 sc1
	v_mov_b32_e32 v5, v8
	v_add_u32_e32 v2, 32, v18
	v_and_b32_e32 v3, 0xff, v2
	v_lshl_add_u32 v3, v3, 2, s12
	ds_read_b32 v4, v3
	v_ashrrev_i32_e32 v3, 31, v2
	v_lshlrev_b64 v[2:3], 5, v[2:3]
	v_lshl_add_u64 v[2:3], s[20:21], 0, v[2:3]
	s_waitcnt lgkmcnt(0)
; __device__ __forceinline__ float fexp2(float x) { return __builtin_amdgcn_exp2f(x); }
; __device__ __forceinline__ float flog2(float x) { return __builtin_amdgcn_logf(x); }
;     __device__ __forceinline__ void operator()(AccRef acc, const pg8::Unit& u, int wr, int wc, int fr, int fq) const {
;     ...
;                 for (int ai = 0; ai < 2; ++ai)
; #pragma unroll
;                     for (int m = 0; m < 4; ++m) {
;                         const int row = row0 + ai * 128 + m * 16;
;                         const float rsr = rst[row & 255];
; #pragma unroll
;                         for (int e = 0; e < 6; ++e) {
;                             const float x = acc[ai][0][m][e >> 2][e & 3] * rsr + fb[e];
;                             const float ls = fminf(x, 0.f) - LN2 * flog2(1.0f + fexp2(-fabsf(x) * LOG2E));
;                             logf[(size_t)row * 8 + e] = ls;
;                         }
;                     }
	v_fmac_f32_e32 v5, v158, v4
	v_min_f32_e32 v6, 0, v5
	v_mul_f32_e64 v5, |v5|, s14
	v_exp_f32_e32 v5, v5
	s_nop 0
	v_add_f32_e32 v5, 1.0, v5
	v_log_f32_e32 v5, v5
	s_nop 0
	v_fmac_f32_e32 v6, 0xbf317218, v5
	global_store_dword v[2:3], v6, off sc0 sc1
	v_mov_b32_e32 v5, v9
	v_fmac_f32_e32 v5, v159, v4
	v_min_f32_e32 v6, 0, v5
	v_mul_f32_e64 v5, |v5|, s14
	v_exp_f32_e32 v5, v5
	s_nop 0
	v_add_f32_e32 v5, 1.0, v5
	v_log_f32_e32 v5, v5
	s_nop 0
	v_fmac_f32_e32 v6, 0xbf317218, v5
	global_store_dword v[2:3], v6, off offset:4 sc0 sc1
	v_mov_b32_e32 v5, v10
	v_fmac_f32_e32 v5, v160, v4
	v_min_f32_e32 v6, 0, v5
	v_mul_f32_e64 v5, |v5|, s14
	v_exp_f32_e32 v5, v5
	s_nop 0
	v_add_f32_e32 v5, 1.0, v5
	v_log_f32_e32 v5, v5
	s_nop 0
	v_fmac_f32_e32 v6, 0xbf317218, v5
	global_store_dword v[2:3], v6, off offset:8 sc0 sc1
	v_mov_b32_e32 v5, v11
	v_fmac_f32_e32 v5, v161, v4
	v_min_f32_e32 v6, 0, v5
	v_mul_f32_e64 v5, |v5|, s14
	v_exp_f32_e32 v5, v5
	s_nop 0
	v_add_f32_e32 v5, 1.0, v5
	v_log_f32_e32 v5, v5
	s_nop 0
	v_fmac_f32_e32 v6, 0xbf317218, v5
	global_store_dword v[2:3], v6, off offset:12 sc0 sc1
	v_mov_b32_e32 v5, v12
	v_fmac_f32_e32 v5, v154, v4
	v_min_f32_e32 v6, 0, v5
	v_mul_f32_e64 v5, |v5|, s14
	v_exp_f32_e32 v5, v5
	s_nop 0
	v_add_f32_e32 v5, 1.0, v5
	v_log_f32_e32 v5, v5
	s_nop 0
	v_fmac_f32_e32 v6, 0xbf317218, v5
	global_store_dword v[2:3], v6, off offset:16 sc0 sc1
	v_mov_b32_e32 v5, v13
	v_fmac_f32_e32 v5, v155, v4
	v_min_f32_e32 v4, 0, v5
	v_mul_f32_e64 v5, |v5|, s14
	v_exp_f32_e32 v5, v5
	s_nop 0
	v_add_f32_e32 v5, 1.0, v5
	v_log_f32_e32 v5, v5
	s_nop 0
	v_fmac_f32_e32 v4, 0xbf317218, v5
	global_store_dword v[2:3], v4, off offset:20 sc0 sc1
	v_mov_b32_e32 v5, v8
	v_add_u32_e32 v2, 48, v18
	v_and_b32_e32 v3, 0xff, v2
	v_lshl_add_u32 v3, v3, 2, s12
	ds_read_b32 v4, v3
	v_ashrrev_i32_e32 v3, 31, v2
	v_lshlrev_b64 v[2:3], 5, v[2:3]
	v_lshl_add_u64 v[2:3], s[20:21], 0, v[2:3]
	s_waitcnt lgkmcnt(0)
	v_fmac_f32_e32 v5, v142, v4
	v_min_f32_e32 v6, 0, v5
	v_mul_f32_e64 v5, |v5|, s14
	v_exp_f32_e32 v5, v5
	s_nop 0
	v_add_f32_e32 v5, 1.0, v5
	v_log_f32_e32 v5, v5
	s_nop 0
	v_fmac_f32_e32 v6, 0xbf317218, v5
	global_store_dword v[2:3], v6, off sc0 sc1
	v_mov_b32_e32 v5, v9
	v_fmac_f32_e32 v5, v143, v4
	v_min_f32_e32 v6, 0, v5
	v_mul_f32_e64 v5, |v5|, s14
	v_exp_f32_e32 v5, v5
	s_nop 0
	v_add_f32_e32 v5, 1.0, v5
	v_log_f32_e32 v5, v5
	s_nop 0
	v_fmac_f32_e32 v6, 0xbf317218, v5
	global_store_dword v[2:3], v6, off offset:4 sc0 sc1
	v_mov_b32_e32 v5, v10
	v_fmac_f32_e32 v5, v144, v4
	v_min_f32_e32 v6, 0, v5
	v_mul_f32_e64 v5, |v5|, s14
	v_exp_f32_e32 v5, v5
	s_nop 0
	v_add_f32_e32 v5, 1.0, v5
	v_log_f32_e32 v5, v5
	s_nop 0
	v_fmac_f32_e32 v6, 0xbf317218, v5
	global_store_dword v[2:3], v6, off offset:8 sc0 sc1
	v_mov_b32_e32 v5, v11
	v_fmac_f32_e32 v5, v145, v4
	v_min_f32_e32 v6, 0, v5
	v_mul_f32_e64 v5, |v5|, s14
	v_exp_f32_e32 v5, v5
	s_nop 0
	v_add_f32_e32 v5, 1.0, v5
	v_log_f32_e32 v5, v5
	s_nop 0
	v_fmac_f32_e32 v6, 0xbf317218, v5
	global_store_dword v[2:3], v6, off offset:12 sc0 sc1
	v_mov_b32_e32 v5, v12
	v_fmac_f32_e32 v5, v138, v4
	v_min_f32_e32 v6, 0, v5
	v_mul_f32_e64 v5, |v5|, s14
	v_exp_f32_e32 v5, v5
	s_nop 0
	v_add_f32_e32 v5, 1.0, v5
	v_log_f32_e32 v5, v5
	s_nop 0
	v_fmac_f32_e32 v6, 0xbf317218, v5
	global_store_dword v[2:3], v6, off offset:16 sc0 sc1
	v_mov_b32_e32 v5, v13
	v_fmac_f32_e32 v5, v139, v4
	v_min_f32_e32 v4, 0, v5
	v_mul_f32_e64 v5, |v5|, s14
	v_exp_f32_e32 v5, v5
	s_nop 0
	v_add_f32_e32 v5, 1.0, v5
	v_log_f32_e32 v5, v5
	s_nop 0
	v_fmac_f32_e32 v4, 0xbf317218, v5
	global_store_dword v[2:3], v4, off offset:20 sc0 sc1
	v_mov_b32_e32 v5, v8
	v_add_u32_e32 v2, 0x80, v18
	v_and_b32_e32 v3, 0xff, v2
	v_lshl_add_u32 v3, v3, 2, s12
	ds_read_b32 v4, v3
	v_ashrrev_i32_e32 v3, 31, v2
	v_lshlrev_b64 v[2:3], 5, v[2:3]
	v_lshl_add_u64 v[2:3], s[20:21], 0, v[2:3]
	s_waitcnt lgkmcnt(0)
	v_fmac_f32_e32 v5, v126, v4
	v_min_f32_e32 v6, 0, v5
	v_mul_f32_e64 v5, |v5|, s14
	v_exp_f32_e32 v5, v5
	s_nop 0
	v_add_f32_e32 v5, 1.0, v5
	v_log_f32_e32 v5, v5
	s_nop 0
	v_fmac_f32_e32 v6, 0xbf317218, v5
	global_store_dword v[2:3], v6, off sc0 sc1
	v_mov_b32_e32 v5, v9
	v_fmac_f32_e32 v5, v127, v4
	v_min_f32_e32 v6, 0, v5
	v_mul_f32_e64 v5, |v5|, s14
	v_exp_f32_e32 v5, v5
	s_nop 0
	v_add_f32_e32 v5, 1.0, v5
	v_log_f32_e32 v5, v5
	s_nop 0
	v_fmac_f32_e32 v6, 0xbf317218, v5
	global_store_dword v[2:3], v6, off offset:4 sc0 sc1
	v_mov_b32_e32 v5, v10
	v_fmac_f32_e32 v5, v128, v4
	v_min_f32_e32 v6, 0, v5
	v_mul_f32_e64 v5, |v5|, s14
	v_exp_f32_e32 v5, v5
	s_nop 0
	v_add_f32_e32 v5, 1.0, v5
	v_log_f32_e32 v5, v5
	s_nop 0
	v_fmac_f32_e32 v6, 0xbf317218, v5
	global_store_dword v[2:3], v6, off offset:8 sc0 sc1
	v_mov_b32_e32 v5, v11
	v_fmac_f32_e32 v5, v129, v4
	v_min_f32_e32 v6, 0, v5
	v_mul_f32_e64 v5, |v5|, s14
	v_exp_f32_e32 v5, v5
	s_nop 0
	v_add_f32_e32 v5, 1.0, v5
	v_log_f32_e32 v5, v5
	s_nop 0
	v_fmac_f32_e32 v6, 0xbf317218, v5
	global_store_dword v[2:3], v6, off offset:12 sc0 sc1
	v_mov_b32_e32 v5, v12
	v_fmac_f32_e32 v5, v122, v4
	v_min_f32_e32 v6, 0, v5
	v_mul_f32_e64 v5, |v5|, s14
	v_exp_f32_e32 v5, v5
	s_nop 0
	v_add_f32_e32 v5, 1.0, v5
	v_log_f32_e32 v5, v5
	s_nop 0
	v_fmac_f32_e32 v6, 0xbf317218, v5
	global_store_dword v[2:3], v6, off offset:16 sc0 sc1
	v_mov_b32_e32 v5, v13
	v_fmac_f32_e32 v5, v123, v4
	v_min_f32_e32 v4, 0, v5
	v_mul_f32_e64 v5, |v5|, s14
	v_exp_f32_e32 v5, v5
	s_nop 0
	v_add_f32_e32 v5, 1.0, v5
	v_log_f32_e32 v5, v5
	s_nop 0
	v_fmac_f32_e32 v4, 0xbf317218, v5
	global_store_dword v[2:3], v4, off offset:20 sc0 sc1
	v_mov_b32_e32 v5, v8
	v_add_u32_e32 v2, 0x90, v18
	v_and_b32_e32 v3, 0xff, v2
	v_lshl_add_u32 v3, v3, 2, s12
	ds_read_b32 v4, v3
	v_ashrrev_i32_e32 v3, 31, v2
	v_lshlrev_b64 v[2:3], 5, v[2:3]
	v_lshl_add_u64 v[2:3], s[20:21], 0, v[2:3]
	s_waitcnt lgkmcnt(0)
; __device__ __forceinline__ float fexp2(float x) { return __builtin_amdgcn_exp2f(x); }
; __device__ __forceinline__ float flog2(float x) { return __builtin_amdgcn_logf(x); }
;     __device__ __forceinline__ void operator()(AccRef acc, const pg8::Unit& u, int wr, int wc, int fr, int fq) const {
;     ...
;                 for (int ai = 0; ai < 2; ++ai)
; #pragma unroll
;                     for (int m = 0; m < 4; ++m) {
;                         const int row = row0 + ai * 128 + m * 16;
;                         const float rsr = rst[row & 255];
; #pragma unroll
;                         for (int e = 0; e < 6; ++e) {
;                             const float x = acc[ai][0][m][e >> 2][e & 3] * rsr + fb[e];
;                             const float ls = fminf(x, 0.f) - LN2 * flog2(1.0f + fexp2(-fabsf(x) * LOG2E));
;                             logf[(size_t)row * 8 + e] = ls;
;                         }
;                     }
	v_fmac_f32_e32 v5, v110, v4
	v_min_f32_e32 v6, 0, v5
	v_mul_f32_e64 v5, |v5|, s14
	v_exp_f32_e32 v5, v5
	s_nop 0
	v_add_f32_e32 v5, 1.0, v5
	v_log_f32_e32 v5, v5
	s_nop 0
	v_fmac_f32_e32 v6, 0xbf317218, v5
	global_store_dword v[2:3], v6, off sc0 sc1
	v_mov_b32_e32 v5, v9
	v_fmac_f32_e32 v5, v111, v4
	v_min_f32_e32 v6, 0, v5
	v_mul_f32_e64 v5, |v5|, s14
	v_exp_f32_e32 v5, v5
	s_nop 0
	v_add_f32_e32 v5, 1.0, v5
	v_log_f32_e32 v5, v5
	s_nop 0
	v_fmac_f32_e32 v6, 0xbf317218, v5
	global_store_dword v[2:3], v6, off offset:4 sc0 sc1
	v_mov_b32_e32 v5, v10
	v_fmac_f32_e32 v5, v112, v4
	v_min_f32_e32 v6, 0, v5
	v_mul_f32_e64 v5, |v5|, s14
	v_exp_f32_e32 v5, v5
	s_nop 0
	v_add_f32_e32 v5, 1.0, v5
	v_log_f32_e32 v5, v5
	s_nop 0
	v_fmac_f32_e32 v6, 0xbf317218, v5
	global_store_dword v[2:3], v6, off offset:8 sc0 sc1
	v_mov_b32_e32 v5, v11
	v_fmac_f32_e32 v5, v113, v4
	v_min_f32_e32 v6, 0, v5
	v_mul_f32_e64 v5, |v5|, s14
	v_exp_f32_e32 v5, v5
	s_nop 0
	v_add_f32_e32 v5, 1.0, v5
	v_log_f32_e32 v5, v5
	s_nop 0
	v_fmac_f32_e32 v6, 0xbf317218, v5
	global_store_dword v[2:3], v6, off offset:12 sc0 sc1
	v_mov_b32_e32 v5, v12
	v_fmac_f32_e32 v5, v106, v4
	v_min_f32_e32 v6, 0, v5
	v_mul_f32_e64 v5, |v5|, s14
	v_exp_f32_e32 v5, v5
	s_nop 0
	v_add_f32_e32 v5, 1.0, v5
	v_log_f32_e32 v5, v5
	s_nop 0
	v_fmac_f32_e32 v6, 0xbf317218, v5
	global_store_dword v[2:3], v6, off offset:16 sc0 sc1
	v_mov_b32_e32 v5, v13
	v_fmac_f32_e32 v5, v107, v4
	v_min_f32_e32 v4, 0, v5
	v_mul_f32_e64 v5, |v5|, s14
	v_exp_f32_e32 v5, v5
	s_nop 0
	v_add_f32_e32 v5, 1.0, v5
	v_log_f32_e32 v5, v5
	s_nop 0
	v_fmac_f32_e32 v4, 0xbf317218, v5
	global_store_dword v[2:3], v4, off offset:20 sc0 sc1
	v_mov_b32_e32 v5, v8
	v_add_u32_e32 v2, 0xa0, v18
	v_and_b32_e32 v3, 0xff, v2
	v_lshl_add_u32 v3, v3, 2, s12
	ds_read_b32 v4, v3
	v_ashrrev_i32_e32 v3, 31, v2
	v_lshlrev_b64 v[2:3], 5, v[2:3]
	v_lshl_add_u64 v[2:3], s[20:21], 0, v[2:3]
	s_waitcnt lgkmcnt(0)
	v_fmac_f32_e32 v5, v94, v4
	v_min_f32_e32 v6, 0, v5
	v_mul_f32_e64 v5, |v5|, s14
	v_exp_f32_e32 v5, v5
	s_nop 0
	v_add_f32_e32 v5, 1.0, v5
	v_log_f32_e32 v5, v5
	s_nop 0
	v_fmac_f32_e32 v6, 0xbf317218, v5
	global_store_dword v[2:3], v6, off sc0 sc1
	v_mov_b32_e32 v5, v9
	v_fmac_f32_e32 v5, v95, v4
	v_min_f32_e32 v6, 0, v5
	v_mul_f32_e64 v5, |v5|, s14
	v_exp_f32_e32 v5, v5
	s_nop 0
	v_add_f32_e32 v5, 1.0, v5
	v_log_f32_e32 v5, v5
	s_nop 0
	v_fmac_f32_e32 v6, 0xbf317218, v5
	global_store_dword v[2:3], v6, off offset:4 sc0 sc1
	v_mov_b32_e32 v5, v10
	v_fmac_f32_e32 v5, v96, v4
	v_min_f32_e32 v6, 0, v5
	v_mul_f32_e64 v5, |v5|, s14
	v_exp_f32_e32 v5, v5
	s_nop 0
	v_add_f32_e32 v5, 1.0, v5
	v_log_f32_e32 v5, v5
	s_nop 0
	v_fmac_f32_e32 v6, 0xbf317218, v5
	global_store_dword v[2:3], v6, off offset:8 sc0 sc1
	v_mov_b32_e32 v5, v11
	v_fmac_f32_e32 v5, v97, v4
	v_min_f32_e32 v6, 0, v5
	v_mul_f32_e64 v5, |v5|, s14
	v_exp_f32_e32 v5, v5
	s_nop 0
	v_add_f32_e32 v5, 1.0, v5
	v_log_f32_e32 v5, v5
	s_nop 0
	v_fmac_f32_e32 v6, 0xbf317218, v5
	global_store_dword v[2:3], v6, off offset:12 sc0 sc1
	v_mov_b32_e32 v5, v12
	v_fmac_f32_e32 v5, v90, v4
	v_min_f32_e32 v6, 0, v5
	v_mul_f32_e64 v5, |v5|, s14
	v_exp_f32_e32 v5, v5
	s_nop 0
	v_add_f32_e32 v5, 1.0, v5
	v_log_f32_e32 v5, v5
	s_nop 0
	v_fmac_f32_e32 v6, 0xbf317218, v5
	global_store_dword v[2:3], v6, off offset:16 sc0 sc1
	v_mov_b32_e32 v5, v13
	v_fmac_f32_e32 v5, v91, v4
	v_min_f32_e32 v4, 0, v5
	v_mul_f32_e64 v5, |v5|, s14
	v_exp_f32_e32 v5, v5
	s_nop 0
	v_add_f32_e32 v5, 1.0, v5
	v_log_f32_e32 v5, v5
	s_nop 0
	v_fmac_f32_e32 v4, 0xbf317218, v5
	global_store_dword v[2:3], v4, off offset:20 sc0 sc1
	v_mov_b32_e32 v5, v8
	v_add_u32_e32 v2, 0xb0, v18
	v_and_b32_e32 v3, 0xff, v2
	v_lshl_add_u32 v3, v3, 2, s12
	ds_read_b32 v4, v3
	v_ashrrev_i32_e32 v3, 31, v2
	v_lshlrev_b64 v[2:3], 5, v[2:3]
	v_lshl_add_u64 v[2:3], s[20:21], 0, v[2:3]
	s_waitcnt lgkmcnt(0)
	v_fmac_f32_e32 v5, v78, v4
	v_min_f32_e32 v6, 0, v5
	v_mul_f32_e64 v5, |v5|, s14
	v_exp_f32_e32 v5, v5
	s_nop 0
	v_add_f32_e32 v5, 1.0, v5
	v_log_f32_e32 v5, v5
	s_nop 0
	v_fmac_f32_e32 v6, 0xbf317218, v5
	global_store_dword v[2:3], v6, off sc0 sc1
	v_mov_b32_e32 v5, v9
	v_fmac_f32_e32 v5, v79, v4
	v_min_f32_e32 v6, 0, v5
	v_mul_f32_e64 v5, |v5|, s14
	v_exp_f32_e32 v5, v5
	s_nop 0
	v_add_f32_e32 v5, 1.0, v5
	v_log_f32_e32 v5, v5
	s_nop 0
	v_fmac_f32_e32 v6, 0xbf317218, v5
	global_store_dword v[2:3], v6, off offset:4 sc0 sc1
	v_mov_b32_e32 v5, v10
	v_fmac_f32_e32 v5, v80, v4
	v_min_f32_e32 v6, 0, v5
	v_mul_f32_e64 v5, |v5|, s14
	v_exp_f32_e32 v5, v5
	s_nop 0
	v_add_f32_e32 v5, 1.0, v5
	v_log_f32_e32 v5, v5
	s_nop 0
	v_fmac_f32_e32 v6, 0xbf317218, v5
	global_store_dword v[2:3], v6, off offset:8 sc0 sc1
	v_mov_b32_e32 v5, v11
	v_fmac_f32_e32 v5, v81, v4
	v_min_f32_e32 v6, 0, v5
	v_mul_f32_e64 v5, |v5|, s14
	v_exp_f32_e32 v5, v5
	s_nop 0
	v_add_f32_e32 v5, 1.0, v5
	v_log_f32_e32 v5, v5
	s_nop 0
	v_fmac_f32_e32 v6, 0xbf317218, v5
	global_store_dword v[2:3], v6, off offset:12 sc0 sc1
	v_mov_b32_e32 v5, v12
	v_fmac_f32_e32 v5, v74, v4
	v_min_f32_e32 v6, 0, v5
	v_mul_f32_e64 v5, |v5|, s14
	v_exp_f32_e32 v5, v5
	s_nop 0
	v_add_f32_e32 v5, 1.0, v5
	v_log_f32_e32 v5, v5
	s_nop 0
	v_fmac_f32_e32 v6, 0xbf317218, v5
	global_store_dword v[2:3], v6, off offset:16 sc0 sc1
	v_mov_b32_e32 v5, v13
	v_fmac_f32_e32 v5, v75, v4
	v_min_f32_e32 v4, 0, v5
	v_mul_f32_e64 v5, |v5|, s14
	v_exp_f32_e32 v5, v5
	s_nop 0
	v_add_f32_e32 v5, 1.0, v5
	v_log_f32_e32 v5, v5
	s_nop 0
	v_fmac_f32_e32 v4, 0xbf317218, v5
	global_store_dword v[2:3], v4, off offset:20 sc0 sc1

; __device__ __forceinline__ unsigned pk2(float lo, float hi) { f32x2_t v = {lo, hi}; bf16x2_t b = __builtin_convertvector(v, bf16x2_t); return __builtin_bit_cast(unsigned, b); }
; __device__ __forceinline__ float sigmoidf_(float x) { return __builtin_amdgcn_rcpf(1.0f + fexp2(-x * LOG2E)); }
;     __device__ __forceinline__ void operator()(AccRef acc, const pg8::Unit& u, int wr, int wc, int fr, int fq) const {
;         const int row0 = u.pm * 256 + wr * 64 + fr, col0 = u.pn * 128 + wc * 32 + 8 * fq;
; #pragma unroll
;         for (int ai = 0; ai < 2; ++ai)
; #pragma unroll
;             for (int m = 0; m < 4; ++m) {
;                 const int row = row0 + ai * 128 + m * 16;
;                 const float rs = rst[row & 255];
;                 float v[8];
; #pragma unroll
;                 for (int n = 0; n < 2; ++n)
; #pragma unroll
;                     for (int j = 0; j < 4; ++j) { const float g = acc[ai][0][m][n][j] * rs, up = acc[ai][1][m][n][j] * rs; v[4 * n + j] = g * sigmoidf_(g) * up; }
;                 v4u w; w.x = pk2(v[0], v[1]); w.y = pk2(v[2], v[3]); w.z = pk2(v[4], v[5]); w.w = pk2(v[6], v[7]);
;                 *(v4u*)(U + (size_t)row * FF + col0) = w;
;             }
.LBB0_260:
	s_and_b64 vcc, exec, s[6:7]
	s_cbranch_vccz .LBB0_377
	v_add_u32_e32 v4, s71, v245
	v_lshl_add_u32 v5, s45, 8, v4
	v_add_u32_e32 v36, 0x90, v5
	s_add_i32 s6, 0, 0x20100
	v_and_b32_e32 v14, 0xff, v36
	v_add_u32_e32 v37, 0xa0, v5
	v_add_u32_e32 v7, 16, v5
	v_add_u32_e32 v9, 32, v5
	v_add_u32_e32 v11, 48, v5
	v_lshl_add_u32 v15, v14, 2, s6
	v_and_b32_e32 v14, 0xff, v37
	v_add_u32_e32 v38, 0xb0, v5
	v_and_b32_e32 v4, 0xff, v4
	v_and_b32_e32 v6, 0xff, v7
	v_and_b32_e32 v8, 0xff, v9
	v_and_b32_e32 v10, 0xff, v11
	v_add_u32_e32 v12, 0x80, v5
	v_lshl_add_u32 v16, v14, 2, s6
	v_and_b32_e32 v14, 0xff, v38
	v_lshl_add_u32 v4, v4, 2, s6
	v_lshl_add_u32 v6, v6, 2, s6
	v_lshl_add_u32 v8, v8, 2, s6
	v_lshl_add_u32 v10, v10, 2, s6
	v_and_b32_e32 v13, 0xff, v12
	v_lshl_add_u32 v17, v14, 2, s6
	v_lshl_add_u32 v13, v13, 2, s6
	ds_read_b32 v14, v4
	ds_read_b32 v18, v6
	ds_read_b32 v20, v8
	ds_read_b32 v22, v10
	ds_read_b32 v10, v13
	ds_read_b32 v8, v15
	ds_read_b32 v6, v16
	ds_read_b32 v4, v17
	s_waitcnt lgkmcnt(0)
	v_pk_mul_f32 v[16:17], v[190:191], v[14:15] op_sel_hi:[1,0]
	s_lshl_b32 s3, s40, 7
	v_mul_f32_e32 v13, 0xbfb8aa3b, v16
	v_mul_f32_e32 v15, 0xbfb8aa3b, v17
	v_exp_f32_e32 v13, v13
	v_exp_f32_e32 v15, v15
	s_or_b32 s3, s3, s67
	v_lshl_add_u32 v2, v244, 3, s3
	v_add_f32_e32 v13, 1.0, v13
	v_pk_mul_f32 v[28:29], v[192:193], v[14:15] op_sel_hi:[1,0]
	v_rcp_f32_e32 v24, v13
	v_pk_mul_f32 v[26:27], v[182:183], v[14:15] op_sel_hi:[1,0]
	v_add_f32_e32 v13, 1.0, v15
	v_mul_f32_e32 v15, 0xbfb8aa3b, v28
	v_exp_f32_e32 v15, v15
	v_mul_f32_e32 v19, 0xbfb8aa3b, v29
	v_exp_f32_e32 v19, v19
	v_rcp_f32_e32 v25, v13
	v_add_f32_e32 v13, 1.0, v15
	v_rcp_f32_e32 v30, v13
	v_add_f32_e32 v13, 1.0, v19
	v_rcp_f32_e32 v31, v13
	v_pk_mul_f32 v[16:17], v[16:17], v[24:25]
	v_pk_mul_f32 v[24:25], v[184:185], v[14:15] op_sel_hi:[1,0]
	v_pk_mul_f32 v[16:17], v[26:27], v[16:17]
	v_pk_mul_f32 v[26:27], v[28:29], v[30:31]
	v_pk_mul_f32 v[28:29], v[186:187], v[14:15] op_sel_hi:[1,0]
	v_pk_mul_f32 v[24:25], v[24:25], v[26:27]
	v_mul_f32_e32 v13, 0xbfb8aa3b, v28
	v_mul_f32_e32 v15, 0xbfb8aa3b, v29
	v_exp_f32_e32 v13, v13
	v_exp_f32_e32 v15, v15
	v_readlane_b32 s6, v255, 23
	v_ashrrev_i32_e32 v3, 31, v2
	v_add_f32_e32 v13, 1.0, v13
	v_pk_mul_f32 v[32:33], v[188:189], v[14:15] op_sel_hi:[1,0]
	v_rcp_f32_e32 v26, v13
	v_pk_mul_f32 v[30:31], v[178:179], v[14:15] op_sel_hi:[1,0]
	v_add_f32_e32 v13, 1.0, v15
	v_mul_f32_e32 v15, 0xbfb8aa3b, v32
	v_exp_f32_e32 v15, v15
	v_mul_f32_e32 v19, 0xbfb8aa3b, v33
	v_exp_f32_e32 v19, v19
	v_rcp_f32_e32 v27, v13
	v_add_f32_e32 v13, 1.0, v15
	v_rcp_f32_e32 v34, v13
	v_add_f32_e32 v13, 1.0, v19
	v_rcp_f32_e32 v35, v13
	v_pk_mul_f32 v[26:27], v[28:29], v[26:27]
	v_readlane_b32 s7, v255, 24
	v_pk_mul_f32 v[26:27], v[30:31], v[26:27]
	v_pk_mul_f32 v[14:15], v[180:181], v[14:15] op_sel_hi:[1,0]
	v_pk_mul_f32 v[28:29], v[32:33], v[34:35]
	v_lshl_add_u64 v[2:3], v[2:3], 1, s[6:7]
	v_pk_mul_f32 v[28:29], v[14:15], v[28:29]
	v_cvt_pk_bf16_f32 v14, v16, v17
	v_cvt_pk_bf16_f32 v16, v26, v27
	s_movk_i32 s3, 0x1600
	v_pk_mul_f32 v[26:27], v[174:175], v[18:19] op_sel_hi:[1,0]
	v_cvt_pk_bf16_f32 v15, v24, v25
	v_mad_i64_i32 v[24:25], s[6:7], v5, s3, v[2:3]
	v_mul_f32_e32 v5, 0xbfb8aa3b, v26
	v_exp_f32_e32 v5, v5
	v_mul_f32_e32 v13, 0xbfb8aa3b, v27
	v_exp_f32_e32 v13, v13
	v_cvt_pk_bf16_f32 v17, v28, v29
	global_store_dwordx4 v[24:25], v[14:17], off sc0 sc1
	v_add_f32_e32 v5, 1.0, v5
	v_pk_mul_f32 v[24:25], v[176:177], v[18:19] op_sel_hi:[1,0]
	v_rcp_f32_e32 v14, v5
	v_add_f32_e32 v5, 1.0, v13
	v_mul_f32_e32 v13, 0xbfb8aa3b, v24
	v_exp_f32_e32 v13, v13
	v_mul_f32_e32 v15, 0xbfb8aa3b, v25
	v_pk_mul_f32 v[16:17], v[166:167], v[18:19] op_sel_hi:[1,0]
	v_exp_f32_e32 v19, v15
	v_rcp_f32_e32 v15, v5
	v_add_f32_e32 v5, 1.0, v13
	v_rcp_f32_e32 v28, v5
	v_add_f32_e32 v5, 1.0, v19
	v_pk_mul_f32 v[14:15], v[26:27], v[14:15]
	v_pk_mul_f32 v[26:27], v[170:171], v[18:19] op_sel_hi:[1,0]
	v_rcp_f32_e32 v29, v5
	v_mul_f32_e32 v5, 0xbfb8aa3b, v26
	v_exp_f32_e32 v5, v5
	v_mul_f32_e32 v13, 0xbfb8aa3b, v27
	v_exp_f32_e32 v13, v13
	v_pk_mul_f32 v[14:15], v[16:17], v[14:15]
	v_pk_mul_f32 v[16:17], v[168:169], v[18:19] op_sel_hi:[1,0]
	v_pk_mul_f32 v[24:25], v[24:25], v[28:29]
	v_add_f32_e32 v5, 1.0, v5
	v_pk_mul_f32 v[30:31], v[172:173], v[18:19] op_sel_hi:[1,0]
	v_pk_mul_f32 v[16:17], v[16:17], v[24:25]
	v_rcp_f32_e32 v24, v5
	v_add_f32_e32 v5, 1.0, v13
	v_mul_f32_e32 v13, 0xbfb8aa3b, v30
	v_pk_mul_f32 v[28:29], v[162:163], v[18:19] op_sel_hi:[1,0]
	v_exp_f32_e32 v13, v13
	v_mul_f32_e32 v19, 0xbfb8aa3b, v31
	v_exp_f32_e32 v19, v19
	v_rcp_f32_e32 v25, v5
	v_add_f32_e32 v5, 1.0, v13
	v_rcp_f32_e32 v32, v5
	v_add_f32_e32 v5, 1.0, v19
	v_rcp_f32_e32 v33, v5
	v_pk_mul_f32 v[24:25], v[26:27], v[24:25]
	v_pk_mul_f32 v[18:19], v[164:165], v[18:19] op_sel_hi:[1,0]
	v_pk_mul_f32 v[24:25], v[28:29], v[24:25]
	v_pk_mul_f32 v[26:27], v[30:31], v[32:33]
	v_cvt_pk_bf16_f32 v14, v14, v15
	v_cvt_pk_bf16_f32 v15, v16, v17
	v_cvt_pk_bf16_f32 v16, v24, v25
	v_pk_mul_f32 v[24:25], v[158:159], v[20:21] op_sel_hi:[1,0]
	v_pk_mul_f32 v[18:19], v[18:19], v[26:27]
	v_mul_f32_e32 v5, 0xbfb8aa3b, v24
	v_cvt_pk_bf16_f32 v17, v18, v19
	v_mad_i64_i32 v[18:19], s[6:7], v7, s3, v[2:3]
	v_exp_f32_e32 v5, v5
	v_mul_f32_e32 v7, 0xbfb8aa3b, v25
	v_exp_f32_e32 v7, v7
	global_store_dwordx4 v[18:19], v[14:17], off sc0 sc1
	v_add_f32_e32 v5, 1.0, v5
	v_pk_mul_f32 v[18:19], v[160:161], v[20:21] op_sel_hi:[1,0]
	v_rcp_f32_e32 v14, v5
	v_add_f32_e32 v5, 1.0, v7
	v_mul_f32_e32 v7, 0xbfb8aa3b, v18
	v_exp_f32_e32 v7, v7
	v_mul_f32_e32 v13, 0xbfb8aa3b, v19
	v_exp_f32_e32 v13, v13
	v_rcp_f32_e32 v15, v5
	v_add_f32_e32 v5, 1.0, v7
; __device__ __forceinline__ unsigned pk2(float lo, float hi) { f32x2_t v = {lo, hi}; bf16x2_t b = __builtin_convertvector(v, bf16x2_t); return __builtin_bit_cast(unsigned, b); }
; __device__ __forceinline__ float sigmoidf_(float x) { return __builtin_amdgcn_rcpf(1.0f + fexp2(-x * LOG2E)); }
;     __device__ __forceinline__ void operator()(AccRef acc, const pg8::Unit& u, int wr, int wc, int fr, int fq) const {
;         const int row0 = u.pm * 256 + wr * 64 + fr, col0 = u.pn * 128 + wc * 32 + 8 * fq;
; #pragma unroll
;         for (int ai = 0; ai < 2; ++ai)
; #pragma unroll
;             for (int m = 0; m < 4; ++m) {
;                 const int row = row0 + ai * 128 + m * 16;
;                 const float rs = rst[row & 255];
;                 float v[8];
; #pragma unroll
;                 for (int n = 0; n < 2; ++n)
; #pragma unroll
;                     for (int j = 0; j < 4; ++j) { const float g = acc[ai][0][m][n][j] * rs, up = acc[ai][1][m][n][j] * rs; v[4 * n + j] = g * sigmoidf_(g) * up; }
;                 v4u w; w.x = pk2(v[0], v[1]); w.y = pk2(v[2], v[3]); w.z = pk2(v[4], v[5]); w.w = pk2(v[6], v[7]);
;                 *(v4u*)(U + (size_t)row * FF + col0) = w;
;             }
	v_rcp_f32_e32 v26, v5
	v_add_f32_e32 v5, 1.0, v13
	v_pk_mul_f32 v[14:15], v[24:25], v[14:15]
	v_pk_mul_f32 v[24:25], v[154:155], v[20:21] op_sel_hi:[1,0]
	v_rcp_f32_e32 v27, v5
	v_mul_f32_e32 v5, 0xbfb8aa3b, v24
	v_exp_f32_e32 v5, v5
	v_mul_f32_e32 v7, 0xbfb8aa3b, v25
	v_exp_f32_e32 v7, v7
	v_pk_mul_f32 v[16:17], v[150:151], v[20:21] op_sel_hi:[1,0]
	v_pk_mul_f32 v[18:19], v[18:19], v[26:27]
	v_pk_mul_f32 v[14:15], v[16:17], v[14:15]
	v_pk_mul_f32 v[16:17], v[152:153], v[20:21] op_sel_hi:[1,0]
	v_add_f32_e32 v5, 1.0, v5
	v_pk_mul_f32 v[28:29], v[156:157], v[20:21] op_sel_hi:[1,0]
	v_pk_mul_f32 v[16:17], v[16:17], v[18:19]
	v_rcp_f32_e32 v18, v5
	v_add_f32_e32 v5, 1.0, v7
	v_mul_f32_e32 v7, 0xbfb8aa3b, v28
	v_exp_f32_e32 v7, v7
	v_mul_f32_e32 v13, 0xbfb8aa3b, v29
	v_exp_f32_e32 v13, v13
	v_rcp_f32_e32 v19, v5
	v_add_f32_e32 v5, 1.0, v7
	v_rcp_f32_e32 v30, v5
	v_add_f32_e32 v5, 1.0, v13
	v_rcp_f32_e32 v31, v5
	v_pk_mul_f32 v[26:27], v[146:147], v[20:21] op_sel_hi:[1,0]
	v_pk_mul_f32 v[18:19], v[24:25], v[18:19]
	v_pk_mul_f32 v[20:21], v[148:149], v[20:21] op_sel_hi:[1,0]
	v_pk_mul_f32 v[24:25], v[28:29], v[30:31]
	v_cvt_pk_bf16_f32 v14, v14, v15
	v_pk_mul_f32 v[20:21], v[20:21], v[24:25]
	v_cvt_pk_bf16_f32 v15, v16, v17
	v_cvt_pk_bf16_f32 v17, v20, v21
	v_pk_mul_f32 v[20:21], v[142:143], v[22:23] op_sel_hi:[1,0]
	v_pk_mul_f32 v[18:19], v[26:27], v[18:19]
	v_mul_f32_e32 v5, 0xbfb8aa3b, v20
	v_exp_f32_e32 v5, v5
	v_mul_f32_e32 v7, 0xbfb8aa3b, v21
	v_exp_f32_e32 v7, v7
	v_cvt_pk_bf16_f32 v16, v18, v19
	v_mad_i64_i32 v[18:19], s[6:7], v9, s3, v[2:3]
	global_store_dwordx4 v[18:19], v[14:17], off sc0 sc1
	v_add_f32_e32 v5, 1.0, v5
	v_pk_mul_f32 v[18:19], v[144:145], v[22:23] op_sel_hi:[1,0]
	v_rcp_f32_e32 v14, v5
	v_add_f32_e32 v5, 1.0, v7
	v_mul_f32_e32 v7, 0xbfb8aa3b, v18
	v_exp_f32_e32 v7, v7
	v_mul_f32_e32 v9, 0xbfb8aa3b, v19
	v_exp_f32_e32 v9, v9
	v_rcp_f32_e32 v15, v5
	v_add_f32_e32 v5, 1.0, v7
	v_rcp_f32_e32 v24, v5
	v_add_f32_e32 v5, 1.0, v9
	v_pk_mul_f32 v[14:15], v[20:21], v[14:15]
	v_pk_mul_f32 v[20:21], v[138:139], v[22:23] op_sel_hi:[1,0]
	v_rcp_f32_e32 v25, v5
	v_mul_f32_e32 v5, 0xbfb8aa3b, v20
	v_exp_f32_e32 v5, v5
	v_mul_f32_e32 v7, 0xbfb8aa3b, v21
	v_exp_f32_e32 v7, v7
	v_pk_mul_f32 v[16:17], v[134:135], v[22:23] op_sel_hi:[1,0]
	v_pk_mul_f32 v[18:19], v[18:19], v[24:25]
	v_pk_mul_f32 v[14:15], v[16:17], v[14:15]
	v_pk_mul_f32 v[16:17], v[136:137], v[22:23] op_sel_hi:[1,0]
	v_add_f32_e32 v5, 1.0, v5
	v_pk_mul_f32 v[26:27], v[140:141], v[22:23] op_sel_hi:[1,0]
	v_pk_mul_f32 v[16:17], v[16:17], v[18:19]
	v_rcp_f32_e32 v18, v5
	v_add_f32_e32 v5, 1.0, v7
	v_mul_f32_e32 v7, 0xbfb8aa3b, v26
	v_exp_f32_e32 v7, v7
	v_mul_f32_e32 v9, 0xbfb8aa3b, v27
	v_exp_f32_e32 v9, v9
	v_rcp_f32_e32 v19, v5
	v_add_f32_e32 v5, 1.0, v7
	v_rcp_f32_e32 v28, v5
	v_add_f32_e32 v5, 1.0, v9
	v_rcp_f32_e32 v29, v5
	v_pk_mul_f32 v[24:25], v[130:131], v[22:23] op_sel_hi:[1,0]
	v_pk_mul_f32 v[18:19], v[20:21], v[18:19]
	v_pk_mul_f32 v[20:21], v[132:133], v[22:23] op_sel_hi:[1,0]
	v_pk_mul_f32 v[22:23], v[26:27], v[28:29]
	v_cvt_pk_bf16_f32 v14, v14, v15
	v_pk_mul_f32 v[20:21], v[20:21], v[22:23]
	v_cvt_pk_bf16_f32 v15, v16, v17
	v_cvt_pk_bf16_f32 v17, v20, v21
	v_pk_mul_f32 v[20:21], v[126:127], v[10:11] op_sel_hi:[1,0]
	v_pk_mul_f32 v[18:19], v[24:25], v[18:19]
	v_mul_f32_e32 v5, 0xbfb8aa3b, v20
	v_exp_f32_e32 v5, v5
	v_mul_f32_e32 v7, 0xbfb8aa3b, v21
	v_exp_f32_e32 v7, v7
	v_cvt_pk_bf16_f32 v16, v18, v19
	v_mad_i64_i32 v[18:19], s[6:7], v11, s3, v[2:3]
	global_store_dwordx4 v[18:19], v[14:17], off sc0 sc1
	v_add_f32_e32 v5, 1.0, v5
	v_pk_mul_f32 v[18:19], v[128:129], v[10:11] op_sel_hi:[1,0]
	v_rcp_f32_e32 v14, v5
	v_add_f32_e32 v5, 1.0, v7
	v_mul_f32_e32 v7, 0xbfb8aa3b, v18
	v_exp_f32_e32 v7, v7
	v_mul_f32_e32 v9, 0xbfb8aa3b, v19
	v_exp_f32_e32 v9, v9
	v_rcp_f32_e32 v15, v5
	v_add_f32_e32 v5, 1.0, v7
	v_rcp_f32_e32 v22, v5
	v_add_f32_e32 v5, 1.0, v9
	v_pk_mul_f32 v[14:15], v[20:21], v[14:15]
	v_pk_mul_f32 v[20:21], v[122:123], v[10:11] op_sel_hi:[1,0]
	v_rcp_f32_e32 v23, v5
	v_mul_f32_e32 v5, 0xbfb8aa3b, v20
	v_exp_f32_e32 v5, v5
	v_mul_f32_e32 v7, 0xbfb8aa3b, v21
	v_exp_f32_e32 v7, v7
	v_pk_mul_f32 v[16:17], v[118:119], v[10:11] op_sel_hi:[1,0]
	v_pk_mul_f32 v[18:19], v[18:19], v[22:23]
	v_pk_mul_f32 v[14:15], v[16:17], v[14:15]
	v_pk_mul_f32 v[16:17], v[120:121], v[10:11] op_sel_hi:[1,0]
	v_add_f32_e32 v5, 1.0, v5
	v_pk_mul_f32 v[24:25], v[124:125], v[10:11] op_sel_hi:[1,0]
	v_pk_mul_f32 v[16:17], v[16:17], v[18:19]
	v_rcp_f32_e32 v18, v5
	v_add_f32_e32 v5, 1.0, v7
	v_mul_f32_e32 v7, 0xbfb8aa3b, v24
	v_exp_f32_e32 v7, v7
	v_mul_f32_e32 v9, 0xbfb8aa3b, v25
	v_exp_f32_e32 v9, v9
	v_rcp_f32_e32 v19, v5
	v_add_f32_e32 v5, 1.0, v7
	v_rcp_f32_e32 v26, v5
	v_add_f32_e32 v5, 1.0, v9
	v_rcp_f32_e32 v27, v5
	v_pk_mul_f32 v[22:23], v[114:115], v[10:11] op_sel_hi:[1,0]
	v_pk_mul_f32 v[18:19], v[20:21], v[18:19]
	v_pk_mul_f32 v[10:11], v[116:117], v[10:11] op_sel_hi:[1,0]
	v_pk_mul_f32 v[20:21], v[24:25], v[26:27]
	v_cvt_pk_bf16_f32 v14, v14, v15
	v_pk_mul_f32 v[10:11], v[10:11], v[20:21]
	v_cvt_pk_bf16_f32 v15, v16, v17
	v_cvt_pk_bf16_f32 v17, v10, v11
	v_mad_i64_i32 v[10:11], s[6:7], v12, s3, v[2:3]
	v_pk_mul_f32 v[12:13], v[110:111], v[8:9] op_sel_hi:[1,0]
	v_pk_mul_f32 v[18:19], v[22:23], v[18:19]
	v_mul_f32_e32 v5, 0xbfb8aa3b, v12
	v_exp_f32_e32 v5, v5
	v_mul_f32_e32 v7, 0xbfb8aa3b, v13
	v_exp_f32_e32 v7, v7
	v_cvt_pk_bf16_f32 v16, v18, v19
	global_store_dwordx4 v[10:11], v[14:17], off sc0 sc1
	v_add_f32_e32 v5, 1.0, v5
	v_rcp_f32_e32 v10, v5
; __device__ __forceinline__ unsigned pk2(float lo, float hi) { f32x2_t v = {lo, hi}; bf16x2_t b = __builtin_convertvector(v, bf16x2_t); return __builtin_bit_cast(unsigned, b); }
; __device__ __forceinline__ float sigmoidf_(float x) { return __builtin_amdgcn_rcpf(1.0f + fexp2(-x * LOG2E)); }
;     __device__ __forceinline__ void operator()(AccRef acc, const pg8::Unit& u, int wr, int wc, int fr, int fq) const {
;         const int row0 = u.pm * 256 + wr * 64 + fr, col0 = u.pn * 128 + wc * 32 + 8 * fq;
; #pragma unroll
;         for (int ai = 0; ai < 2; ++ai)
; #pragma unroll
;             for (int m = 0; m < 4; ++m) {
;                 const int row = row0 + ai * 128 + m * 16;
;                 const float rs = rst[row & 255];
;                 float v[8];
; #pragma unroll
;                 for (int n = 0; n < 2; ++n)
; #pragma unroll
;                     for (int j = 0; j < 4; ++j) { const float g = acc[ai][0][m][n][j] * rs, up = acc[ai][1][m][n][j] * rs; v[4 * n + j] = g * sigmoidf_(g) * up; }
;                 v4u w; w.x = pk2(v[0], v[1]); w.y = pk2(v[2], v[3]); w.z = pk2(v[4], v[5]); w.w = pk2(v[6], v[7]);
;                 *(v4u*)(U + (size_t)row * FF + col0) = w;
;             }
	v_pk_mul_f32 v[16:17], v[112:113], v[8:9] op_sel_hi:[1,0]
	v_add_f32_e32 v5, 1.0, v7
	v_mul_f32_e32 v7, 0xbfb8aa3b, v16
	v_pk_mul_f32 v[14:15], v[102:103], v[8:9] op_sel_hi:[1,0]
	v_exp_f32_e32 v7, v7
	v_mul_f32_e32 v9, 0xbfb8aa3b, v17
	v_exp_f32_e32 v9, v9
	v_rcp_f32_e32 v11, v5
	v_add_f32_e32 v5, 1.0, v7
	v_rcp_f32_e32 v18, v5
	v_add_f32_e32 v5, 1.0, v9
	v_rcp_f32_e32 v19, v5
	v_pk_mul_f32 v[10:11], v[12:13], v[10:11]
	v_pk_mul_f32 v[12:13], v[104:105], v[8:9] op_sel_hi:[1,0]
	v_pk_mul_f32 v[10:11], v[14:15], v[10:11]
	v_pk_mul_f32 v[14:15], v[16:17], v[18:19]
	v_pk_mul_f32 v[16:17], v[106:107], v[8:9] op_sel_hi:[1,0]
	v_pk_mul_f32 v[20:21], v[108:109], v[8:9] op_sel_hi:[1,0]
	v_mul_f32_e32 v5, 0xbfb8aa3b, v16
	v_exp_f32_e32 v5, v5
	v_mul_f32_e32 v7, 0xbfb8aa3b, v17
	v_exp_f32_e32 v7, v7
	v_pk_mul_f32 v[12:13], v[12:13], v[14:15]
	v_add_f32_e32 v5, 1.0, v5
	v_rcp_f32_e32 v14, v5
	v_add_f32_e32 v5, 1.0, v7
	v_mul_f32_e32 v7, 0xbfb8aa3b, v20
	v_pk_mul_f32 v[18:19], v[98:99], v[8:9] op_sel_hi:[1,0]
	v_exp_f32_e32 v7, v7
	v_mul_f32_e32 v9, 0xbfb8aa3b, v21
	v_exp_f32_e32 v9, v9
	v_rcp_f32_e32 v15, v5
	v_add_f32_e32 v5, 1.0, v7
	v_rcp_f32_e32 v22, v5
	v_add_f32_e32 v5, 1.0, v9
	v_rcp_f32_e32 v23, v5
	v_pk_mul_f32 v[14:15], v[16:17], v[14:15]
	v_pk_mul_f32 v[8:9], v[100:101], v[8:9] op_sel_hi:[1,0]
	v_pk_mul_f32 v[14:15], v[18:19], v[14:15]
	v_pk_mul_f32 v[16:17], v[20:21], v[22:23]
	s_nop 0
	v_pk_mul_f32 v[16:17], v[8:9], v[16:17]
	v_cvt_pk_bf16_f32 v8, v10, v11
	v_cvt_pk_bf16_f32 v10, v14, v15
	v_pk_mul_f32 v[14:15], v[94:95], v[6:7] op_sel_hi:[1,0]
	v_cvt_pk_bf16_f32 v9, v12, v13
	v_mul_f32_e32 v5, 0xbfb8aa3b, v14
	v_mul_f32_e32 v7, 0xbfb8aa3b, v15
	v_exp_f32_e32 v5, v5
	v_exp_f32_e32 v7, v7
	v_cvt_pk_bf16_f32 v11, v16, v17
	v_mad_i64_i32 v[12:13], s[6:7], v36, s3, v[2:3]
	global_store_dwordx4 v[12:13], v[8:11], off sc0 sc1
	v_add_f32_e32 v5, 1.0, v5
	v_pk_mul_f32 v[12:13], v[96:97], v[6:7] op_sel_hi:[1,0]
	v_rcp_f32_e32 v8, v5
	v_pk_mul_f32 v[10:11], v[86:87], v[6:7] op_sel_hi:[1,0]
	v_add_f32_e32 v5, 1.0, v7
	v_mul_f32_e32 v7, 0xbfb8aa3b, v12
	v_exp_f32_e32 v7, v7
	v_mul_f32_e32 v9, 0xbfb8aa3b, v13
	v_exp_f32_e32 v17, v9
	v_rcp_f32_e32 v9, v5
	v_add_f32_e32 v5, 1.0, v7
	v_rcp_f32_e32 v16, v5
	v_add_f32_e32 v5, 1.0, v17
	v_pk_mul_f32 v[8:9], v[14:15], v[8:9]
	v_pk_mul_f32 v[14:15], v[90:91], v[6:7] op_sel_hi:[1,0]
	v_rcp_f32_e32 v17, v5
	v_pk_mul_f32 v[8:9], v[10:11], v[8:9]
	v_pk_mul_f32 v[10:11], v[88:89], v[6:7] op_sel_hi:[1,0]
	v_mul_f32_e32 v5, 0xbfb8aa3b, v14
	v_mul_f32_e32 v7, 0xbfb8aa3b, v15
	v_exp_f32_e32 v5, v5
	v_exp_f32_e32 v7, v7
	v_pk_mul_f32 v[12:13], v[12:13], v[16:17]
	v_add_f32_e32 v5, 1.0, v5
	v_pk_mul_f32 v[18:19], v[92:93], v[6:7] op_sel_hi:[1,0]
	v_pk_mul_f32 v[10:11], v[10:11], v[12:13]
	v_rcp_f32_e32 v12, v5
	v_pk_mul_f32 v[16:17], v[82:83], v[6:7] op_sel_hi:[1,0]
	v_add_f32_e32 v5, 1.0, v7
	v_mul_f32_e32 v7, 0xbfb8aa3b, v18
	v_exp_f32_e32 v7, v7
	v_mul_f32_e32 v13, 0xbfb8aa3b, v19
	v_exp_f32_e32 v21, v13
	v_rcp_f32_e32 v13, v5
	v_add_f32_e32 v5, 1.0, v7
	v_rcp_f32_e32 v20, v5
	v_add_f32_e32 v5, 1.0, v21
	v_rcp_f32_e32 v21, v5
	v_pk_mul_f32 v[12:13], v[14:15], v[12:13]
	v_pk_mul_f32 v[6:7], v[84:85], v[6:7] op_sel_hi:[1,0]
	v_pk_mul_f32 v[12:13], v[16:17], v[12:13]
	v_pk_mul_f32 v[14:15], v[18:19], v[20:21]
	s_nop 0
	v_pk_mul_f32 v[14:15], v[6:7], v[14:15]
	v_cvt_pk_bf16_f32 v6, v8, v9
	v_cvt_pk_bf16_f32 v8, v12, v13
	v_pk_mul_f32 v[12:13], v[78:79], v[4:5] op_sel_hi:[1,0]
	v_cvt_pk_bf16_f32 v7, v10, v11
	v_cvt_pk_bf16_f32 v9, v14, v15
	v_mad_i64_i32 v[10:11], s[6:7], v37, s3, v[2:3]
	v_mul_f32_e32 v5, 0xbfb8aa3b, v12
	v_exp_f32_e32 v5, v5
	global_store_dwordx4 v[10:11], v[6:9], off sc0 sc1
	v_mad_i64_i32 v[2:3], s[6:7], v38, s3, v[2:3]
	s_nop 0
	v_mul_f32_e32 v6, 0xbfb8aa3b, v13
	v_exp_f32_e32 v7, v6
	v_add_f32_e32 v5, 1.0, v5
	v_rcp_f32_e32 v6, v5
	v_pk_mul_f32 v[8:9], v[70:71], v[4:5] op_sel_hi:[1,0]
	v_add_f32_e32 v5, 1.0, v7
	v_pk_mul_f32 v[10:11], v[80:81], v[4:5] op_sel_hi:[1,0]
	s_nop 0
	v_mul_f32_e32 v7, 0xbfb8aa3b, v10
	v_exp_f32_e32 v14, v7
	v_mul_f32_e32 v7, 0xbfb8aa3b, v11
	v_exp_f32_e32 v15, v7
	v_rcp_f32_e32 v7, v5
	v_add_f32_e32 v5, 1.0, v14
	v_rcp_f32_e32 v14, v5
	v_add_f32_e32 v5, 1.0, v15
	v_rcp_f32_e32 v15, v5
	v_pk_mul_f32 v[6:7], v[12:13], v[6:7]
	v_pk_mul_f32 v[12:13], v[74:75], v[4:5] op_sel_hi:[1,0]
	v_pk_mul_f32 v[6:7], v[8:9], v[6:7]
	v_pk_mul_f32 v[8:9], v[72:73], v[4:5] op_sel_hi:[1,0]
	v_pk_mul_f32 v[10:11], v[10:11], v[14:15]
	v_mul_f32_e32 v5, 0xbfb8aa3b, v12
	v_exp_f32_e32 v5, v5
	v_pk_mul_f32 v[8:9], v[8:9], v[10:11]
	v_mul_f32_e32 v10, 0xbfb8aa3b, v13
	v_exp_f32_e32 v11, v10
	v_add_f32_e32 v5, 1.0, v5
	v_rcp_f32_e32 v10, v5
	v_pk_mul_f32 v[14:15], v[66:67], v[4:5] op_sel_hi:[1,0]
	v_add_f32_e32 v5, 1.0, v11
	v_pk_mul_f32 v[16:17], v[76:77], v[4:5] op_sel_hi:[1,0]
	s_nop 0
	v_mul_f32_e32 v11, 0xbfb8aa3b, v16
	v_exp_f32_e32 v18, v11
	v_mul_f32_e32 v11, 0xbfb8aa3b, v17
	v_exp_f32_e32 v19, v11
	v_rcp_f32_e32 v11, v5
	v_add_f32_e32 v5, 1.0, v18
	v_rcp_f32_e32 v18, v5
	v_add_f32_e32 v5, 1.0, v19
	v_rcp_f32_e32 v19, v5
	v_pk_mul_f32 v[10:11], v[12:13], v[10:11]
	v_pk_mul_f32 v[4:5], v[68:69], v[4:5] op_sel_hi:[1,0]
	v_pk_mul_f32 v[10:11], v[14:15], v[10:11]
	v_pk_mul_f32 v[12:13], v[16:17], v[18:19]
	s_nop 0
	v_pk_mul_f32 v[12:13], v[4:5], v[12:13]
	v_cvt_pk_bf16_f32 v4, v6, v7
	v_cvt_pk_bf16_f32 v5, v8, v9
	v_cvt_pk_bf16_f32 v6, v10, v11
	v_cvt_pk_bf16_f32 v7, v12, v13
	global_store_dwordx4 v[2:3], v[4:7], off sc0 sc1
	s_andn2_b64 vcc, exec, s[96:97]
	s_cbranch_vccnz .LBB0_469
	s_branch .LBB0_378

; __device__ __forceinline__ unsigned pk2(float lo, float hi) { f32x2_t v = {lo, hi}; bf16x2_t b = __builtin_convertvector(v, bf16x2_t); return __builtin_bit_cast(unsigned, b); }
;     __device__ __forceinline__ void operator()(AccRef acc, const pg8::Unit& u, int wr, int wc, int fr, int fq) const {
;     ...
;                     v4u w; w.x = pk2(v[0], v[1]); w.y = pk2(v[2], v[3]); w.z = pk2(v[4], v[5]); w.w = pk2(v[6], v[7]);
;                     if (!last) TMP[ci] = w;
;                     else *(v4u*)(MRG + (size_t)(row0 + ai * 128 + m * 16) * D + col0 + bj * 128) = w;
.Lgate_f_m0:
	global_store_dwordx4 v226, v[2:5], s[8:9] sc0 sc1
	s_add_u32 s8, s8, 0x8000
	s_addc_u32 s9, s9, 0

; __device__ __forceinline__ unsigned pk2(float lo, float hi) { f32x2_t v = {lo, hi}; bf16x2_t b = __builtin_convertvector(v, bf16x2_t); return __builtin_bit_cast(unsigned, b); }
;     __device__ __forceinline__ void operator()(AccRef acc, const pg8::Unit& u, int wr, int wc, int fr, int fq) const {
;     ...
;                     v4u w; w.x = pk2(v[0], v[1]); w.y = pk2(v[2], v[3]); w.z = pk2(v[4], v[5]); w.w = pk2(v[6], v[7]);
;                     if (!last) TMP[ci] = w;
;                     else *(v4u*)(MRG + (size_t)(row0 + ai * 128 + m * 16) * D + col0 + bj * 128) = w;
.Lgate_f_m1:
	global_store_dwordx4 v226, v[10:13], s[8:9] sc0 sc1
	s_add_u32 s8, s8, 0x8000
	s_addc_u32 s9, s9, 0

; __device__ __forceinline__ unsigned pk2(float lo, float hi) { f32x2_t v = {lo, hi}; bf16x2_t b = __builtin_convertvector(v, bf16x2_t); return __builtin_bit_cast(unsigned, b); }
;     __device__ __forceinline__ void operator()(AccRef acc, const pg8::Unit& u, int wr, int wc, int fr, int fq) const {
;     ...
;                     v4u w; w.x = pk2(v[0], v[1]); w.y = pk2(v[2], v[3]); w.z = pk2(v[4], v[5]); w.w = pk2(v[6], v[7]);
;                     if (!last) TMP[ci] = w;
;                     else *(v4u*)(MRG + (size_t)(row0 + ai * 128 + m * 16) * D + col0 + bj * 128) = w;
.Lgate_f_m2:
	global_store_dwordx4 v226, v[18:21], s[8:9] sc0 sc1
	s_add_u32 s8, s8, 0x8000
	s_addc_u32 s9, s9, 0

; __device__ __forceinline__ unsigned pk2(float lo, float hi) { f32x2_t v = {lo, hi}; bf16x2_t b = __builtin_convertvector(v, bf16x2_t); return __builtin_bit_cast(unsigned, b); }
;     __device__ __forceinline__ void operator()(AccRef acc, const pg8::Unit& u, int wr, int wc, int fr, int fq) const {
;     ...
;                     v4u w; w.x = pk2(v[0], v[1]); w.y = pk2(v[2], v[3]); w.z = pk2(v[4], v[5]); w.w = pk2(v[6], v[7]);
;                     if (!last) TMP[ci] = w;
;                     else *(v4u*)(MRG + (size_t)(row0 + ai * 128 + m * 16) * D + col0 + bj * 128) = w;
.Lgate_f_m3:
	global_store_dwordx4 v226, v[26:29], s[8:9] sc0 sc1
	s_sub_u32 s8, s8, 0x17f00
	s_subb_u32 s9, s9, 0

; __device__ __forceinline__ unsigned pk2(float lo, float hi) { f32x2_t v = {lo, hi}; bf16x2_t b = __builtin_convertvector(v, bf16x2_t); return __builtin_bit_cast(unsigned, b); }
;     __device__ __forceinline__ void operator()(AccRef acc, const pg8::Unit& u, int wr, int wc, int fr, int fq) const {
;     ...
;                     v4u w; w.x = pk2(v[0], v[1]); w.y = pk2(v[2], v[3]); w.z = pk2(v[4], v[5]); w.w = pk2(v[6], v[7]);
;                     if (!last) TMP[ci] = w;
;                     else *(v4u*)(MRG + (size_t)(row0 + ai * 128 + m * 16) * D + col0 + bj * 128) = w;
.Lgate_f_m4:
	global_store_dwordx4 v226, v[34:37], s[8:9] sc0 sc1
	s_add_u32 s8, s8, 0x8000
	s_addc_u32 s9, s9, 0

; __device__ __forceinline__ unsigned pk2(float lo, float hi) { f32x2_t v = {lo, hi}; bf16x2_t b = __builtin_convertvector(v, bf16x2_t); return __builtin_bit_cast(unsigned, b); }
;     __device__ __forceinline__ void operator()(AccRef acc, const pg8::Unit& u, int wr, int wc, int fr, int fq) const {
;     ...
;                     v4u w; w.x = pk2(v[0], v[1]); w.y = pk2(v[2], v[3]); w.z = pk2(v[4], v[5]); w.w = pk2(v[6], v[7]);
;                     if (!last) TMP[ci] = w;
;                     else *(v4u*)(MRG + (size_t)(row0 + ai * 128 + m * 16) * D + col0 + bj * 128) = w;
.Lgate_f_m5:
	global_store_dwordx4 v226, v[42:45], s[8:9] sc0 sc1
	s_add_u32 s8, s8, 0x8000
	s_addc_u32 s9, s9, 0

; __device__ __forceinline__ unsigned pk2(float lo, float hi) { f32x2_t v = {lo, hi}; bf16x2_t b = __builtin_convertvector(v, bf16x2_t); return __builtin_bit_cast(unsigned, b); }
;     __device__ __forceinline__ void operator()(AccRef acc, const pg8::Unit& u, int wr, int wc, int fr, int fq) const {
;     ...
;                     v4u w; w.x = pk2(v[0], v[1]); w.y = pk2(v[2], v[3]); w.z = pk2(v[4], v[5]); w.w = pk2(v[6], v[7]);
;                     if (!last) TMP[ci] = w;
;                     else *(v4u*)(MRG + (size_t)(row0 + ai * 128 + m * 16) * D + col0 + bj * 128) = w;
.Lgate_f_m7:
	global_store_dwordx4 v226, v[10:13], s[8:9] sc0 sc1
	s_add_u32 s8, s8, 0x27f00
	s_addc_u32 s9, s9, 0

; __device__ __forceinline__ unsigned pk2(float lo, float hi) { f32x2_t v = {lo, hi}; bf16x2_t b = __builtin_convertvector(v, bf16x2_t); return __builtin_bit_cast(unsigned, b); }
;     __device__ __forceinline__ void operator()(AccRef acc, const pg8::Unit& u, int wr, int wc, int fr, int fq) const {
;     ...
;                     v4u w; w.x = pk2(v[0], v[1]); w.y = pk2(v[2], v[3]); w.z = pk2(v[4], v[5]); w.w = pk2(v[6], v[7]);
;                     if (!last) TMP[ci] = w;
;                     else *(v4u*)(MRG + (size_t)(row0 + ai * 128 + m * 16) * D + col0 + bj * 128) = w;
.Lgate_f_m9:
	global_store_dwordx4 v226, v[26:29], s[8:9] sc0 sc1
	s_add_u32 s8, s8, 0x8000
	s_addc_u32 s9, s9, 0

; __device__ __forceinline__ unsigned pk2(float lo, float hi) { f32x2_t v = {lo, hi}; bf16x2_t b = __builtin_convertvector(v, bf16x2_t); return __builtin_bit_cast(unsigned, b); }
;     __device__ __forceinline__ void operator()(AccRef acc, const pg8::Unit& u, int wr, int wc, int fr, int fq) const {
;     ...
;                     v4u w; w.x = pk2(v[0], v[1]); w.y = pk2(v[2], v[3]); w.z = pk2(v[4], v[5]); w.w = pk2(v[6], v[7]);
;                     if (!last) TMP[ci] = w;
;                     else *(v4u*)(MRG + (size_t)(row0 + ai * 128 + m * 16) * D + col0 + bj * 128) = w;
.Lgate_f_m11:
	global_store_dwordx4 v226, v[42:45], s[8:9] sc0 sc1
	s_sub_u32 s8, s8, 0x17f00
	s_subb_u32 s9, s9, 0

; __device__ __forceinline__ unsigned pk2(float lo, float hi) { f32x2_t v = {lo, hi}; bf16x2_t b = __builtin_convertvector(v, bf16x2_t); return __builtin_bit_cast(unsigned, b); }
;     __device__ __forceinline__ void operator()(AccRef acc, const pg8::Unit& u, int wr, int wc, int fr, int fq) const {
;     ...
;                     v4u w; w.x = pk2(v[0], v[1]); w.y = pk2(v[2], v[3]); w.z = pk2(v[4], v[5]); w.w = pk2(v[6], v[7]);
;                     if (!last) TMP[ci] = w;
;                     else *(v4u*)(MRG + (size_t)(row0 + ai * 128 + m * 16) * D + col0 + bj * 128) = w;
.Lgate_f_m15:
	global_store_dwordx4 v226, v[26:29], s[8:9] sc0 sc1

; __device__ __forceinline__ unsigned pk2(float lo, float hi) { f32x2_t v = {lo, hi}; bf16x2_t b = __builtin_convertvector(v, bf16x2_t); return __builtin_bit_cast(unsigned, b); }
;     __device__ __forceinline__ void operator()(AccRef acc, const pg8::Unit& u, int wr, int wc, int fr, int fq) const {
;         const int row0 = u.pm * 256 + wr * 64 + fr, col0 = u.pn * 256 + wc * 32 + 8 * fq;
; #pragma unroll
;         for (int ai = 0; ai < 2; ++ai) {
;             v4u xw[4][2];
; #pragma unroll
;             for (int m = 0; m < 4; ++m)
; #pragma unroll
;                 for (int bj = 0; bj < 2; ++bj) xw[m][bj] = *(const v4u*)(xb + (size_t)(row0 + ai * 128 + m * 16) * D + col0 + bj * 128);
; #pragma unroll
;             for (int m = 0; m < 4; ++m) {
;                 const int row = row0 + ai * 128 + m * 16;
;                 float ss = 0.f;
; #pragma unroll
;                 for (int bj = 0; bj < 2; ++bj) {
;                     const size_t p = (size_t)row * D + col0 + bj * 128;
;                     const v4u w0 = xw[m][bj];
;                     f32x4 a = {bflo(w0.x), bfhi(w0.x), bflo(w0.y), bfhi(w0.y)}, b = {bflo(w0.z), bfhi(w0.z), bflo(w0.w), bfhi(w0.w)};
;                     a = a + acc[ai][bj][m][0] * scale; b = b + acc[ai][bj][m][1] * scale;
;                     if (outf) { *(f32x4*)(outf + p) = a; *(f32x4*)(outf + p + 4) = b; }
;                     else {
;                         ss += (a[0] * a[0] + a[1] * a[1]) + (a[2] * a[2] + a[3] * a[3]) + (b[0] * b[0] + b[1] * b[1]) + (b[2] * b[2] + b[3] * b[3]);
;                         v4u w; w.x = pk2(a[0], a[1]); w.y = pk2(a[2], a[3]); w.z = pk2(b[0], b[1]); w.w = pk2(b[2], b[3]);
;                         *(v4u*)(xb + p) = w;
;                     }
;                 }
;                 if (!outf) {
;                     ss += __shfl_xor(ss, 16); ss += __shfl_xor(ss, 32);
;                     if (fq == 0) rss[(size_t)row * 16 + u.pn * 4 + wc] = ss;
;                 }
.LBB0_378:
	s_lshl_b32 s3, s45, 8
	s_add_i32 s3, s3, s71
	v_add_u32_e32 v42, s3, v245
	s_lshl_b32 s3, s40, 8
	s_or_b32 s3, s3, s67
	v_lshl_add_u32 v40, v244, 3, s3
	v_ashrrev_i32_e32 v41, 31, v40
	v_ashrrev_i32_e32 v43, 31, v42
	v_add_u32_e32 v52, 16, v42
	v_lshl_add_u64 v[38:39], v[40:41], 1, s[46:47]
	v_lshlrev_b64 v[2:3], 11, v[42:43]
	v_ashrrev_i32_e32 v53, 31, v52
	v_add_u32_e32 v48, 32, v42
	v_lshl_add_u64 v[56:57], v[38:39], 0, v[2:3]
	v_lshlrev_b64 v[2:3], 11, v[52:53]
	v_ashrrev_i32_e32 v49, 31, v48
	v_add_u32_e32 v44, 48, v42
	v_lshl_add_u64 v[54:55], v[38:39], 0, v[2:3]
	v_lshlrev_b64 v[2:3], 11, v[48:49]
	v_ashrrev_i32_e32 v45, 31, v44
	v_lshl_add_u64 v[50:51], v[38:39], 0, v[2:3]
	v_lshlrev_b64 v[2:3], 11, v[44:45]
	global_load_dwordx4 v[30:33], v[56:57], off
	global_load_dwordx4 v[26:29], v[56:57], off offset:256
	v_lshl_add_u64 v[46:47], v[38:39], 0, v[2:3]
	global_load_dwordx4 v[22:25], v[54:55], off
	global_load_dwordx4 v[18:21], v[54:55], off offset:256
	global_load_dwordx4 v[14:17], v[50:51], off
	global_load_dwordx4 v[10:13], v[50:51], off offset:256
	global_load_dwordx4 v[6:9], v[46:47], off
	global_load_dwordx4 v[2:5], v[46:47], off offset:256
	v_cndmask_b32_e64 v34, 0, 1, s[74:75]
	v_lshlrev_b64 v[60:61], 10, v[42:43]
	v_cmp_ne_u32_e64 s[6:7], 1, v34
	v_lshl_add_u64 v[58:59], v[60:61], 0, v[40:41]
	s_mov_b64 s[8:9], -1
	s_andn2_b64 vcc, exec, s[74:75]
	v_lshl_add_u64 v[58:59], v[58:59], 2, s[54:55]
	s_waitcnt vmcnt(0)
	v_lshlrev_b32_e32 v34, 16, v30
	v_and_b32_e32 v35, 0xffff0000, v30
	v_lshlrev_b32_e32 v30, 16, v31
	v_and_b32_e32 v31, 0xffff0000, v31
	v_lshlrev_b32_e32 v62, 16, v32
	v_and_b32_e32 v63, 0xffff0000, v32
	v_lshlrev_b32_e32 v32, 16, v33
	v_and_b32_e32 v33, 0xffff0000, v33
	v_pk_fma_f32 v[36:37], s[72:73], v[192:193], v[30:31]
	v_pk_fma_f32 v[34:35], s[52:53], v[190:191], v[34:35]
	v_pk_fma_f32 v[32:33], s[72:73], v[188:189], v[32:33]
	v_pk_fma_f32 v[30:31], s[52:53], v[186:187], v[62:63]
	s_cbranch_vccnz .LBB0_380
	s_mov_b64 s[8:9], 0
	global_store_dwordx4 v[58:59], v[34:37], off sc0 sc1
	global_store_dwordx4 v[58:59], v[30:33], off offset:16 sc0 sc1
.LBB0_380:
	s_andn2_b64 vcc, exec, s[8:9]
	v_mov_b32_e32 v62, 0
	s_cbranch_vccnz .LBB0_382
	v_pk_mul_f32 v[62:63], v[36:37], v[36:37]
	v_pk_mul_f32 v[64:65], v[34:35], v[34:35]
	v_cvt_pk_bf16_f32 v34, v34, v35
	v_pk_mov_b32 v[186:187], v[64:65], v[62:63] op_sel:[1,0]
	v_mov_b32_e32 v65, v63
	v_pk_add_f32 v[62:63], v[186:187], v[64:65]
	v_pk_mul_f32 v[64:65], v[32:33], v[32:33]
	v_pk_mul_f32 v[186:187], v[30:31], v[30:31]
	v_mov_b32_e32 v188, v64
	v_mov_b32_e32 v189, v186
	v_mov_b32_e32 v186, v65
	v_pk_add_f32 v[64:65], v[188:189], v[186:187]
	v_add_f32_e32 v62, v62, v63
	v_add_f32_e32 v62, v65, v62
	v_add_f32_e32 v62, v64, v62
	v_cvt_pk_bf16_f32 v35, v36, v37
	v_cvt_pk_bf16_f32 v36, v30, v31
	v_cvt_pk_bf16_f32 v37, v32, v33
	v_lshl_add_u64 v[30:31], v[60:61], 1, v[38:39]
	global_store_dwordx4 v[30:31], v[34:37], off sc0 sc1
.LBB0_382:
	v_lshlrev_b32_e32 v30, 16, v26
	v_and_b32_e32 v31, 0xffff0000, v26
	v_lshlrev_b32_e32 v26, 16, v27
	v_and_b32_e32 v27, 0xffff0000, v27
	v_lshlrev_b32_e32 v34, 16, v28
	v_and_b32_e32 v35, 0xffff0000, v28
	v_lshlrev_b32_e32 v32, 16, v29
	v_and_b32_e32 v33, 0xffff0000, v29
	v_pk_fma_f32 v[28:29], s[72:73], v[184:185], v[26:27]
	v_pk_fma_f32 v[26:27], s[52:53], v[182:183], v[30:31]
	v_pk_fma_f32 v[32:33], s[72:73], v[180:181], v[32:33]
	v_pk_fma_f32 v[30:31], s[52:53], v[178:179], v[34:35]
	s_and_b64 vcc, exec, s[6:7]
	s_mov_b64 s[8:9], -1
	s_cbranch_vccnz .LBB0_384
	s_mov_b64 s[8:9], 0
	global_store_dwordx4 v[58:59], v[26:29], off offset:512 sc0 sc1
	global_store_dwordx4 v[58:59], v[30:33], off offset:528 sc0 sc1
.LBB0_384:
	s_andn2_b64 vcc, exec, s[8:9]
	s_cbranch_vccnz .LBB0_386
	v_pk_mul_f32 v[34:35], v[28:29], v[28:29]
	v_pk_mul_f32 v[36:37], v[26:27], v[26:27]
	v_cvt_pk_bf16_f32 v26, v26, v27
	v_pk_mov_b32 v[58:59], v[36:37], v[34:35] op_sel:[1,0]
	v_mov_b32_e32 v37, v35
	v_pk_add_f32 v[34:35], v[58:59], v[36:37]
	v_pk_mul_f32 v[36:37], v[32:33], v[32:33]
	v_pk_mul_f32 v[58:59], v[30:31], v[30:31]
	v_mov_b32_e32 v60, v36
	v_mov_b32_e32 v61, v58
	v_mov_b32_e32 v58, v37
	v_pk_add_f32 v[36:37], v[60:61], v[58:59]
	v_add_f32_e32 v34, v34, v35
	v_add_f32_e32 v34, v37, v34
	v_add_f32_e32 v34, v36, v34
	v_add_f32_e32 v62, v34, v62
	v_cvt_pk_bf16_f32 v27, v28, v29
	v_cvt_pk_bf16_f32 v28, v30, v31
	v_cvt_pk_bf16_f32 v29, v32, v33
	global_store_dwordx4 v[56:57], v[26:29], off offset:256 sc0 sc1
.LBB0_386:
	s_nop 1
	v_cndmask_b32_e64 v26, 0, 1, s[24:25]
	v_cmp_eq_u32_e64 s[8:9], 0, v244
	v_cmp_ne_u32_e64 s[10:11], 1, v26
	s_andn2_b64 vcc, exec, s[24:25]
	s_cbranch_vccnz .LBB0_390
	v_and_b32_e32 v27, 64, v236
	v_xor_b32_e32 v26, 16, v236
	v_add_u32_e32 v27, 64, v27
	v_cmp_lt_i32_e32 vcc, v26, v27
	v_xor_b32_e32 v28, 32, v236
	s_nop 0
	v_cndmask_b32_e32 v26, v236, v26, vcc
	v_lshlrev_b32_e32 v26, 2, v26
	ds_bpermute_b32 v26, v26, v62
	v_cmp_lt_i32_e32 vcc, v28, v27
	s_waitcnt lgkmcnt(0)
	v_add_f32_e32 v26, v62, v26
	v_cndmask_b32_e32 v27, v236, v28, vcc
	v_lshlrev_b32_e32 v27, 2, v27
	ds_bpermute_b32 v27, v27, v26
	s_and_saveexec_b64 s[12:13], s[8:9]
	s_cbranch_execz .LBB0_389
	s_waitcnt lgkmcnt(0)
	v_add_f32_e32 v28, v26, v27
	s_lshl_b32 s18, s40, 2
	v_lshlrev_b64 v[26:27], 6, v[42:43]
	s_ashr_i32 s19, s18, 31
	v_lshl_add_u64 v[26:27], s[64:65], 0, v[26:27]
	v_lshl_add_u64 v[26:27], s[18:19], 2, v[26:27]
	s_lshl_b32 s38, s63, 2
	v_lshl_add_u64 v[26:27], v[26:27], 0, s[38:39]
	global_store_dword v[26:27], v28, off sc0 sc1

; __device__ __forceinline__ unsigned pk2(float lo, float hi) { f32x2_t v = {lo, hi}; bf16x2_t b = __builtin_convertvector(v, bf16x2_t); return __builtin_bit_cast(unsigned, b); }
;     __device__ __forceinline__ void operator()(AccRef acc, const pg8::Unit& u, int wr, int wc, int fr, int fq) const {
;     ...
;             for (int m = 0; m < 4; ++m) {
;                 const int row = row0 + ai * 128 + m * 16;
;                 float ss = 0.f;
; #pragma unroll
;                 for (int bj = 0; bj < 2; ++bj) {
;                     const size_t p = (size_t)row * D + col0 + bj * 128;
;                     const v4u w0 = xw[m][bj];
;                     f32x4 a = {bflo(w0.x), bfhi(w0.x), bflo(w0.y), bfhi(w0.y)}, b = {bflo(w0.z), bfhi(w0.z), bflo(w0.w), bfhi(w0.w)};
;                     a = a + acc[ai][bj][m][0] * scale; b = b + acc[ai][bj][m][1] * scale;
;                     if (outf) { *(f32x4*)(outf + p) = a; *(f32x4*)(outf + p + 4) = b; }
;                     else {
;                         ss += (a[0] * a[0] + a[1] * a[1]) + (a[2] * a[2] + a[3] * a[3]) + (b[0] * b[0] + b[1] * b[1]) + (b[2] * b[2] + b[3] * b[3]);
;                         v4u w; w.x = pk2(a[0], a[1]); w.y = pk2(a[2], a[3]); w.z = pk2(b[0], b[1]); w.w = pk2(b[2], b[3]);
;                         *(v4u*)(xb + p) = w;
;                     }
;                 }
;                 if (!outf) {
;                     ss += __shfl_xor(ss, 16); ss += __shfl_xor(ss, 32);
;                     if (fq == 0) rss[(size_t)row * 16 + u.pn * 4 + wc] = ss;
;                 }
.LBB0_390:
	v_lshlrev_b64 v[32:33], 10, v[52:53]
	v_lshl_add_u64 v[30:31], v[32:33], 0, v[40:41]
	v_lshlrev_b32_e32 v26, 16, v22
	s_waitcnt lgkmcnt(0)
	v_and_b32_e32 v27, 0xffff0000, v22
	v_lshlrev_b32_e32 v22, 16, v23
	v_and_b32_e32 v23, 0xffff0000, v23
	v_lshlrev_b32_e32 v34, 16, v24
	v_and_b32_e32 v35, 0xffff0000, v24
	v_lshlrev_b32_e32 v28, 16, v25
	v_and_b32_e32 v29, 0xffff0000, v25
	v_pk_fma_f32 v[24:25], s[72:73], v[176:177], v[22:23]
	v_pk_fma_f32 v[22:23], s[52:53], v[174:175], v[26:27]
	v_pk_fma_f32 v[28:29], s[72:73], v[172:173], v[28:29]
	v_pk_fma_f32 v[26:27], s[52:53], v[170:171], v[34:35]
	s_mov_b64 s[12:13], -1
	s_and_b64 vcc, exec, s[6:7]
	v_lshl_add_u64 v[30:31], v[30:31], 2, s[54:55]
	s_cbranch_vccnz .LBB0_392
	s_mov_b64 s[12:13], 0
	global_store_dwordx4 v[30:31], v[22:25], off sc0 sc1
	global_store_dwordx4 v[30:31], v[26:29], off offset:16 sc0 sc1
.LBB0_392:
	s_andn2_b64 vcc, exec, s[12:13]
	v_mov_b32_e32 v34, 0
	s_cbranch_vccnz .LBB0_394
	v_pk_mul_f32 v[34:35], v[24:25], v[24:25]
	v_pk_mul_f32 v[36:37], v[22:23], v[22:23]
	v_cvt_pk_bf16_f32 v22, v22, v23
	v_pk_mov_b32 v[56:57], v[36:37], v[34:35] op_sel:[1,0]
	v_mov_b32_e32 v37, v35
	v_pk_add_f32 v[34:35], v[56:57], v[36:37]
	v_pk_mul_f32 v[36:37], v[28:29], v[28:29]
	v_pk_mul_f32 v[56:57], v[26:27], v[26:27]
	v_mov_b32_e32 v58, v36
	v_mov_b32_e32 v59, v56
	v_mov_b32_e32 v56, v37
	v_pk_add_f32 v[36:37], v[58:59], v[56:57]
	v_add_f32_e32 v34, v34, v35
	v_add_f32_e32 v34, v37, v34
	v_add_f32_e32 v34, v36, v34
	v_cvt_pk_bf16_f32 v23, v24, v25
	v_cvt_pk_bf16_f32 v24, v26, v27
	v_cvt_pk_bf16_f32 v25, v28, v29
	v_lshl_add_u64 v[26:27], v[32:33], 1, v[38:39]
	global_store_dwordx4 v[26:27], v[22:25], off sc0 sc1
.LBB0_394:
	s_nop 1
	v_lshlrev_b32_e32 v22, 16, v18
	v_and_b32_e32 v23, 0xffff0000, v18
	v_lshlrev_b32_e32 v18, 16, v19
	v_and_b32_e32 v19, 0xffff0000, v19
	v_lshlrev_b32_e32 v26, 16, v20
	v_and_b32_e32 v27, 0xffff0000, v20
	v_lshlrev_b32_e32 v24, 16, v21
	v_and_b32_e32 v25, 0xffff0000, v21
	v_pk_fma_f32 v[20:21], s[72:73], v[168:169], v[18:19]
	v_pk_fma_f32 v[18:19], s[52:53], v[166:167], v[22:23]
	v_pk_fma_f32 v[24:25], s[72:73], v[164:165], v[24:25]
	v_pk_fma_f32 v[22:23], s[52:53], v[162:163], v[26:27]
	s_and_b64 vcc, exec, s[6:7]
	s_mov_b64 s[12:13], -1
	s_cbranch_vccnz .LBB0_397
	global_store_dwordx4 v[30:31], v[18:21], off offset:512 sc0 sc1
	global_store_dwordx4 v[30:31], v[22:25], off offset:528 sc0 sc1
	s_cbranch_execz .LBB0_398

; __device__ __forceinline__ unsigned pk2(float lo, float hi) { f32x2_t v = {lo, hi}; bf16x2_t b = __builtin_convertvector(v, bf16x2_t); return __builtin_bit_cast(unsigned, b); }
;     __device__ __forceinline__ void operator()(AccRef acc, const pg8::Unit& u, int wr, int wc, int fr, int fq) const {
;     ...
;             for (int m = 0; m < 4; ++m) {
;                 const int row = row0 + ai * 128 + m * 16;
;                 float ss = 0.f;
; #pragma unroll
;                 for (int bj = 0; bj < 2; ++bj) {
;                     const size_t p = (size_t)row * D + col0 + bj * 128;
;                     const v4u w0 = xw[m][bj];
;                     f32x4 a = {bflo(w0.x), bfhi(w0.x), bflo(w0.y), bfhi(w0.y)}, b = {bflo(w0.z), bfhi(w0.z), bflo(w0.w), bfhi(w0.w)};
;                     a = a + acc[ai][bj][m][0] * scale; b = b + acc[ai][bj][m][1] * scale;
;                     if (outf) { *(f32x4*)(outf + p) = a; *(f32x4*)(outf + p + 4) = b; }
;                     else {
;                         ss += (a[0] * a[0] + a[1] * a[1]) + (a[2] * a[2] + a[3] * a[3]) + (b[0] * b[0] + b[1] * b[1]) + (b[2] * b[2] + b[3] * b[3]);
;                         v4u w; w.x = pk2(a[0], a[1]); w.y = pk2(a[2], a[3]); w.z = pk2(b[0], b[1]); w.w = pk2(b[2], b[3]);
;                         *(v4u*)(xb + p) = w;
;                     }
;                 }
;                 if (!outf) {
;                     ss += __shfl_xor(ss, 16); ss += __shfl_xor(ss, 32);
;                     if (fq == 0) rss[(size_t)row * 16 + u.pn * 4 + wc] = ss;
;                 }
.LBB0_398:
	v_pk_mul_f32 v[26:27], v[20:21], v[20:21]
	v_pk_mul_f32 v[28:29], v[18:19], v[18:19]
	v_cvt_pk_bf16_f32 v18, v18, v19
	v_pk_mov_b32 v[30:31], v[28:29], v[26:27] op_sel:[1,0]
	v_mov_b32_e32 v29, v27
	v_pk_add_f32 v[26:27], v[30:31], v[28:29]
	v_pk_mul_f32 v[28:29], v[24:25], v[24:25]
	v_pk_mul_f32 v[30:31], v[22:23], v[22:23]
	v_mov_b32_e32 v32, v28
	v_mov_b32_e32 v33, v30
	v_mov_b32_e32 v30, v29
	v_pk_add_f32 v[28:29], v[32:33], v[30:31]
	v_add_f32_e32 v26, v26, v27
	v_add_f32_e32 v26, v29, v26
	v_add_f32_e32 v26, v28, v26
	v_add_f32_e32 v34, v26, v34
	v_cvt_pk_bf16_f32 v19, v20, v21
	v_cvt_pk_bf16_f32 v20, v22, v23
	v_cvt_pk_bf16_f32 v21, v24, v25
	global_store_dwordx4 v[54:55], v[18:21], off offset:256 sc0 sc1
	s_and_b64 vcc, exec, s[10:11]
	s_cbranch_vccnz .LBB0_402
.LBB0_399:
	v_and_b32_e32 v19, 64, v236
	v_xor_b32_e32 v18, 16, v236
	v_add_u32_e32 v19, 64, v19
	v_cmp_lt_i32_e32 vcc, v18, v19
	v_xor_b32_e32 v20, 32, v236
	s_nop 0
	v_cndmask_b32_e32 v18, v236, v18, vcc
	v_lshlrev_b32_e32 v18, 2, v18
	ds_bpermute_b32 v18, v18, v34
	v_cmp_lt_i32_e32 vcc, v20, v19
	s_waitcnt lgkmcnt(0)
	v_add_f32_e32 v18, v34, v18
	v_cndmask_b32_e32 v19, v236, v20, vcc
	v_lshlrev_b32_e32 v19, 2, v19
	ds_bpermute_b32 v19, v19, v18
	s_and_saveexec_b64 s[12:13], s[8:9]
	s_cbranch_execz .LBB0_401
	s_waitcnt lgkmcnt(0)
	v_add_f32_e32 v20, v18, v19
	s_lshl_b32 s18, s40, 2
	v_lshlrev_b64 v[18:19], 6, v[52:53]
	s_ashr_i32 s19, s18, 31
	v_lshl_add_u64 v[18:19], s[64:65], 0, v[18:19]
	v_lshl_add_u64 v[18:19], s[18:19], 2, v[18:19]
	s_lshl_b32 s38, s63, 2
	v_lshl_add_u64 v[18:19], v[18:19], 0, s[38:39]
	global_store_dword v[18:19], v20, off sc0 sc1

; __device__ __forceinline__ unsigned pk2(float lo, float hi) { f32x2_t v = {lo, hi}; bf16x2_t b = __builtin_convertvector(v, bf16x2_t); return __builtin_bit_cast(unsigned, b); }
;     __device__ __forceinline__ void operator()(AccRef acc, const pg8::Unit& u, int wr, int wc, int fr, int fq) const {
;     ...
;             for (int m = 0; m < 4; ++m) {
;                 const int row = row0 + ai * 128 + m * 16;
;                 float ss = 0.f;
; #pragma unroll
;                 for (int bj = 0; bj < 2; ++bj) {
;                     const size_t p = (size_t)row * D + col0 + bj * 128;
;                     const v4u w0 = xw[m][bj];
;                     f32x4 a = {bflo(w0.x), bfhi(w0.x), bflo(w0.y), bfhi(w0.y)}, b = {bflo(w0.z), bfhi(w0.z), bflo(w0.w), bfhi(w0.w)};
;                     a = a + acc[ai][bj][m][0] * scale; b = b + acc[ai][bj][m][1] * scale;
;                     if (outf) { *(f32x4*)(outf + p) = a; *(f32x4*)(outf + p + 4) = b; }
;                     else {
;                         ss += (a[0] * a[0] + a[1] * a[1]) + (a[2] * a[2] + a[3] * a[3]) + (b[0] * b[0] + b[1] * b[1]) + (b[2] * b[2] + b[3] * b[3]);
;                         v4u w; w.x = pk2(a[0], a[1]); w.y = pk2(a[2], a[3]); w.z = pk2(b[0], b[1]); w.w = pk2(b[2], b[3]);
;                         *(v4u*)(xb + p) = w;
;                     }
;                 }
;                 if (!outf) {
;                     ss += __shfl_xor(ss, 16); ss += __shfl_xor(ss, 32);
;                     if (fq == 0) rss[(size_t)row * 16 + u.pn * 4 + wc] = ss;
;                 }
.LBB0_402:
	v_lshlrev_b64 v[24:25], 10, v[48:49]
	v_lshl_add_u64 v[22:23], v[24:25], 0, v[40:41]
	v_lshlrev_b32_e32 v18, 16, v14
	s_waitcnt lgkmcnt(0)
	v_and_b32_e32 v19, 0xffff0000, v14
	v_lshlrev_b32_e32 v14, 16, v15
	v_and_b32_e32 v15, 0xffff0000, v15
	v_lshlrev_b32_e32 v26, 16, v16
	v_and_b32_e32 v27, 0xffff0000, v16
	v_lshlrev_b32_e32 v20, 16, v17
	v_and_b32_e32 v21, 0xffff0000, v17
	v_pk_fma_f32 v[16:17], s[72:73], v[160:161], v[14:15]
	v_pk_fma_f32 v[14:15], s[52:53], v[158:159], v[18:19]
	v_pk_fma_f32 v[20:21], s[72:73], v[156:157], v[20:21]
	v_pk_fma_f32 v[18:19], s[52:53], v[154:155], v[26:27]
	s_mov_b64 s[12:13], -1
	s_and_b64 vcc, exec, s[6:7]
	v_lshl_add_u64 v[22:23], v[22:23], 2, s[54:55]
	s_cbranch_vccnz .LBB0_404
	s_mov_b64 s[12:13], 0
	global_store_dwordx4 v[22:23], v[14:17], off sc0 sc1
	global_store_dwordx4 v[22:23], v[18:21], off offset:16 sc0 sc1
.LBB0_404:
	s_andn2_b64 vcc, exec, s[12:13]
	v_mov_b32_e32 v26, 0
	s_cbranch_vccnz .LBB0_406
	v_pk_mul_f32 v[26:27], v[16:17], v[16:17]
	v_pk_mul_f32 v[28:29], v[14:15], v[14:15]
	v_cvt_pk_bf16_f32 v14, v14, v15
	v_pk_mov_b32 v[30:31], v[28:29], v[26:27] op_sel:[1,0]
	v_mov_b32_e32 v29, v27
	v_pk_add_f32 v[26:27], v[30:31], v[28:29]
	v_pk_mul_f32 v[28:29], v[20:21], v[20:21]
	v_pk_mul_f32 v[30:31], v[18:19], v[18:19]
	v_mov_b32_e32 v32, v28
	v_mov_b32_e32 v33, v30
	v_mov_b32_e32 v30, v29
	v_pk_add_f32 v[28:29], v[32:33], v[30:31]
	v_add_f32_e32 v26, v26, v27
	v_add_f32_e32 v26, v29, v26
	v_add_f32_e32 v26, v28, v26
	v_cvt_pk_bf16_f32 v15, v16, v17
	v_cvt_pk_bf16_f32 v16, v18, v19
	v_cvt_pk_bf16_f32 v17, v20, v21
	v_lshl_add_u64 v[18:19], v[24:25], 1, v[38:39]
	global_store_dwordx4 v[18:19], v[14:17], off sc0 sc1
.LBB0_406:
	s_nop 1
	v_lshlrev_b32_e32 v14, 16, v10
	v_and_b32_e32 v15, 0xffff0000, v10
	v_lshlrev_b32_e32 v10, 16, v11
	v_and_b32_e32 v11, 0xffff0000, v11
	v_lshlrev_b32_e32 v18, 16, v12
	v_and_b32_e32 v19, 0xffff0000, v12
	v_lshlrev_b32_e32 v16, 16, v13
	v_and_b32_e32 v17, 0xffff0000, v13
	v_pk_fma_f32 v[12:13], s[72:73], v[152:153], v[10:11]
	v_pk_fma_f32 v[10:11], s[52:53], v[150:151], v[14:15]
	v_pk_fma_f32 v[16:17], s[72:73], v[148:149], v[16:17]
	v_pk_fma_f32 v[14:15], s[52:53], v[146:147], v[18:19]
	s_and_b64 vcc, exec, s[6:7]
	s_mov_b64 s[12:13], -1
	s_cbranch_vccnz .LBB0_409
	global_store_dwordx4 v[22:23], v[10:13], off offset:512 sc0 sc1
	global_store_dwordx4 v[22:23], v[14:17], off offset:528 sc0 sc1
	s_cbranch_execz .LBB0_410

; __device__ __forceinline__ unsigned pk2(float lo, float hi) { f32x2_t v = {lo, hi}; bf16x2_t b = __builtin_convertvector(v, bf16x2_t); return __builtin_bit_cast(unsigned, b); }
;     __device__ __forceinline__ void operator()(AccRef acc, const pg8::Unit& u, int wr, int wc, int fr, int fq) const {
;     ...
;             for (int m = 0; m < 4; ++m) {
;                 const int row = row0 + ai * 128 + m * 16;
;                 float ss = 0.f;
; #pragma unroll
;                 for (int bj = 0; bj < 2; ++bj) {
;                     const size_t p = (size_t)row * D + col0 + bj * 128;
;                     const v4u w0 = xw[m][bj];
;                     f32x4 a = {bflo(w0.x), bfhi(w0.x), bflo(w0.y), bfhi(w0.y)}, b = {bflo(w0.z), bfhi(w0.z), bflo(w0.w), bfhi(w0.w)};
;                     a = a + acc[ai][bj][m][0] * scale; b = b + acc[ai][bj][m][1] * scale;
;                     if (outf) { *(f32x4*)(outf + p) = a; *(f32x4*)(outf + p + 4) = b; }
;                     else {
;                         ss += (a[0] * a[0] + a[1] * a[1]) + (a[2] * a[2] + a[3] * a[3]) + (b[0] * b[0] + b[1] * b[1]) + (b[2] * b[2] + b[3] * b[3]);
;                         v4u w; w.x = pk2(a[0], a[1]); w.y = pk2(a[2], a[3]); w.z = pk2(b[0], b[1]); w.w = pk2(b[2], b[3]);
;                         *(v4u*)(xb + p) = w;
;                     }
;                 }
;                 if (!outf) {
;                     ss += __shfl_xor(ss, 16); ss += __shfl_xor(ss, 32);
;                     if (fq == 0) rss[(size_t)row * 16 + u.pn * 4 + wc] = ss;
;                 }
.LBB0_410:
	v_pk_mul_f32 v[18:19], v[12:13], v[12:13]
	v_pk_mul_f32 v[20:21], v[10:11], v[10:11]
	v_cvt_pk_bf16_f32 v10, v10, v11
	v_pk_mov_b32 v[22:23], v[20:21], v[18:19] op_sel:[1,0]
	v_mov_b32_e32 v21, v19
	v_pk_add_f32 v[18:19], v[22:23], v[20:21]
	v_pk_mul_f32 v[20:21], v[16:17], v[16:17]
	v_pk_mul_f32 v[22:23], v[14:15], v[14:15]
	v_mov_b32_e32 v24, v20
	v_mov_b32_e32 v25, v22
	v_mov_b32_e32 v22, v21
	v_pk_add_f32 v[20:21], v[24:25], v[22:23]
	v_add_f32_e32 v18, v18, v19
	v_add_f32_e32 v18, v21, v18
	v_add_f32_e32 v18, v20, v18
	v_add_f32_e32 v26, v18, v26
	v_cvt_pk_bf16_f32 v11, v12, v13
	v_cvt_pk_bf16_f32 v12, v14, v15
	v_cvt_pk_bf16_f32 v13, v16, v17
	global_store_dwordx4 v[50:51], v[10:13], off offset:256 sc0 sc1
	s_and_b64 vcc, exec, s[10:11]
	s_cbranch_vccnz .LBB0_414
.LBB0_411:
	v_and_b32_e32 v11, 64, v236
	v_xor_b32_e32 v10, 16, v236
	v_add_u32_e32 v11, 64, v11
	v_cmp_lt_i32_e32 vcc, v10, v11
	v_xor_b32_e32 v12, 32, v236
	s_nop 0
	v_cndmask_b32_e32 v10, v236, v10, vcc
	v_lshlrev_b32_e32 v10, 2, v10
	ds_bpermute_b32 v10, v10, v26
	v_cmp_lt_i32_e32 vcc, v12, v11
	s_waitcnt lgkmcnt(0)
	v_add_f32_e32 v10, v26, v10
	v_cndmask_b32_e32 v11, v236, v12, vcc
	v_lshlrev_b32_e32 v11, 2, v11
	ds_bpermute_b32 v11, v11, v10
	s_and_saveexec_b64 s[12:13], s[8:9]
	s_cbranch_execz .LBB0_413
	s_waitcnt lgkmcnt(0)
	v_add_f32_e32 v12, v10, v11
	s_lshl_b32 s18, s40, 2
	v_lshlrev_b64 v[10:11], 6, v[48:49]
	s_ashr_i32 s19, s18, 31
	v_lshl_add_u64 v[10:11], s[64:65], 0, v[10:11]
	v_lshl_add_u64 v[10:11], s[18:19], 2, v[10:11]
	s_lshl_b32 s38, s63, 2
	v_lshl_add_u64 v[10:11], v[10:11], 0, s[38:39]
	global_store_dword v[10:11], v12, off sc0 sc1

; __device__ __forceinline__ unsigned pk2(float lo, float hi) { f32x2_t v = {lo, hi}; bf16x2_t b = __builtin_convertvector(v, bf16x2_t); return __builtin_bit_cast(unsigned, b); }
;     __device__ __forceinline__ void operator()(AccRef acc, const pg8::Unit& u, int wr, int wc, int fr, int fq) const {
;     ...
;             for (int m = 0; m < 4; ++m) {
;                 const int row = row0 + ai * 128 + m * 16;
;                 float ss = 0.f;
; #pragma unroll
;                 for (int bj = 0; bj < 2; ++bj) {
;                     const size_t p = (size_t)row * D + col0 + bj * 128;
;                     const v4u w0 = xw[m][bj];
;                     f32x4 a = {bflo(w0.x), bfhi(w0.x), bflo(w0.y), bfhi(w0.y)}, b = {bflo(w0.z), bfhi(w0.z), bflo(w0.w), bfhi(w0.w)};
;                     a = a + acc[ai][bj][m][0] * scale; b = b + acc[ai][bj][m][1] * scale;
;                     if (outf) { *(f32x4*)(outf + p) = a; *(f32x4*)(outf + p + 4) = b; }
;                     else {
;                         ss += (a[0] * a[0] + a[1] * a[1]) + (a[2] * a[2] + a[3] * a[3]) + (b[0] * b[0] + b[1] * b[1]) + (b[2] * b[2] + b[3] * b[3]);
;                         v4u w; w.x = pk2(a[0], a[1]); w.y = pk2(a[2], a[3]); w.z = pk2(b[0], b[1]); w.w = pk2(b[2], b[3]);
;                         *(v4u*)(xb + p) = w;
;                     }
;                 }
;                 if (!outf) {
;                     ss += __shfl_xor(ss, 16); ss += __shfl_xor(ss, 32);
;                     if (fq == 0) rss[(size_t)row * 16 + u.pn * 4 + wc] = ss;
;                 }
.LBB0_414:
	v_lshlrev_b64 v[16:17], 10, v[44:45]
	v_lshl_add_u64 v[14:15], v[16:17], 0, v[40:41]
	v_lshlrev_b32_e32 v10, 16, v6
	s_waitcnt lgkmcnt(0)
	v_and_b32_e32 v11, 0xffff0000, v6
	v_lshlrev_b32_e32 v6, 16, v7
	v_and_b32_e32 v7, 0xffff0000, v7
	v_lshlrev_b32_e32 v18, 16, v8
	v_and_b32_e32 v19, 0xffff0000, v8
	v_lshlrev_b32_e32 v12, 16, v9
	v_and_b32_e32 v13, 0xffff0000, v9
	v_pk_fma_f32 v[8:9], s[72:73], v[144:145], v[6:7]
	v_pk_fma_f32 v[6:7], s[52:53], v[142:143], v[10:11]
	v_pk_fma_f32 v[12:13], s[72:73], v[140:141], v[12:13]
	v_pk_fma_f32 v[10:11], s[52:53], v[138:139], v[18:19]
	s_mov_b64 s[12:13], -1
	s_and_b64 vcc, exec, s[6:7]
	v_lshl_add_u64 v[14:15], v[14:15], 2, s[54:55]
	s_cbranch_vccnz .LBB0_416
	s_mov_b64 s[12:13], 0
	global_store_dwordx4 v[14:15], v[6:9], off sc0 sc1
	global_store_dwordx4 v[14:15], v[10:13], off offset:16 sc0 sc1
.LBB0_416:
	s_andn2_b64 vcc, exec, s[12:13]
	v_mov_b32_e32 v18, 0
	s_cbranch_vccnz .LBB0_418
	v_pk_mul_f32 v[18:19], v[8:9], v[8:9]
	v_pk_mul_f32 v[20:21], v[6:7], v[6:7]
	v_cvt_pk_bf16_f32 v6, v6, v7
	v_pk_mov_b32 v[22:23], v[20:21], v[18:19] op_sel:[1,0]
	v_mov_b32_e32 v21, v19
	v_pk_add_f32 v[18:19], v[22:23], v[20:21]
	v_pk_mul_f32 v[20:21], v[12:13], v[12:13]
	v_pk_mul_f32 v[22:23], v[10:11], v[10:11]
	v_mov_b32_e32 v24, v20
	v_mov_b32_e32 v25, v22
	v_mov_b32_e32 v22, v21
	v_pk_add_f32 v[20:21], v[24:25], v[22:23]
	v_add_f32_e32 v18, v18, v19
	v_add_f32_e32 v18, v21, v18
	v_add_f32_e32 v18, v20, v18
	v_cvt_pk_bf16_f32 v7, v8, v9
	v_cvt_pk_bf16_f32 v8, v10, v11
	v_cvt_pk_bf16_f32 v9, v12, v13
	v_lshl_add_u64 v[10:11], v[16:17], 1, v[38:39]
	global_store_dwordx4 v[10:11], v[6:9], off sc0 sc1
.LBB0_418:
	s_nop 1
	v_lshlrev_b32_e32 v6, 16, v2
	v_and_b32_e32 v7, 0xffff0000, v2
	v_lshlrev_b32_e32 v2, 16, v3
	v_and_b32_e32 v3, 0xffff0000, v3
	v_lshlrev_b32_e32 v10, 16, v4
	v_and_b32_e32 v11, 0xffff0000, v4
	v_lshlrev_b32_e32 v8, 16, v5
	v_and_b32_e32 v9, 0xffff0000, v5
	v_pk_fma_f32 v[4:5], s[72:73], v[136:137], v[2:3]
	v_pk_fma_f32 v[2:3], s[52:53], v[134:135], v[6:7]
	v_pk_fma_f32 v[8:9], s[72:73], v[132:133], v[8:9]
	v_pk_fma_f32 v[6:7], s[52:53], v[130:131], v[10:11]
	s_and_b64 vcc, exec, s[6:7]
	s_mov_b64 s[12:13], -1
	s_cbranch_vccnz .LBB0_421
	global_store_dwordx4 v[14:15], v[2:5], off offset:512 sc0 sc1
	global_store_dwordx4 v[14:15], v[6:9], off offset:528 sc0 sc1
	s_cbranch_execz .LBB0_422

; __device__ __forceinline__ unsigned pk2(float lo, float hi) { f32x2_t v = {lo, hi}; bf16x2_t b = __builtin_convertvector(v, bf16x2_t); return __builtin_bit_cast(unsigned, b); }
;     __device__ __forceinline__ void operator()(AccRef acc, const pg8::Unit& u, int wr, int wc, int fr, int fq) const {
;     ...
;             for (int m = 0; m < 4; ++m) {
;                 const int row = row0 + ai * 128 + m * 16;
;                 float ss = 0.f;
; #pragma unroll
;                 for (int bj = 0; bj < 2; ++bj) {
;                     const size_t p = (size_t)row * D + col0 + bj * 128;
;                     const v4u w0 = xw[m][bj];
;                     f32x4 a = {bflo(w0.x), bfhi(w0.x), bflo(w0.y), bfhi(w0.y)}, b = {bflo(w0.z), bfhi(w0.z), bflo(w0.w), bfhi(w0.w)};
;                     a = a + acc[ai][bj][m][0] * scale; b = b + acc[ai][bj][m][1] * scale;
;                     if (outf) { *(f32x4*)(outf + p) = a; *(f32x4*)(outf + p + 4) = b; }
;                     else {
;                         ss += (a[0] * a[0] + a[1] * a[1]) + (a[2] * a[2] + a[3] * a[3]) + (b[0] * b[0] + b[1] * b[1]) + (b[2] * b[2] + b[3] * b[3]);
;                         v4u w; w.x = pk2(a[0], a[1]); w.y = pk2(a[2], a[3]); w.z = pk2(b[0], b[1]); w.w = pk2(b[2], b[3]);
;                         *(v4u*)(xb + p) = w;
;                     }
;                 }
;                 if (!outf) {
;                     ss += __shfl_xor(ss, 16); ss += __shfl_xor(ss, 32);
;                     if (fq == 0) rss[(size_t)row * 16 + u.pn * 4 + wc] = ss;
;                 }
.LBB0_422:
	v_pk_mul_f32 v[10:11], v[4:5], v[4:5]
	v_pk_mul_f32 v[12:13], v[2:3], v[2:3]
	v_cvt_pk_bf16_f32 v2, v2, v3
	v_pk_mov_b32 v[14:15], v[12:13], v[10:11] op_sel:[1,0]
	v_mov_b32_e32 v13, v11
	v_pk_add_f32 v[10:11], v[14:15], v[12:13]
	v_pk_mul_f32 v[12:13], v[8:9], v[8:9]
	v_pk_mul_f32 v[14:15], v[6:7], v[6:7]
	v_mov_b32_e32 v16, v12
	v_mov_b32_e32 v17, v14
	v_mov_b32_e32 v14, v13
	v_pk_add_f32 v[12:13], v[16:17], v[14:15]
	v_add_f32_e32 v10, v10, v11
	v_add_f32_e32 v10, v13, v10
	v_add_f32_e32 v10, v12, v10
	v_add_f32_e32 v18, v10, v18
	v_cvt_pk_bf16_f32 v3, v4, v5
	v_cvt_pk_bf16_f32 v4, v6, v7
	v_cvt_pk_bf16_f32 v5, v8, v9
	global_store_dwordx4 v[46:47], v[2:5], off offset:256 sc0 sc1
	s_and_b64 vcc, exec, s[10:11]
	s_cbranch_vccnz .LBB0_426
.LBB0_423:
	v_and_b32_e32 v3, 64, v236
	v_xor_b32_e32 v2, 16, v236
	v_add_u32_e32 v3, 64, v3
	v_cmp_lt_i32_e32 vcc, v2, v3
	v_xor_b32_e32 v4, 32, v236
	s_nop 0
	v_cndmask_b32_e32 v2, v236, v2, vcc
	v_lshlrev_b32_e32 v2, 2, v2
	ds_bpermute_b32 v2, v2, v18
	v_cmp_lt_i32_e32 vcc, v4, v3
	s_waitcnt lgkmcnt(0)
	v_add_f32_e32 v2, v18, v2
	v_cndmask_b32_e32 v3, v236, v4, vcc
	v_lshlrev_b32_e32 v3, 2, v3
	ds_bpermute_b32 v3, v3, v2
	s_and_saveexec_b64 s[12:13], s[8:9]
	s_cbranch_execz .LBB0_425
	s_waitcnt lgkmcnt(0)
	v_add_f32_e32 v4, v2, v3
	s_lshl_b32 s18, s40, 2
	v_lshlrev_b64 v[2:3], 6, v[44:45]
	s_ashr_i32 s19, s18, 31
	v_lshl_add_u64 v[2:3], s[64:65], 0, v[2:3]
	v_lshl_add_u64 v[2:3], s[18:19], 2, v[2:3]
	s_lshl_b32 s38, s63, 2
	v_lshl_add_u64 v[2:3], v[2:3], 0, s[38:39]
	global_store_dword v[2:3], v4, off sc0 sc1

; __device__ __forceinline__ unsigned pk2(float lo, float hi) { f32x2_t v = {lo, hi}; bf16x2_t b = __builtin_convertvector(v, bf16x2_t); return __builtin_bit_cast(unsigned, b); }
;     __device__ __forceinline__ void operator()(AccRef acc, const pg8::Unit& u, int wr, int wc, int fr, int fq) const {
;     ...
;             for (int m = 0; m < 4; ++m) {
;                 const int row = row0 + ai * 128 + m * 16;
;                 float ss = 0.f;
; #pragma unroll
;                 for (int bj = 0; bj < 2; ++bj) {
;                     const size_t p = (size_t)row * D + col0 + bj * 128;
;                     const v4u w0 = xw[m][bj];
;                     f32x4 a = {bflo(w0.x), bfhi(w0.x), bflo(w0.y), bfhi(w0.y)}, b = {bflo(w0.z), bfhi(w0.z), bflo(w0.w), bfhi(w0.w)};
;                     a = a + acc[ai][bj][m][0] * scale; b = b + acc[ai][bj][m][1] * scale;
;                     if (outf) { *(f32x4*)(outf + p) = a; *(f32x4*)(outf + p + 4) = b; }
;                     else {
;                         ss += (a[0] * a[0] + a[1] * a[1]) + (a[2] * a[2] + a[3] * a[3]) + (b[0] * b[0] + b[1] * b[1]) + (b[2] * b[2] + b[3] * b[3]);
;                         v4u w; w.x = pk2(a[0], a[1]); w.y = pk2(a[2], a[3]); w.z = pk2(b[0], b[1]); w.w = pk2(b[2], b[3]);
;                         *(v4u*)(xb + p) = w;
;                     }
;                 }
;                 if (!outf) {
;                     ss += __shfl_xor(ss, 16); ss += __shfl_xor(ss, 32);
;                     if (fq == 0) rss[(size_t)row * 16 + u.pn * 4 + wc] = ss;
;                 }
.LBB0_426:
	v_add_u32_e32 v54, 0x80, v42
	v_ashrrev_i32_e32 v55, 31, v54
	v_add_u32_e32 v50, 0x90, v42
	s_waitcnt lgkmcnt(0)
	v_lshlrev_b64 v[2:3], 11, v[54:55]
	v_ashrrev_i32_e32 v51, 31, v50
	v_add_u32_e32 v46, 0xa0, v42
	v_lshl_add_u64 v[56:57], v[38:39], 0, v[2:3]
	v_lshlrev_b64 v[2:3], 11, v[50:51]
	v_ashrrev_i32_e32 v47, 31, v46
	v_add_u32_e32 v42, 0xb0, v42
	v_lshl_add_u64 v[52:53], v[38:39], 0, v[2:3]
	v_lshlrev_b64 v[2:3], 11, v[46:47]
	v_ashrrev_i32_e32 v43, 31, v42
	v_lshl_add_u64 v[48:49], v[38:39], 0, v[2:3]
	v_lshlrev_b64 v[2:3], 11, v[42:43]
	global_load_dwordx4 v[30:33], v[56:57], off
	global_load_dwordx4 v[26:29], v[56:57], off offset:256
	v_lshl_add_u64 v[44:45], v[38:39], 0, v[2:3]
	global_load_dwordx4 v[22:25], v[52:53], off
	global_load_dwordx4 v[18:21], v[52:53], off offset:256
	global_load_dwordx4 v[14:17], v[48:49], off
	global_load_dwordx4 v[10:13], v[48:49], off offset:256
	global_load_dwordx4 v[6:9], v[44:45], off
	global_load_dwordx4 v[2:5], v[44:45], off offset:256
	v_lshlrev_b64 v[60:61], 10, v[54:55]
	v_lshl_add_u64 v[58:59], v[60:61], 0, v[40:41]
	s_mov_b64 s[12:13], -1
	s_and_b64 vcc, exec, s[6:7]
	v_lshl_add_u64 v[58:59], v[58:59], 2, s[54:55]
	s_waitcnt vmcnt(7)
	v_lshlrev_b32_e32 v34, 16, v30
	v_and_b32_e32 v35, 0xffff0000, v30
	v_lshlrev_b32_e32 v30, 16, v31
	v_and_b32_e32 v31, 0xffff0000, v31
	v_lshlrev_b32_e32 v62, 16, v32
	v_and_b32_e32 v63, 0xffff0000, v32
	v_lshlrev_b32_e32 v32, 16, v33
	v_and_b32_e32 v33, 0xffff0000, v33
	v_pk_fma_f32 v[36:37], s[72:73], v[128:129], v[30:31]
	v_pk_fma_f32 v[34:35], s[52:53], v[126:127], v[34:35]
	v_pk_fma_f32 v[32:33], s[72:73], v[124:125], v[32:33]
	v_pk_fma_f32 v[30:31], s[52:53], v[122:123], v[62:63]
	s_cbranch_vccnz .LBB0_428
	s_mov_b64 s[12:13], 0
	global_store_dwordx4 v[58:59], v[34:37], off sc0 sc1
	global_store_dwordx4 v[58:59], v[30:33], off offset:16 sc0 sc1
.LBB0_428:
	s_andn2_b64 vcc, exec, s[12:13]
	v_mov_b32_e32 v62, 0
	s_cbranch_vccnz .LBB0_430
	v_pk_mul_f32 v[62:63], v[36:37], v[36:37]
	v_pk_mul_f32 v[64:65], v[34:35], v[34:35]
	v_cvt_pk_bf16_f32 v34, v34, v35
	v_pk_mov_b32 v[122:123], v[64:65], v[62:63] op_sel:[1,0]
	v_mov_b32_e32 v65, v63
	v_pk_add_f32 v[62:63], v[122:123], v[64:65]
	v_pk_mul_f32 v[64:65], v[32:33], v[32:33]
	v_pk_mul_f32 v[122:123], v[30:31], v[30:31]
	v_mov_b32_e32 v124, v64
	v_mov_b32_e32 v125, v122
	v_mov_b32_e32 v122, v65
	v_pk_add_f32 v[64:65], v[124:125], v[122:123]
	v_add_f32_e32 v62, v62, v63
	v_add_f32_e32 v62, v65, v62
	v_add_f32_e32 v62, v64, v62
	v_cvt_pk_bf16_f32 v35, v36, v37
	v_cvt_pk_bf16_f32 v36, v30, v31
	v_cvt_pk_bf16_f32 v37, v32, v33
	v_lshl_add_u64 v[30:31], v[60:61], 1, v[38:39]
	global_store_dwordx4 v[30:31], v[34:37], off sc0 sc1
.LBB0_430:
	s_waitcnt vmcnt(6)
	v_lshlrev_b32_e32 v30, 16, v26
	v_and_b32_e32 v31, 0xffff0000, v26
	v_lshlrev_b32_e32 v26, 16, v27
	v_and_b32_e32 v27, 0xffff0000, v27
	v_lshlrev_b32_e32 v34, 16, v28
	v_and_b32_e32 v35, 0xffff0000, v28
	v_lshlrev_b32_e32 v32, 16, v29
	v_and_b32_e32 v33, 0xffff0000, v29
	v_pk_fma_f32 v[28:29], s[72:73], v[120:121], v[26:27]
	v_pk_fma_f32 v[26:27], s[52:53], v[118:119], v[30:31]
	v_pk_fma_f32 v[32:33], s[72:73], v[116:117], v[32:33]
	v_pk_fma_f32 v[30:31], s[52:53], v[114:115], v[34:35]
	s_and_b64 vcc, exec, s[6:7]
	s_mov_b64 s[12:13], -1
	s_cbranch_vccnz .LBB0_433
	global_store_dwordx4 v[58:59], v[26:29], off offset:512 sc0 sc1
	global_store_dwordx4 v[58:59], v[30:33], off offset:528 sc0 sc1
	s_cbranch_execz .LBB0_434

; __device__ __forceinline__ unsigned pk2(float lo, float hi) { f32x2_t v = {lo, hi}; bf16x2_t b = __builtin_convertvector(v, bf16x2_t); return __builtin_bit_cast(unsigned, b); }
;     __device__ __forceinline__ void operator()(AccRef acc, const pg8::Unit& u, int wr, int wc, int fr, int fq) const {
;     ...
;             for (int m = 0; m < 4; ++m) {
;                 const int row = row0 + ai * 128 + m * 16;
;                 float ss = 0.f;
; #pragma unroll
;                 for (int bj = 0; bj < 2; ++bj) {
;                     const size_t p = (size_t)row * D + col0 + bj * 128;
;                     const v4u w0 = xw[m][bj];
;                     f32x4 a = {bflo(w0.x), bfhi(w0.x), bflo(w0.y), bfhi(w0.y)}, b = {bflo(w0.z), bfhi(w0.z), bflo(w0.w), bfhi(w0.w)};
;                     a = a + acc[ai][bj][m][0] * scale; b = b + acc[ai][bj][m][1] * scale;
;                     if (outf) { *(f32x4*)(outf + p) = a; *(f32x4*)(outf + p + 4) = b; }
;                     else {
;                         ss += (a[0] * a[0] + a[1] * a[1]) + (a[2] * a[2] + a[3] * a[3]) + (b[0] * b[0] + b[1] * b[1]) + (b[2] * b[2] + b[3] * b[3]);
;                         v4u w; w.x = pk2(a[0], a[1]); w.y = pk2(a[2], a[3]); w.z = pk2(b[0], b[1]); w.w = pk2(b[2], b[3]);
;                         *(v4u*)(xb + p) = w;
;                     }
;                 }
;                 if (!outf) {
;                     ss += __shfl_xor(ss, 16); ss += __shfl_xor(ss, 32);
;                     if (fq == 0) rss[(size_t)row * 16 + u.pn * 4 + wc] = ss;
;                 }
.LBB0_434:
	v_pk_mul_f32 v[34:35], v[28:29], v[28:29]
	v_pk_mul_f32 v[36:37], v[26:27], v[26:27]
	v_cvt_pk_bf16_f32 v26, v26, v27
	v_pk_mov_b32 v[58:59], v[36:37], v[34:35] op_sel:[1,0]
	v_mov_b32_e32 v37, v35
	v_pk_add_f32 v[34:35], v[58:59], v[36:37]
	v_pk_mul_f32 v[36:37], v[32:33], v[32:33]
	v_pk_mul_f32 v[58:59], v[30:31], v[30:31]
	v_mov_b32_e32 v60, v36
	v_mov_b32_e32 v61, v58
	v_mov_b32_e32 v58, v37
	v_pk_add_f32 v[36:37], v[60:61], v[58:59]
	v_add_f32_e32 v34, v34, v35
	v_add_f32_e32 v34, v37, v34
	v_add_f32_e32 v34, v36, v34
	v_add_f32_e32 v62, v34, v62
	v_cvt_pk_bf16_f32 v27, v28, v29
	v_cvt_pk_bf16_f32 v28, v30, v31
	v_cvt_pk_bf16_f32 v29, v32, v33
	global_store_dwordx4 v[56:57], v[26:29], off offset:256 sc0 sc1
	s_and_b64 vcc, exec, s[10:11]
	s_cbranch_vccnz .LBB0_438
.LBB0_435:
	v_and_b32_e32 v27, 64, v236
	v_xor_b32_e32 v26, 16, v236
	v_add_u32_e32 v27, 64, v27
	v_cmp_lt_i32_e32 vcc, v26, v27
	v_xor_b32_e32 v28, 32, v236
	s_nop 0
	v_cndmask_b32_e32 v26, v236, v26, vcc
	v_lshlrev_b32_e32 v26, 2, v26
	ds_bpermute_b32 v26, v26, v62
	v_cmp_lt_i32_e32 vcc, v28, v27
	s_waitcnt lgkmcnt(0)
	v_add_f32_e32 v26, v62, v26
	v_cndmask_b32_e32 v27, v236, v28, vcc
	v_lshlrev_b32_e32 v27, 2, v27
	ds_bpermute_b32 v27, v27, v26
	s_and_saveexec_b64 s[12:13], s[8:9]
	s_cbranch_execz .LBB0_437
	s_waitcnt lgkmcnt(0)
	v_add_f32_e32 v28, v26, v27
	s_lshl_b32 s18, s40, 2
	v_lshlrev_b64 v[26:27], 6, v[54:55]
	s_ashr_i32 s19, s18, 31
	v_lshl_add_u64 v[26:27], s[64:65], 0, v[26:27]
	v_lshl_add_u64 v[26:27], s[18:19], 2, v[26:27]
	s_lshl_b32 s38, s63, 2
	v_lshl_add_u64 v[26:27], v[26:27], 0, s[38:39]
	global_store_dword v[26:27], v28, off sc0 sc1

; __device__ __forceinline__ unsigned pk2(float lo, float hi) { f32x2_t v = {lo, hi}; bf16x2_t b = __builtin_convertvector(v, bf16x2_t); return __builtin_bit_cast(unsigned, b); }
;     __device__ __forceinline__ void operator()(AccRef acc, const pg8::Unit& u, int wr, int wc, int fr, int fq) const {
;     ...
;             for (int m = 0; m < 4; ++m) {
;                 const int row = row0 + ai * 128 + m * 16;
;                 float ss = 0.f;
; #pragma unroll
;                 for (int bj = 0; bj < 2; ++bj) {
;                     const size_t p = (size_t)row * D + col0 + bj * 128;
;                     const v4u w0 = xw[m][bj];
;                     f32x4 a = {bflo(w0.x), bfhi(w0.x), bflo(w0.y), bfhi(w0.y)}, b = {bflo(w0.z), bfhi(w0.z), bflo(w0.w), bfhi(w0.w)};
;                     a = a + acc[ai][bj][m][0] * scale; b = b + acc[ai][bj][m][1] * scale;
;                     if (outf) { *(f32x4*)(outf + p) = a; *(f32x4*)(outf + p + 4) = b; }
;                     else {
;                         ss += (a[0] * a[0] + a[1] * a[1]) + (a[2] * a[2] + a[3] * a[3]) + (b[0] * b[0] + b[1] * b[1]) + (b[2] * b[2] + b[3] * b[3]);
;                         v4u w; w.x = pk2(a[0], a[1]); w.y = pk2(a[2], a[3]); w.z = pk2(b[0], b[1]); w.w = pk2(b[2], b[3]);
;                         *(v4u*)(xb + p) = w;
;                     }
;                 }
;                 if (!outf) {
;                     ss += __shfl_xor(ss, 16); ss += __shfl_xor(ss, 32);
;                     if (fq == 0) rss[(size_t)row * 16 + u.pn * 4 + wc] = ss;
;                 }
.LBB0_438:
	v_lshlrev_b64 v[32:33], 10, v[50:51]
	v_lshl_add_u64 v[30:31], v[32:33], 0, v[40:41]
	s_waitcnt vmcnt(5)
	v_lshlrev_b32_e32 v26, 16, v22
	s_waitcnt lgkmcnt(0)
	v_and_b32_e32 v27, 0xffff0000, v22
	v_lshlrev_b32_e32 v22, 16, v23
	v_and_b32_e32 v23, 0xffff0000, v23
	v_lshlrev_b32_e32 v34, 16, v24
	v_and_b32_e32 v35, 0xffff0000, v24
	v_lshlrev_b32_e32 v28, 16, v25
	v_and_b32_e32 v29, 0xffff0000, v25
	v_pk_fma_f32 v[24:25], s[72:73], v[112:113], v[22:23]
	v_pk_fma_f32 v[22:23], s[52:53], v[110:111], v[26:27]
	v_pk_fma_f32 v[28:29], s[72:73], v[108:109], v[28:29]
	v_pk_fma_f32 v[26:27], s[52:53], v[106:107], v[34:35]
	s_mov_b64 s[12:13], -1
	s_and_b64 vcc, exec, s[6:7]
	v_lshl_add_u64 v[30:31], v[30:31], 2, s[54:55]
	s_cbranch_vccnz .LBB0_440
	s_mov_b64 s[12:13], 0
	global_store_dwordx4 v[30:31], v[22:25], off sc0 sc1
	global_store_dwordx4 v[30:31], v[26:29], off offset:16 sc0 sc1
.LBB0_440:
	s_andn2_b64 vcc, exec, s[12:13]
	v_mov_b32_e32 v34, 0
	s_cbranch_vccnz .LBB0_442
	v_pk_mul_f32 v[34:35], v[24:25], v[24:25]
	v_pk_mul_f32 v[36:37], v[22:23], v[22:23]
	v_cvt_pk_bf16_f32 v22, v22, v23
	v_pk_mov_b32 v[54:55], v[36:37], v[34:35] op_sel:[1,0]
	v_mov_b32_e32 v37, v35
	v_pk_add_f32 v[34:35], v[54:55], v[36:37]
	v_pk_mul_f32 v[36:37], v[28:29], v[28:29]
	v_pk_mul_f32 v[54:55], v[26:27], v[26:27]
	v_mov_b32_e32 v56, v36
	v_mov_b32_e32 v57, v54
	v_mov_b32_e32 v54, v37
	v_pk_add_f32 v[36:37], v[56:57], v[54:55]
	v_add_f32_e32 v34, v34, v35
	v_add_f32_e32 v34, v37, v34
	v_add_f32_e32 v34, v36, v34
	v_cvt_pk_bf16_f32 v23, v24, v25
	v_cvt_pk_bf16_f32 v24, v26, v27
	v_cvt_pk_bf16_f32 v25, v28, v29
	v_lshl_add_u64 v[26:27], v[32:33], 1, v[38:39]
	global_store_dwordx4 v[26:27], v[22:25], off sc0 sc1
.LBB0_442:
	s_waitcnt vmcnt(4)
	s_nop 0
	v_lshlrev_b32_e32 v22, 16, v18
	v_and_b32_e32 v23, 0xffff0000, v18
	v_lshlrev_b32_e32 v18, 16, v19
	v_and_b32_e32 v19, 0xffff0000, v19
	v_lshlrev_b32_e32 v26, 16, v20
	v_and_b32_e32 v27, 0xffff0000, v20
	v_lshlrev_b32_e32 v24, 16, v21
	v_and_b32_e32 v25, 0xffff0000, v21
	v_pk_fma_f32 v[20:21], s[72:73], v[104:105], v[18:19]
	v_pk_fma_f32 v[18:19], s[52:53], v[102:103], v[22:23]
	v_pk_fma_f32 v[24:25], s[72:73], v[100:101], v[24:25]
	v_pk_fma_f32 v[22:23], s[52:53], v[98:99], v[26:27]
	s_and_b64 vcc, exec, s[6:7]
	s_mov_b64 s[12:13], -1
	s_cbranch_vccnz .LBB0_445
	global_store_dwordx4 v[30:31], v[18:21], off offset:512 sc0 sc1
	global_store_dwordx4 v[30:31], v[22:25], off offset:528 sc0 sc1
	s_cbranch_execz .LBB0_446

; __device__ __forceinline__ unsigned pk2(float lo, float hi) { f32x2_t v = {lo, hi}; bf16x2_t b = __builtin_convertvector(v, bf16x2_t); return __builtin_bit_cast(unsigned, b); }
;     __device__ __forceinline__ void operator()(AccRef acc, const pg8::Unit& u, int wr, int wc, int fr, int fq) const {
;     ...
;             for (int m = 0; m < 4; ++m) {
;                 const int row = row0 + ai * 128 + m * 16;
;                 float ss = 0.f;
; #pragma unroll
;                 for (int bj = 0; bj < 2; ++bj) {
;                     const size_t p = (size_t)row * D + col0 + bj * 128;
;                     const v4u w0 = xw[m][bj];
;                     f32x4 a = {bflo(w0.x), bfhi(w0.x), bflo(w0.y), bfhi(w0.y)}, b = {bflo(w0.z), bfhi(w0.z), bflo(w0.w), bfhi(w0.w)};
;                     a = a + acc[ai][bj][m][0] * scale; b = b + acc[ai][bj][m][1] * scale;
;                     if (outf) { *(f32x4*)(outf + p) = a; *(f32x4*)(outf + p + 4) = b; }
;                     else {
;                         ss += (a[0] * a[0] + a[1] * a[1]) + (a[2] * a[2] + a[3] * a[3]) + (b[0] * b[0] + b[1] * b[1]) + (b[2] * b[2] + b[3] * b[3]);
;                         v4u w; w.x = pk2(a[0], a[1]); w.y = pk2(a[2], a[3]); w.z = pk2(b[0], b[1]); w.w = pk2(b[2], b[3]);
;                         *(v4u*)(xb + p) = w;
;                     }
;                 }
;                 if (!outf) {
;                     ss += __shfl_xor(ss, 16); ss += __shfl_xor(ss, 32);
;                     if (fq == 0) rss[(size_t)row * 16 + u.pn * 4 + wc] = ss;
;                 }
.LBB0_446:
	v_pk_mul_f32 v[26:27], v[20:21], v[20:21]
	v_pk_mul_f32 v[28:29], v[18:19], v[18:19]
	v_cvt_pk_bf16_f32 v18, v18, v19
	v_pk_mov_b32 v[30:31], v[28:29], v[26:27] op_sel:[1,0]
	v_mov_b32_e32 v29, v27
	v_pk_add_f32 v[26:27], v[30:31], v[28:29]
	v_pk_mul_f32 v[28:29], v[24:25], v[24:25]
	v_pk_mul_f32 v[30:31], v[22:23], v[22:23]
	v_mov_b32_e32 v32, v28
	v_mov_b32_e32 v33, v30
	v_mov_b32_e32 v30, v29
	v_pk_add_f32 v[28:29], v[32:33], v[30:31]
	v_add_f32_e32 v26, v26, v27
	v_add_f32_e32 v26, v29, v26
	v_add_f32_e32 v26, v28, v26
	v_add_f32_e32 v34, v26, v34
	v_cvt_pk_bf16_f32 v19, v20, v21
	v_cvt_pk_bf16_f32 v20, v22, v23
	v_cvt_pk_bf16_f32 v21, v24, v25
	global_store_dwordx4 v[52:53], v[18:21], off offset:256 sc0 sc1
	s_and_b64 vcc, exec, s[10:11]
	s_cbranch_vccnz .LBB0_450
.LBB0_447:
	v_and_b32_e32 v19, 64, v236
	v_xor_b32_e32 v18, 16, v236
	v_add_u32_e32 v19, 64, v19
	v_cmp_lt_i32_e32 vcc, v18, v19
	v_xor_b32_e32 v20, 32, v236
	s_nop 0
	v_cndmask_b32_e32 v18, v236, v18, vcc
	v_lshlrev_b32_e32 v18, 2, v18
	ds_bpermute_b32 v18, v18, v34
	v_cmp_lt_i32_e32 vcc, v20, v19
	s_waitcnt lgkmcnt(0)
	v_add_f32_e32 v18, v34, v18
	v_cndmask_b32_e32 v19, v236, v20, vcc
	v_lshlrev_b32_e32 v19, 2, v19
	ds_bpermute_b32 v19, v19, v18
	s_and_saveexec_b64 s[12:13], s[8:9]
	s_cbranch_execz .LBB0_449
	s_waitcnt lgkmcnt(0)
	v_add_f32_e32 v20, v18, v19
	s_lshl_b32 s18, s40, 2
	v_lshlrev_b64 v[18:19], 6, v[50:51]
	s_ashr_i32 s19, s18, 31
	v_lshl_add_u64 v[18:19], s[64:65], 0, v[18:19]
	v_lshl_add_u64 v[18:19], s[18:19], 2, v[18:19]
	s_lshl_b32 s38, s63, 2
	v_lshl_add_u64 v[18:19], v[18:19], 0, s[38:39]
	global_store_dword v[18:19], v20, off sc0 sc1

; __device__ __forceinline__ unsigned pk2(float lo, float hi) { f32x2_t v = {lo, hi}; bf16x2_t b = __builtin_convertvector(v, bf16x2_t); return __builtin_bit_cast(unsigned, b); }
;     __device__ __forceinline__ void operator()(AccRef acc, const pg8::Unit& u, int wr, int wc, int fr, int fq) const {
;     ...
;             for (int m = 0; m < 4; ++m) {
;                 const int row = row0 + ai * 128 + m * 16;
;                 float ss = 0.f;
; #pragma unroll
;                 for (int bj = 0; bj < 2; ++bj) {
;                     const size_t p = (size_t)row * D + col0 + bj * 128;
;                     const v4u w0 = xw[m][bj];
;                     f32x4 a = {bflo(w0.x), bfhi(w0.x), bflo(w0.y), bfhi(w0.y)}, b = {bflo(w0.z), bfhi(w0.z), bflo(w0.w), bfhi(w0.w)};
;                     a = a + acc[ai][bj][m][0] * scale; b = b + acc[ai][bj][m][1] * scale;
;                     if (outf) { *(f32x4*)(outf + p) = a; *(f32x4*)(outf + p + 4) = b; }
;                     else {
;                         ss += (a[0] * a[0] + a[1] * a[1]) + (a[2] * a[2] + a[3] * a[3]) + (b[0] * b[0] + b[1] * b[1]) + (b[2] * b[2] + b[3] * b[3]);
;                         v4u w; w.x = pk2(a[0], a[1]); w.y = pk2(a[2], a[3]); w.z = pk2(b[0], b[1]); w.w = pk2(b[2], b[3]);
;                         *(v4u*)(xb + p) = w;
;                     }
;                 }
;                 if (!outf) {
;                     ss += __shfl_xor(ss, 16); ss += __shfl_xor(ss, 32);
;                     if (fq == 0) rss[(size_t)row * 16 + u.pn * 4 + wc] = ss;
;                 }
.LBB0_450:
	v_lshlrev_b64 v[24:25], 10, v[46:47]
	v_lshl_add_u64 v[22:23], v[24:25], 0, v[40:41]
	s_waitcnt vmcnt(3)
	v_lshlrev_b32_e32 v18, 16, v14
	s_waitcnt lgkmcnt(0)
	v_and_b32_e32 v19, 0xffff0000, v14
	v_lshlrev_b32_e32 v14, 16, v15
	v_and_b32_e32 v15, 0xffff0000, v15
	v_lshlrev_b32_e32 v26, 16, v16
	v_and_b32_e32 v27, 0xffff0000, v16
	v_lshlrev_b32_e32 v20, 16, v17
	v_and_b32_e32 v21, 0xffff0000, v17
	v_pk_fma_f32 v[16:17], s[72:73], v[96:97], v[14:15]
	v_pk_fma_f32 v[14:15], s[52:53], v[94:95], v[18:19]
	v_pk_fma_f32 v[20:21], s[72:73], v[92:93], v[20:21]
	v_pk_fma_f32 v[18:19], s[52:53], v[90:91], v[26:27]
	s_mov_b64 s[12:13], -1
	s_and_b64 vcc, exec, s[6:7]
	v_lshl_add_u64 v[22:23], v[22:23], 2, s[54:55]
	s_cbranch_vccnz .LBB0_452
	s_mov_b64 s[12:13], 0
	global_store_dwordx4 v[22:23], v[14:17], off sc0 sc1
	global_store_dwordx4 v[22:23], v[18:21], off offset:16 sc0 sc1

; __device__ __forceinline__ unsigned pk2(float lo, float hi) { f32x2_t v = {lo, hi}; bf16x2_t b = __builtin_convertvector(v, bf16x2_t); return __builtin_bit_cast(unsigned, b); }
;     __device__ __forceinline__ void operator()(AccRef acc, const pg8::Unit& u, int wr, int wc, int fr, int fq) const {
;     ...
;             for (int m = 0; m < 4; ++m) {
;                 const int row = row0 + ai * 128 + m * 16;
;                 float ss = 0.f;
; #pragma unroll
;                 for (int bj = 0; bj < 2; ++bj) {
;                     const size_t p = (size_t)row * D + col0 + bj * 128;
;                     const v4u w0 = xw[m][bj];
;                     f32x4 a = {bflo(w0.x), bfhi(w0.x), bflo(w0.y), bfhi(w0.y)}, b = {bflo(w0.z), bfhi(w0.z), bflo(w0.w), bfhi(w0.w)};
;                     a = a + acc[ai][bj][m][0] * scale; b = b + acc[ai][bj][m][1] * scale;
;                     if (outf) { *(f32x4*)(outf + p) = a; *(f32x4*)(outf + p + 4) = b; }
;                     else {
;                         ss += (a[0] * a[0] + a[1] * a[1]) + (a[2] * a[2] + a[3] * a[3]) + (b[0] * b[0] + b[1] * b[1]) + (b[2] * b[2] + b[3] * b[3]);
;                         v4u w; w.x = pk2(a[0], a[1]); w.y = pk2(a[2], a[3]); w.z = pk2(b[0], b[1]); w.w = pk2(b[2], b[3]);
;                         *(v4u*)(xb + p) = w;
;                     }
;                 }
;                 if (!outf) {
;                     ss += __shfl_xor(ss, 16); ss += __shfl_xor(ss, 32);
;                     if (fq == 0) rss[(size_t)row * 16 + u.pn * 4 + wc] = ss;
;                 }
.LBB0_454:
	s_waitcnt vmcnt(2)
	s_nop 0
	v_lshlrev_b32_e32 v14, 16, v10
	v_and_b32_e32 v15, 0xffff0000, v10
	v_lshlrev_b32_e32 v10, 16, v11
	v_and_b32_e32 v11, 0xffff0000, v11
	v_lshlrev_b32_e32 v18, 16, v12
	v_and_b32_e32 v19, 0xffff0000, v12
	v_lshlrev_b32_e32 v16, 16, v13
	v_and_b32_e32 v17, 0xffff0000, v13
	v_pk_fma_f32 v[12:13], s[72:73], v[88:89], v[10:11]
	v_pk_fma_f32 v[10:11], s[52:53], v[86:87], v[14:15]
	v_pk_fma_f32 v[16:17], s[72:73], v[84:85], v[16:17]
	v_pk_fma_f32 v[14:15], s[52:53], v[82:83], v[18:19]
	s_and_b64 vcc, exec, s[6:7]
	s_mov_b64 s[12:13], -1
	s_cbranch_vccnz .LBB0_457
	global_store_dwordx4 v[22:23], v[10:13], off offset:512 sc0 sc1
	global_store_dwordx4 v[22:23], v[14:17], off offset:528 sc0 sc1
	s_cbranch_execz .LBB0_458

; __device__ __forceinline__ unsigned pk2(float lo, float hi) { f32x2_t v = {lo, hi}; bf16x2_t b = __builtin_convertvector(v, bf16x2_t); return __builtin_bit_cast(unsigned, b); }
;     __device__ __forceinline__ void operator()(AccRef acc, const pg8::Unit& u, int wr, int wc, int fr, int fq) const {
;     ...
;             for (int m = 0; m < 4; ++m) {
;                 const int row = row0 + ai * 128 + m * 16;
;                 float ss = 0.f;
; #pragma unroll
;                 for (int bj = 0; bj < 2; ++bj) {
;                     const size_t p = (size_t)row * D + col0 + bj * 128;
;                     const v4u w0 = xw[m][bj];
;                     f32x4 a = {bflo(w0.x), bfhi(w0.x), bflo(w0.y), bfhi(w0.y)}, b = {bflo(w0.z), bfhi(w0.z), bflo(w0.w), bfhi(w0.w)};
;                     a = a + acc[ai][bj][m][0] * scale; b = b + acc[ai][bj][m][1] * scale;
;                     if (outf) { *(f32x4*)(outf + p) = a; *(f32x4*)(outf + p + 4) = b; }
;                     else {
;                         ss += (a[0] * a[0] + a[1] * a[1]) + (a[2] * a[2] + a[3] * a[3]) + (b[0] * b[0] + b[1] * b[1]) + (b[2] * b[2] + b[3] * b[3]);
;                         v4u w; w.x = pk2(a[0], a[1]); w.y = pk2(a[2], a[3]); w.z = pk2(b[0], b[1]); w.w = pk2(b[2], b[3]);
;                         *(v4u*)(xb + p) = w;
;                     }
;                 }
;                 if (!outf) {
;                     ss += __shfl_xor(ss, 16); ss += __shfl_xor(ss, 32);
;                     if (fq == 0) rss[(size_t)row * 16 + u.pn * 4 + wc] = ss;
;                 }
.LBB0_458:
	v_pk_mul_f32 v[18:19], v[12:13], v[12:13]
	v_pk_mul_f32 v[20:21], v[10:11], v[10:11]
	v_cvt_pk_bf16_f32 v10, v10, v11
	v_pk_mov_b32 v[22:23], v[20:21], v[18:19] op_sel:[1,0]
	v_mov_b32_e32 v21, v19
	v_pk_add_f32 v[18:19], v[22:23], v[20:21]
	v_pk_mul_f32 v[20:21], v[16:17], v[16:17]
	v_pk_mul_f32 v[22:23], v[14:15], v[14:15]
	v_mov_b32_e32 v24, v20
	v_mov_b32_e32 v25, v22
	v_mov_b32_e32 v22, v21
	v_pk_add_f32 v[20:21], v[24:25], v[22:23]
	v_add_f32_e32 v18, v18, v19
	v_add_f32_e32 v18, v21, v18
	v_add_f32_e32 v18, v20, v18
	v_add_f32_e32 v26, v18, v26
	v_cvt_pk_bf16_f32 v11, v12, v13
	v_cvt_pk_bf16_f32 v12, v14, v15
	v_cvt_pk_bf16_f32 v13, v16, v17
	global_store_dwordx4 v[48:49], v[10:13], off offset:256 sc0 sc1
	s_and_b64 vcc, exec, s[10:11]
	s_cbranch_vccnz .LBB0_462
.LBB0_459:
	v_and_b32_e32 v11, 64, v236
	v_xor_b32_e32 v10, 16, v236
	v_add_u32_e32 v11, 64, v11
	v_cmp_lt_i32_e32 vcc, v10, v11
	v_xor_b32_e32 v12, 32, v236
	s_nop 0
	v_cndmask_b32_e32 v10, v236, v10, vcc
	v_lshlrev_b32_e32 v10, 2, v10
	ds_bpermute_b32 v10, v10, v26
	v_cmp_lt_i32_e32 vcc, v12, v11
	s_waitcnt lgkmcnt(0)
	v_add_f32_e32 v10, v26, v10
	v_cndmask_b32_e32 v11, v236, v12, vcc
	v_lshlrev_b32_e32 v11, 2, v11
	ds_bpermute_b32 v11, v11, v10
	s_and_saveexec_b64 s[12:13], s[8:9]
	s_cbranch_execz .LBB0_461
	s_waitcnt lgkmcnt(0)
	v_add_f32_e32 v12, v10, v11
	s_lshl_b32 s18, s40, 2
	v_lshlrev_b64 v[10:11], 6, v[46:47]
	s_ashr_i32 s19, s18, 31
	v_lshl_add_u64 v[10:11], s[64:65], 0, v[10:11]
	v_lshl_add_u64 v[10:11], s[18:19], 2, v[10:11]
	s_lshl_b32 s38, s63, 2
	v_lshl_add_u64 v[10:11], v[10:11], 0, s[38:39]
	global_store_dword v[10:11], v12, off sc0 sc1

; __device__ __forceinline__ unsigned pk2(float lo, float hi) { f32x2_t v = {lo, hi}; bf16x2_t b = __builtin_convertvector(v, bf16x2_t); return __builtin_bit_cast(unsigned, b); }
;     __device__ __forceinline__ void operator()(AccRef acc, const pg8::Unit& u, int wr, int wc, int fr, int fq) const {
;     ...
;             for (int m = 0; m < 4; ++m) {
;                 const int row = row0 + ai * 128 + m * 16;
;                 float ss = 0.f;
; #pragma unroll
;                 for (int bj = 0; bj < 2; ++bj) {
;                     const size_t p = (size_t)row * D + col0 + bj * 128;
;                     const v4u w0 = xw[m][bj];
;                     f32x4 a = {bflo(w0.x), bfhi(w0.x), bflo(w0.y), bfhi(w0.y)}, b = {bflo(w0.z), bfhi(w0.z), bflo(w0.w), bfhi(w0.w)};
;                     a = a + acc[ai][bj][m][0] * scale; b = b + acc[ai][bj][m][1] * scale;
;                     if (outf) { *(f32x4*)(outf + p) = a; *(f32x4*)(outf + p + 4) = b; }
;                     else {
;                         ss += (a[0] * a[0] + a[1] * a[1]) + (a[2] * a[2] + a[3] * a[3]) + (b[0] * b[0] + b[1] * b[1]) + (b[2] * b[2] + b[3] * b[3]);
;                         v4u w; w.x = pk2(a[0], a[1]); w.y = pk2(a[2], a[3]); w.z = pk2(b[0], b[1]); w.w = pk2(b[2], b[3]);
;                         *(v4u*)(xb + p) = w;
;                     }
;                 }
;                 if (!outf) {
;                     ss += __shfl_xor(ss, 16); ss += __shfl_xor(ss, 32);
;                     if (fq == 0) rss[(size_t)row * 16 + u.pn * 4 + wc] = ss;
;                 }
.LBB0_462:
	v_lshlrev_b64 v[16:17], 10, v[42:43]
	v_lshl_add_u64 v[14:15], v[16:17], 0, v[40:41]
	s_waitcnt vmcnt(1)
	v_lshlrev_b32_e32 v10, 16, v6
	s_waitcnt lgkmcnt(0)
	v_and_b32_e32 v11, 0xffff0000, v6
	v_lshlrev_b32_e32 v6, 16, v7
	v_and_b32_e32 v7, 0xffff0000, v7
	v_lshlrev_b32_e32 v18, 16, v8
	v_and_b32_e32 v19, 0xffff0000, v8
	v_lshlrev_b32_e32 v12, 16, v9
	v_and_b32_e32 v13, 0xffff0000, v9
	v_pk_fma_f32 v[8:9], s[72:73], v[80:81], v[6:7]
	v_pk_fma_f32 v[6:7], s[52:53], v[78:79], v[10:11]
	v_pk_fma_f32 v[12:13], s[72:73], v[76:77], v[12:13]
	v_pk_fma_f32 v[10:11], s[52:53], v[74:75], v[18:19]
	s_mov_b64 s[12:13], -1
	s_and_b64 vcc, exec, s[6:7]
	v_lshl_add_u64 v[14:15], v[14:15], 2, s[54:55]
	s_cbranch_vccnz .LBB0_464
	s_mov_b64 s[12:13], 0
	global_store_dwordx4 v[14:15], v[6:9], off sc0 sc1
	global_store_dwordx4 v[14:15], v[10:13], off offset:16 sc0 sc1
.LBB0_464:
	v_mov_b32_e32 v18, 0
	s_andn2_b64 vcc, exec, s[12:13]
	s_cbranch_vccnz .LBB0_466
	v_pk_mul_f32 v[18:19], v[8:9], v[8:9]
	v_pk_mul_f32 v[20:21], v[6:7], v[6:7]
	v_cvt_pk_bf16_f32 v6, v6, v7
	v_pk_mov_b32 v[22:23], v[20:21], v[18:19] op_sel:[1,0]
	v_mov_b32_e32 v21, v19
	v_pk_add_f32 v[18:19], v[22:23], v[20:21]
	v_pk_mul_f32 v[20:21], v[12:13], v[12:13]
	v_pk_mul_f32 v[22:23], v[10:11], v[10:11]
	v_mov_b32_e32 v24, v20
	v_mov_b32_e32 v25, v22
	v_mov_b32_e32 v22, v21
	v_pk_add_f32 v[20:21], v[24:25], v[22:23]
	v_add_f32_e32 v18, v18, v19
	v_add_f32_e32 v18, v21, v18
	v_add_f32_e32 v18, v20, v18
	v_cvt_pk_bf16_f32 v7, v8, v9
	v_cvt_pk_bf16_f32 v8, v10, v11
	v_cvt_pk_bf16_f32 v9, v12, v13
	v_lshl_add_u64 v[10:11], v[16:17], 1, v[38:39]
	global_store_dwordx4 v[10:11], v[6:9], off sc0 sc1
.LBB0_466:
	s_waitcnt vmcnt(0)
	s_nop 0
	v_lshlrev_b32_e32 v6, 16, v2
	v_and_b32_e32 v7, 0xffff0000, v2
	v_lshlrev_b32_e32 v2, 16, v3
	v_and_b32_e32 v3, 0xffff0000, v3
	v_lshlrev_b32_e32 v10, 16, v4
	v_and_b32_e32 v11, 0xffff0000, v4
	v_lshlrev_b32_e32 v8, 16, v5
	v_and_b32_e32 v9, 0xffff0000, v5
	v_pk_fma_f32 v[4:5], s[72:73], v[72:73], v[2:3]
	v_pk_fma_f32 v[2:3], s[52:53], v[70:71], v[6:7]
	v_pk_fma_f32 v[8:9], s[72:73], v[68:69], v[8:9]
	v_pk_fma_f32 v[6:7], s[52:53], v[66:67], v[10:11]
	s_and_b64 vcc, exec, s[6:7]
	s_mov_b64 s[6:7], -1
	s_cbranch_vccnz .LBB0_472
	global_store_dwordx4 v[14:15], v[2:5], off offset:512 sc0 sc1
	global_store_dwordx4 v[14:15], v[6:9], off offset:528 sc0 sc1
	s_cbranch_execz .LBB0_473

; __device__ __forceinline__ void attention_phase(PPtr p, int layer, LAS unsigned char* L, unsigned* counter, const bool do_store) {
;     ...
;             { const float inv = lam / (l + __shfl_xor(l, 32));
;               float ss = 0.f;
; #pragma unroll
;               for (int db = 0; db < 4; ++db)
; #pragma unroll
;                   for (int i = 0; i < 8; ++i) {
;                       const unsigned w0 = o0p[(db * 8 + i) * NTHREADS];
;                       const float a = bflo(w0) - o[db][2 * i] * inv, c = bfhi(w0) - o[db][2 * i + 1] * inv;
;                       o[db][2 * i] = a; o[db][2 * i + 1] = c; ss += a * a + c * c;
;                   }
;               ss += __shfl_xor(ss, 32);
.LBB0_496:
	s_load_dword s1, s[50:51], 0xc0
	ds_bpermute_b32 v66, v159, v176
	v_sub_f32_e32 v0, v241, v242
	s_waitcnt lgkmcnt(0)
	v_add_f32_e32 v0, s1, v0
	v_add_f32_e32 v66, v176, v66
	v_div_scale_f32 v67, s[2:3], v66, v66, v0
	v_rcp_f32_e32 v68, v67
	s_mov_b32 s2, 0x800000
	v_fma_f32 v69, -v67, v68, 1.0
	v_fmac_f32_e32 v68, v69, v68
	v_div_scale_f32 v69, vcc, v0, v66, v0
	v_mul_f32_e32 v70, v69, v68
	v_fma_f32 v71, -v67, v70, v69
	v_fmac_f32_e32 v70, v71, v68
	v_fma_f32 v67, -v67, v70, v69
	v_div_fmas_f32 v67, v67, v68, v70
	v_div_fixup_f32 v72, v67, v66, v0
	ds_read2st64_b32 v[66:67], v210 offset1:8
	v_mov_b32_e32 v70, v10
	v_mov_b32_e32 v71, v12
	v_mov_b32_e32 v12, v11
	v_lshlrev_b32_e32 v0, 3, v230
	s_waitcnt lgkmcnt(0)
	v_lshlrev_b32_e32 v128, 16, v66
	v_and_b32_e32 v129, 0xffff0000, v66
	s_waitcnt vmcnt(2)
	v_lshlrev_b32_e32 v130, 16, v67
	v_and_b32_e32 v131, 0xffff0000, v67
	ds_read2st64_b32 v[66:67], v210 offset0:16 offset1:24
	s_waitcnt lgkmcnt(0)
	v_lshlrev_b32_e32 v122, 16, v66
	v_and_b32_e32 v123, 0xffff0000, v66
	v_lshlrev_b32_e32 v126, 16, v67
	v_and_b32_e32 v127, 0xffff0000, v67
	ds_read2st64_b32 v[66:67], v210 offset0:32 offset1:40
	s_waitcnt lgkmcnt(0)
	v_lshlrev_b32_e32 v118, 16, v66
	v_and_b32_e32 v119, 0xffff0000, v66
	v_lshlrev_b32_e32 v124, 16, v67
	v_and_b32_e32 v125, 0xffff0000, v67
	ds_read2st64_b32 v[66:67], v210 offset0:48 offset1:56
	s_waitcnt lgkmcnt(0)
	v_lshlrev_b32_e32 v114, 16, v66
	v_and_b32_e32 v115, 0xffff0000, v66
	v_lshlrev_b32_e32 v120, 16, v67
	v_and_b32_e32 v121, 0xffff0000, v67
	ds_read2st64_b32 v[66:67], v210 offset0:64 offset1:72
	s_waitcnt lgkmcnt(0)
	v_lshlrev_b32_e32 v110, 16, v66
	v_and_b32_e32 v111, 0xffff0000, v66
	v_lshlrev_b32_e32 v116, 16, v67
	v_and_b32_e32 v117, 0xffff0000, v67
	ds_read2st64_b32 v[66:67], v210 offset0:80 offset1:88
	s_waitcnt lgkmcnt(0)
	v_lshlrev_b32_e32 v106, 16, v66
	v_and_b32_e32 v107, 0xffff0000, v66
	v_lshlrev_b32_e32 v112, 16, v67
	v_and_b32_e32 v113, 0xffff0000, v67
	ds_read2st64_b32 v[66:67], v210 offset0:96 offset1:104
	s_waitcnt lgkmcnt(0)
	v_lshlrev_b32_e32 v102, 16, v66
	v_and_b32_e32 v103, 0xffff0000, v66
	v_lshlrev_b32_e32 v108, 16, v67
	v_and_b32_e32 v109, 0xffff0000, v67
	ds_read2st64_b32 v[66:67], v210 offset0:112 offset1:120
	s_waitcnt lgkmcnt(0)
	v_lshlrev_b32_e32 v98, 16, v66
	v_and_b32_e32 v99, 0xffff0000, v66
	v_lshlrev_b32_e32 v104, 16, v67
	v_and_b32_e32 v105, 0xffff0000, v67
	ds_read2st64_b32 v[66:67], v210 offset0:128 offset1:136
	s_waitcnt lgkmcnt(0)
	v_lshlrev_b32_e32 v94, 16, v66
	v_and_b32_e32 v95, 0xffff0000, v66
	v_lshlrev_b32_e32 v100, 16, v67
	v_and_b32_e32 v101, 0xffff0000, v67
	ds_read2st64_b32 v[66:67], v210 offset0:144 offset1:152
	s_waitcnt lgkmcnt(0)
	v_lshlrev_b32_e32 v90, 16, v66
	v_and_b32_e32 v91, 0xffff0000, v66
	v_lshlrev_b32_e32 v96, 16, v67
	v_and_b32_e32 v97, 0xffff0000, v67
	ds_read2st64_b32 v[66:67], v210 offset0:160 offset1:168
	s_waitcnt lgkmcnt(0)
	v_lshlrev_b32_e32 v86, 16, v66
	v_and_b32_e32 v87, 0xffff0000, v66
	v_lshlrev_b32_e32 v92, 16, v67
	v_and_b32_e32 v93, 0xffff0000, v67
	ds_read2st64_b32 v[66:67], v210 offset0:176 offset1:184
	s_waitcnt lgkmcnt(0)
	v_lshlrev_b32_e32 v84, 16, v66
	v_and_b32_e32 v85, 0xffff0000, v66
	v_lshlrev_b32_e32 v88, 16, v67
	v_and_b32_e32 v89, 0xffff0000, v67
	ds_read2st64_b32 v[66:67], v210 offset0:192 offset1:200
	s_waitcnt lgkmcnt(0)
	v_lshlrev_b32_e32 v80, 16, v66
	v_and_b32_e32 v81, 0xffff0000, v66
	v_lshlrev_b32_e32 v82, 16, v67
	v_and_b32_e32 v83, 0xffff0000, v67
	ds_read2st64_b32 v[66:67], v210 offset0:208 offset1:216
	s_waitcnt lgkmcnt(0)
	v_lshlrev_b32_e32 v76, 16, v66
	v_and_b32_e32 v77, 0xffff0000, v66
	v_lshlrev_b32_e32 v78, 16, v67
	v_and_b32_e32 v79, 0xffff0000, v67
	ds_read2st64_b32 v[66:67], v210 offset0:224 offset1:232
	s_waitcnt lgkmcnt(0)
	v_lshlrev_b32_e32 v69, 16, v67
	v_lshlrev_b32_e32 v68, 16, v66
	v_and_b32_e32 v67, 0xffff0000, v67
	v_and_b32_e32 v66, 0xffff0000, v66
	v_pk_fma_f32 v[70:71], v[70:71], v[72:73], v[68:69] op_sel_hi:[1,0,1] neg_lo:[1,0,0] neg_hi:[1,0,0]
	v_pk_fma_f32 v[68:69], v[12:13], v[72:73], v[66:67] op_sel_hi:[1,0,1] neg_lo:[1,0,0] neg_hi:[1,0,0]
	v_mov_b32_e32 v67, v16
	v_pk_mul_f32 v[10:11], v[68:69], v[68:69]
	v_mov_b32_e32 v16, v15
	v_pk_fma_f32 v[74:75], v[70:71], v[70:71], v[10:11]
	ds_read2st64_b32 v[10:11], v210 offset0:240 offset1:248
	s_load_dword s1, s[50:51], 0xc8
	s_load_dwordx2 s[16:17], s[42:43], 0x60
	v_mov_b32_e32 v66, v14
	s_waitcnt lgkmcnt(0)
; __device__ __forceinline__ void attention_phase(PPtr p, int layer, LAS unsigned char* L, unsigned* counter, const bool do_store) {
;     ...
;                   for (int i = 0; i < 8; ++i) {
;                       const unsigned w0 = o0p[(db * 8 + i) * NTHREADS];
;                       const float a = bflo(w0) - o[db][2 * i] * inv, c = bfhi(w0) - o[db][2 * i + 1] * inv;
;                       o[db][2 * i] = a; o[db][2 * i + 1] = c; ss += a * a + c * c;
;                   }
;               ss += __shfl_xor(ss, 32);
;               const float rs = rsqrtf(ss * (1.0f / 128.0f) + RMS_EPS) * p->one_minus_lam_init[layer];
;               const float* sg = p->in[12] + (size_t)layer * 128;
;               bf16* orow = QA + (size_t)(q0w + r) * 512;
	v_lshlrev_b32_e32 v13, 16, v11
	v_lshlrev_b32_e32 v12, 16, v10
	v_and_b32_e32 v11, 0xffff0000, v11
	v_and_b32_e32 v10, 0xffff0000, v10
	v_pk_fma_f32 v[14:15], v[16:17], v[72:73], v[10:11] op_sel_hi:[1,0,1] neg_lo:[1,0,0] neg_hi:[1,0,0]
	v_pk_fma_f32 v[66:67], v[66:67], v[72:73], v[12:13] op_sel_hi:[1,0,1] neg_lo:[1,0,0] neg_hi:[1,0,0]
	v_pk_mul_f32 v[10:11], v[14:15], v[14:15]
	s_add_u32 s16, s16, s52
	v_pk_fma_f32 v[16:17], v[66:67], v[66:67], v[10:11]
	v_or_b32_e32 v10, v240, v231
	v_ashrrev_i32_e32 v11, 31, v10
	s_addc_u32 s17, s17, s53
	v_lshlrev_b64 v[10:11], 10, v[10:11]
	v_lshlrev_b32_e32 v73, 4, v230
	v_add_u32_e32 v73, 0x13000, v73
	v_lshl_add_u64 v[132:133], s[14:15], 0, v[10:11]
	ds_read_b128 v[10:13], v73
	v_pk_fma_f32 v[130:131], v[52:53], v[72:73], v[130:131] op_sel_hi:[1,0,1] neg_lo:[1,0,0] neg_hi:[1,0,0]
	v_pk_fma_f32 v[128:129], v[50:51], v[72:73], v[128:129] op_sel_hi:[1,0,1] neg_lo:[1,0,0] neg_hi:[1,0,0]
	v_lshl_add_u64 v[50:51], v[132:133], 0, v[0:1]
	v_pk_fma_f32 v[132:133], v[54:55], v[72:73], v[122:123] op_sel_hi:[1,0,1] neg_lo:[1,0,0] neg_hi:[1,0,0]
	v_pk_fma_f32 v[122:123], v[60:61], v[72:73], v[124:125] op_sel_hi:[1,0,1] neg_lo:[1,0,0] neg_hi:[1,0,0]
	v_pk_fma_f32 v[60:61], v[34:35], v[72:73], v[110:111] op_sel_hi:[1,0,1] neg_lo:[1,0,0] neg_hi:[1,0,0]
	v_pk_fma_f32 v[52:53], v[40:41], v[72:73], v[112:113] op_sel_hi:[1,0,1] neg_lo:[1,0,0] neg_hi:[1,0,0]
	v_pk_fma_f32 v[40:41], v[18:19], v[72:73], v[94:95] op_sel_hi:[1,0,1] neg_lo:[1,0,0] neg_hi:[1,0,0]
	v_pk_fma_f32 v[34:35], v[24:25], v[72:73], v[96:97] op_sel_hi:[1,0,1] neg_lo:[1,0,0] neg_hi:[1,0,0]
	v_pk_fma_f32 v[18:19], v[32:33], v[72:73], v[88:89] op_sel_hi:[1,0,1] neg_lo:[1,0,0] neg_hi:[1,0,0]
	v_pk_fma_f32 v[24:25], v[30:31], v[72:73], v[84:85] op_sel_hi:[1,0,1] neg_lo:[1,0,0] neg_hi:[1,0,0]
	v_mov_b32_e32 v31, v19
	v_mov_b32_e32 v30, v25
	v_pk_fma_f32 v[126:127], v[56:57], v[72:73], v[126:127] op_sel_hi:[1,0,1] neg_lo:[1,0,0] neg_hi:[1,0,0]
	v_pk_fma_f32 v[56:57], v[38:39], v[72:73], v[106:107] op_sel_hi:[1,0,1] neg_lo:[1,0,0] neg_hi:[1,0,0]
	v_pk_fma_f32 v[38:39], v[20:21], v[72:73], v[100:101] op_sel_hi:[1,0,1] neg_lo:[1,0,0] neg_hi:[1,0,0]
	v_mov_b32_e32 v20, v24
	v_mov_b32_e32 v21, v18
	v_pk_mul_f32 v[30:31], v[30:31], v[30:31]
	v_pk_fma_f32 v[4:5], v[4:5], v[72:73], v[82:83] op_sel_hi:[1,0,1] neg_lo:[1,0,0] neg_hi:[1,0,0]
	v_pk_fma_f32 v[30:31], v[20:21], v[20:21], v[30:31]
	v_pk_fma_f32 v[20:21], v[2:3], v[72:73], v[80:81] op_sel_hi:[1,0,1] neg_lo:[1,0,0] neg_hi:[1,0,0]
	v_mov_b32_e32 v33, v5
	v_mov_b32_e32 v32, v21
	s_waitcnt vmcnt(1)
	v_pk_mul_f32 v[134:135], v[130:131], v[130:131]
	v_pk_mul_f32 v[136:137], v[128:129], v[128:129]
	v_mov_b32_e32 v2, v20
	v_mov_b32_e32 v3, v4
	v_pk_mul_f32 v[32:33], v[32:33], v[32:33]
	s_waitcnt vmcnt(0)
	v_pk_mul_f32 v[140:141], v[132:133], v[132:133]
	v_pk_fma_f32 v[118:119], v[58:59], v[72:73], v[118:119] op_sel_hi:[1,0,1] neg_lo:[1,0,0] neg_hi:[1,0,0]
	v_pk_fma_f32 v[64:65], v[64:65], v[72:73], v[120:121] op_sel_hi:[1,0,1] neg_lo:[1,0,0] neg_hi:[1,0,0]
	v_pk_fma_f32 v[62:63], v[62:63], v[72:73], v[114:115] op_sel_hi:[1,0,1] neg_lo:[1,0,0] neg_hi:[1,0,0]
	v_pk_fma_f32 v[58:59], v[36:37], v[72:73], v[116:117] op_sel_hi:[1,0,1] neg_lo:[1,0,0] neg_hi:[1,0,0]
	v_pk_fma_f32 v[44:45], v[44:45], v[72:73], v[108:109] op_sel_hi:[1,0,1] neg_lo:[1,0,0] neg_hi:[1,0,0]
	v_pk_fma_f32 v[54:55], v[42:43], v[72:73], v[102:103] op_sel_hi:[1,0,1] neg_lo:[1,0,0] neg_hi:[1,0,0]
	v_pk_fma_f32 v[42:43], v[48:49], v[72:73], v[104:105] op_sel_hi:[1,0,1] neg_lo:[1,0,0] neg_hi:[1,0,0]
	v_pk_fma_f32 v[46:47], v[46:47], v[72:73], v[98:99] op_sel_hi:[1,0,1] neg_lo:[1,0,0] neg_hi:[1,0,0]
	v_pk_fma_f32 v[36:37], v[22:23], v[72:73], v[90:91] op_sel_hi:[1,0,1] neg_lo:[1,0,0] neg_hi:[1,0,0]
	v_pk_fma_f32 v[22:23], v[28:29], v[72:73], v[92:93] op_sel_hi:[1,0,1] neg_lo:[1,0,0] neg_hi:[1,0,0]
	v_pk_fma_f32 v[26:27], v[26:27], v[72:73], v[86:87] op_sel_hi:[1,0,1] neg_lo:[1,0,0] neg_hi:[1,0,0]
	v_pk_fma_f32 v[32:33], v[2:3], v[2:3], v[32:33]
	v_pk_fma_f32 v[2:3], v[8:9], v[72:73], v[78:79] op_sel_hi:[1,0,1] neg_lo:[1,0,0] neg_hi:[1,0,0]
	v_pk_fma_f32 v[6:7], v[6:7], v[72:73], v[76:77] op_sel_hi:[1,0,1] neg_lo:[1,0,0] neg_hi:[1,0,0]
	v_add_f32_e32 v0, v134, v135
	v_add_f32_e32 v72, v136, v137
	v_pk_mul_f32 v[138:139], v[126:127], v[126:127]
	v_add_f32_e32 v0, v72, v0
	v_add_f32_e32 v72, v140, v141
	v_pk_mul_f32 v[142:143], v[118:119], v[118:119]
	v_add_f32_e32 v0, v0, v72
	v_add_f32_e32 v72, v138, v139
	v_pk_mul_f32 v[124:125], v[122:123], v[122:123]
	v_add_f32_e32 v0, v0, v72
	v_add_f32_e32 v72, v142, v143
	v_pk_mul_f32 v[114:115], v[62:63], v[62:63]
	v_add_f32_e32 v0, v0, v72
	v_add_f32_e32 v72, v124, v125
	v_pk_mul_f32 v[120:121], v[64:65], v[64:65]
	v_add_f32_e32 v0, v0, v72
	v_add_f32_e32 v72, v114, v115
	v_pk_mul_f32 v[110:111], v[60:61], v[60:61]
	v_add_f32_e32 v0, v0, v72
	v_add_f32_e32 v72, v120, v121
	v_pk_mul_f32 v[116:117], v[58:59], v[58:59]
	v_add_f32_e32 v0, v0, v72
	v_add_f32_e32 v72, v110, v111
	v_pk_mul_f32 v[106:107], v[56:57], v[56:57]
	v_add_f32_e32 v0, v0, v72
	v_add_f32_e32 v72, v116, v117
	v_pk_mul_f32 v[112:113], v[52:53], v[52:53]
	v_add_f32_e32 v0, v0, v72
	v_add_f32_e32 v72, v106, v107
	v_pk_mul_f32 v[102:103], v[54:55], v[54:55]
	v_add_f32_e32 v0, v0, v72
	v_add_f32_e32 v72, v112, v113
	v_pk_mul_f32 v[108:109], v[44:45], v[44:45]
	v_add_f32_e32 v0, v0, v72
	v_add_f32_e32 v72, v102, v103
	v_pk_mul_f32 v[98:99], v[46:47], v[46:47]
	v_add_f32_e32 v0, v0, v72
	v_add_f32_e32 v72, v108, v109
	v_pk_mul_f32 v[48:49], v[42:43], v[42:43]
	v_add_f32_e32 v0, v0, v72
	v_add_f32_e32 v72, v98, v99
	v_pk_mul_f32 v[94:95], v[40:41], v[40:41]
	v_add_f32_e32 v0, v0, v72
	v_add_f32_e32 v48, v48, v49
	v_pk_mul_f32 v[100:101], v[38:39], v[38:39]
	v_add_f32_e32 v0, v0, v48
	v_add_f32_e32 v48, v94, v95
	v_pk_mul_f32 v[90:91], v[36:37], v[36:37]
	v_add_f32_e32 v0, v0, v48
	v_add_f32_e32 v48, v100, v101
	v_pk_mul_f32 v[96:97], v[34:35], v[34:35]
	v_add_f32_e32 v0, v0, v48
	v_add_f32_e32 v48, v90, v91
	v_pk_mul_f32 v[86:87], v[26:27], v[26:27]
	v_add_f32_e32 v0, v0, v48
	v_add_f32_e32 v48, v96, v97
	v_pk_mul_f32 v[28:29], v[22:23], v[22:23]
	v_add_f32_e32 v0, v0, v48
	v_add_f32_e32 v48, v86, v87
	v_add_f32_e32 v0, v0, v48
	v_add_f32_e32 v28, v28, v29
	v_add_f32_e32 v0, v0, v28
	v_add_f32_e32 v0, v0, v30
	v_mov_b32_e32 v76, v7
	v_mov_b32_e32 v77, v3
	v_add_f32_e32 v0, v0, v31
	v_mov_b32_e32 v8, v6
	v_mov_b32_e32 v9, v2
	v_pk_mul_f32 v[76:77], v[76:77], v[76:77]
	v_add_f32_e32 v0, v0, v32
	v_pk_fma_f32 v[8:9], v[8:9], v[8:9], v[76:77]
	v_add_f32_e32 v0, v0, v33
	v_add_f32_e32 v0, v0, v8
	v_add_f32_e32 v0, v0, v9
	v_add_f32_e32 v0, v0, v74
	v_add_f32_e32 v0, v0, v75
	v_add_f32_e32 v0, v0, v16
	v_add_f32_e32 v0, v0, v17
	ds_bpermute_b32 v8, v159, v0
	s_waitcnt lgkmcnt(0)
; __device__ __forceinline__ unsigned pk2(float lo, float hi) { f32x2_t v = {lo, hi}; bf16x2_t b = __builtin_convertvector(v, bf16x2_t); return __builtin_bit_cast(unsigned, b); }
; __device__ __forceinline__ void attention_phase(PPtr p, int layer, LAS unsigned char* L, unsigned* counter, const bool do_store) {
;     ...
;               ss += __shfl_xor(ss, 32);
;               const float rs = rsqrtf(ss * (1.0f / 128.0f) + RMS_EPS) * p->one_minus_lam_init[layer];
;               const float* sg = p->in[12] + (size_t)layer * 128;
;               bf16* orow = QA + (size_t)(q0w + r) * 512;
;               if (do_store)
; #pragma unroll
;               for (int db = 0; db < 4; ++db)
; #pragma unroll
;                   for (int c = 0; c < 4; ++c) {
;                       const int dv = 32 * db + 8 * c + 4 * h;
;                       const f32x4 g4 = *(const f32x4*)(sg + dv);
;                       v2u w; w.x = pk2(o[db][4 * c] * rs * g4[0], o[db][4 * c + 1] * rs * g4[1]); w.y = pk2(o[db][4 * c + 2] * rs * g4[2], o[db][4 * c + 3] * rs * g4[3]);
;                       *(v2u*)(orow + dv) = w;
;                   }
	v_add_f32_e32 v0, v0, v8
	v_fmamk_f32 v0, v0, 0x3c000000, v215
	v_cmp_gt_f32_e32 vcc, s2, v0
	v_mul_f32_e32 v8, 0x4b800000, v0
	s_nop 0
	v_cndmask_b32_e32 v0, v0, v8, vcc
	v_rsq_f32_e32 v0, v0
	s_nop 0
	v_mul_f32_e32 v8, 0x45800000, v0
	v_cndmask_b32_e32 v0, v0, v8, vcc
	v_mul_f32_e32 v0, s1, v0
	v_pk_mul_f32 v[8:9], v[128:129], v[0:1] op_sel_hi:[1,0]
	v_pk_mul_f32 v[4:5], v[4:5], v[0:1] op_sel_hi:[1,0]
	s_waitcnt vmcnt(0) lgkmcnt(0)
	v_pk_mul_f32 v[8:9], v[10:11], v[8:9]
	v_pk_mul_f32 v[10:11], v[130:131], v[0:1] op_sel_hi:[1,0]
	v_cvt_pk_bf16_f32 v8, v8, v9
	v_pk_mul_f32 v[10:11], v[12:13], v[10:11]
	v_pk_mul_f32 v[12:13], v[132:133], v[0:1] op_sel_hi:[1,0]
	v_cvt_pk_bf16_f32 v9, v10, v11
	global_store_dwordx2 v[50:51], v[8:9], off sc0 sc1
	ds_read_b128 v[8:11], v73 offset:32
	v_pk_mul_f32 v[2:3], v[2:3], v[0:1] op_sel_hi:[1,0]
	s_waitcnt lgkmcnt(0)
	v_pk_mul_f32 v[8:9], v[8:9], v[12:13]
	v_pk_mul_f32 v[12:13], v[126:127], v[0:1] op_sel_hi:[1,0]
	v_cvt_pk_bf16_f32 v8, v8, v9
	v_pk_mul_f32 v[10:11], v[10:11], v[12:13]
	v_pk_mul_f32 v[12:13], v[118:119], v[0:1] op_sel_hi:[1,0]
	v_cvt_pk_bf16_f32 v9, v10, v11
	global_store_dwordx2 v[50:51], v[8:9], off offset:16 sc0 sc1
	ds_read_b128 v[8:11], v73 offset:64
	s_waitcnt lgkmcnt(0)
	v_pk_mul_f32 v[8:9], v[8:9], v[12:13]
	v_pk_mul_f32 v[12:13], v[122:123], v[0:1] op_sel_hi:[1,0]
	v_cvt_pk_bf16_f32 v8, v8, v9
	v_pk_mul_f32 v[10:11], v[10:11], v[12:13]
	v_pk_mul_f32 v[12:13], v[62:63], v[0:1] op_sel_hi:[1,0]
	v_cvt_pk_bf16_f32 v9, v10, v11
	global_store_dwordx2 v[50:51], v[8:9], off offset:32 sc0 sc1
	ds_read_b128 v[8:11], v73 offset:96
	s_waitcnt lgkmcnt(0)
	v_pk_mul_f32 v[8:9], v[8:9], v[12:13]
	v_pk_mul_f32 v[12:13], v[64:65], v[0:1] op_sel_hi:[1,0]
	v_cvt_pk_bf16_f32 v8, v8, v9
	v_pk_mul_f32 v[10:11], v[10:11], v[12:13]
	v_pk_mul_f32 v[12:13], v[60:61], v[0:1] op_sel_hi:[1,0]
	v_cvt_pk_bf16_f32 v9, v10, v11
	global_store_dwordx2 v[50:51], v[8:9], off offset:48 sc0 sc1
	ds_read_b128 v[8:11], v73 offset:128
	s_waitcnt lgkmcnt(0)
	v_pk_mul_f32 v[8:9], v[8:9], v[12:13]
	v_pk_mul_f32 v[12:13], v[58:59], v[0:1] op_sel_hi:[1,0]
	v_cvt_pk_bf16_f32 v8, v8, v9
	v_pk_mul_f32 v[10:11], v[10:11], v[12:13]
	v_pk_mul_f32 v[12:13], v[56:57], v[0:1] op_sel_hi:[1,0]
	v_cvt_pk_bf16_f32 v9, v10, v11
	global_store_dwordx2 v[50:51], v[8:9], off offset:64 sc0 sc1
	ds_read_b128 v[8:11], v73 offset:160
	s_waitcnt lgkmcnt(0)
	v_pk_mul_f32 v[8:9], v[8:9], v[12:13]
	v_pk_mul_f32 v[12:13], v[52:53], v[0:1] op_sel_hi:[1,0]
	v_cvt_pk_bf16_f32 v8, v8, v9
	v_pk_mul_f32 v[10:11], v[10:11], v[12:13]
	v_pk_mul_f32 v[12:13], v[54:55], v[0:1] op_sel_hi:[1,0]
	v_cvt_pk_bf16_f32 v9, v10, v11
	global_store_dwordx2 v[50:51], v[8:9], off offset:80 sc0 sc1
	ds_read_b128 v[8:11], v73 offset:192
	s_waitcnt lgkmcnt(0)
	v_pk_mul_f32 v[8:9], v[8:9], v[12:13]
	v_pk_mul_f32 v[12:13], v[44:45], v[0:1] op_sel_hi:[1,0]
	v_cvt_pk_bf16_f32 v8, v8, v9
	v_pk_mul_f32 v[10:11], v[10:11], v[12:13]
	v_pk_mul_f32 v[12:13], v[46:47], v[0:1] op_sel_hi:[1,0]
	v_cvt_pk_bf16_f32 v9, v10, v11
	global_store_dwordx2 v[50:51], v[8:9], off offset:96 sc0 sc1
	ds_read_b128 v[8:11], v73 offset:224
	s_waitcnt lgkmcnt(0)
	v_pk_mul_f32 v[8:9], v[12:13], v[8:9]
	v_pk_mul_f32 v[12:13], v[42:43], v[0:1] op_sel_hi:[1,0]
	v_cvt_pk_bf16_f32 v8, v8, v9
	v_pk_mul_f32 v[10:11], v[12:13], v[10:11]
	v_pk_mul_f32 v[12:13], v[40:41], v[0:1] op_sel_hi:[1,0]
	v_cvt_pk_bf16_f32 v9, v10, v11
	global_store_dwordx2 v[50:51], v[8:9], off offset:112 sc0 sc1
	ds_read_b128 v[8:11], v73 offset:256
	s_waitcnt lgkmcnt(0)
	v_pk_mul_f32 v[8:9], v[12:13], v[8:9]
	v_pk_mul_f32 v[12:13], v[38:39], v[0:1] op_sel_hi:[1,0]
	v_cvt_pk_bf16_f32 v8, v8, v9
	v_pk_mul_f32 v[10:11], v[12:13], v[10:11]
	v_pk_mul_f32 v[12:13], v[36:37], v[0:1] op_sel_hi:[1,0]
	v_cvt_pk_bf16_f32 v9, v10, v11
	global_store_dwordx2 v[50:51], v[8:9], off offset:128 sc0 sc1
	ds_read_b128 v[8:11], v73 offset:288
	s_waitcnt lgkmcnt(0)
	v_pk_mul_f32 v[8:9], v[12:13], v[8:9]
	v_pk_mul_f32 v[12:13], v[34:35], v[0:1] op_sel_hi:[1,0]
	v_cvt_pk_bf16_f32 v8, v8, v9
	v_pk_mul_f32 v[10:11], v[12:13], v[10:11]
	v_pk_mul_f32 v[12:13], v[26:27], v[0:1] op_sel_hi:[1,0]
	v_cvt_pk_bf16_f32 v9, v10, v11
	global_store_dwordx2 v[50:51], v[8:9], off offset:144 sc0 sc1
	ds_read_b128 v[8:11], v73 offset:320
	s_waitcnt lgkmcnt(0)
	v_pk_mul_f32 v[8:9], v[12:13], v[8:9]
	v_pk_mul_f32 v[12:13], v[22:23], v[0:1] op_sel_hi:[1,0]
	v_cvt_pk_bf16_f32 v8, v8, v9
	v_pk_mul_f32 v[10:11], v[12:13], v[10:11]
	v_pk_mul_f32 v[12:13], v[24:25], v[0:1] op_sel_hi:[1,0]
	v_cvt_pk_bf16_f32 v9, v10, v11
	global_store_dwordx2 v[50:51], v[8:9], off offset:160 sc0 sc1
	ds_read_b128 v[8:11], v73 offset:352
	s_waitcnt lgkmcnt(0)
	v_pk_mul_f32 v[8:9], v[12:13], v[8:9]
	v_pk_mul_f32 v[12:13], v[18:19], v[0:1] op_sel_hi:[1,0]
	v_cvt_pk_bf16_f32 v8, v8, v9
	v_pk_mul_f32 v[10:11], v[12:13], v[10:11]
	v_pk_mul_f32 v[12:13], v[20:21], v[0:1] op_sel_hi:[1,0]
	v_cvt_pk_bf16_f32 v9, v10, v11
	global_store_dwordx2 v[50:51], v[8:9], off offset:176 sc0 sc1
	ds_read_b128 v[8:11], v73 offset:384
	s_waitcnt lgkmcnt(0)
	v_pk_mul_f32 v[8:9], v[12:13], v[8:9]
	v_pk_mul_f32 v[4:5], v[4:5], v[10:11]
	v_cvt_pk_bf16_f32 v8, v8, v9
	v_cvt_pk_bf16_f32 v9, v4, v5
	global_store_dwordx2 v[50:51], v[8:9], off offset:192 sc0 sc1
	ds_read_b128 v[8:11], v73 offset:416
	v_pk_mul_f32 v[4:5], v[6:7], v[0:1] op_sel_hi:[1,0]
	v_mov_b32_e32 v6, v70
	v_mov_b32_e32 v7, v68
	v_pk_mul_f32 v[6:7], v[6:7], v[0:1] op_sel_hi:[1,0]
	v_mov_b32_e32 v68, v71
	s_waitcnt lgkmcnt(0)
	v_pk_mul_f32 v[4:5], v[4:5], v[8:9]
	v_pk_mul_f32 v[2:3], v[2:3], v[10:11]
	v_cvt_pk_bf16_f32 v4, v4, v5
	v_cvt_pk_bf16_f32 v5, v2, v3
	global_store_dwordx2 v[50:51], v[4:5], off offset:208 sc0 sc1
	ds_read_b128 v[2:5], v73 offset:448
	s_waitcnt lgkmcnt(0)
	v_pk_mul_f32 v[2:3], v[6:7], v[2:3]
	v_pk_mul_f32 v[6:7], v[68:69], v[0:1] op_sel_hi:[1,0]
	v_cvt_pk_bf16_f32 v2, v2, v3
	v_pk_mul_f32 v[4:5], v[6:7], v[4:5]
	v_mov_b32_e32 v6, v66
	v_cvt_pk_bf16_f32 v3, v4, v5
	global_store_dwordx2 v[50:51], v[2:3], off offset:224 sc0 sc1
	ds_read_b128 v[2:5], v73 offset:480
	v_mov_b32_e32 v7, v14
	v_pk_mul_f32 v[6:7], v[6:7], v[0:1] op_sel_hi:[1,0]
	v_mov_b32_e32 v14, v67
	s_waitcnt lgkmcnt(0)
	v_pk_mul_f32 v[2:3], v[6:7], v[2:3]
	v_pk_mul_f32 v[6:7], v[14:15], v[0:1] op_sel_hi:[1,0]
	v_cvt_pk_bf16_f32 v2, v2, v3
	v_pk_mul_f32 v[4:5], v[6:7], v[4:5]
	s_nop 0
	v_cvt_pk_bf16_f32 v3, v4, v5
	global_store_dwordx2 v[50:51], v[2:3], off offset:240 sc0 sc1

; __device__ __forceinline__ void attention_phase(PPtr p, int layer, LAS unsigned char* L, unsigned* counter, const bool do_store) {
;     ...
;                 const float lt = l + __shfl_xor(l, 32);
;                 if (won && do_store) {
;                     const size_t tok = rowb + rho + (size_t)dd * (q0wv + r);
;                     float* po = (float*)((unsigned char*)p->out + DP_O) + ((size_t)g * M + tok) * 128 + hs * 64;
; #pragma unroll
;                     for (int db = 0; db < 2; ++db)
; #pragma unroll
;                         for (int c = 0; c < 4; ++c) *(f32x4*)(po + 32 * db + 8 * c + 4 * h) = (f32x4){o[db][4 * c], o[db][4 * c + 1], o[db][4 * c + 2], o[db][4 * c + 3]};
;                     if (h == 0) ((float*)((unsigned char*)p->out + DP_L))[((size_t)g * M + tok) * 2 + hs] = lt;
;                 }
.LBB0_547:
	ds_bpermute_b32 v0, v106, v108
	s_and_saveexec_b64 s[20:21], s[16:17]
	s_cbranch_execz .LBB0_528
	s_add_u32 s8, s75, s72
	s_addc_u32 s9, 0, 0
	s_waitcnt vmcnt(1)
	v_or_b32_e32 v4, v107, v231
	v_mov_b64_e32 v[2:3], s[8:9]
	v_mad_u64_u32 v[2:3], s[8:9], v4, s2, v[2:3]
	v_ashrrev_i32_e32 v5, 31, v107
	v_mov_b32_e32 v4, v3
	v_mad_u64_u32 v[4:5], s[8:9], v5, s2, v[4:5]
	v_mov_b32_e32 v3, v4
	v_lshlrev_b64 v[4:5], 9, v[2:3]
	v_lshl_add_u64 v[4:5], v[104:105], 0, v[4:5]
	global_store_dwordx4 v[4:5], v[32:35], off sc0 sc1
	global_store_dwordx4 v[4:5], v[36:39], off offset:32 sc0 sc1
	global_store_dwordx4 v[4:5], v[40:43], off offset:64 sc0 sc1
	global_store_dwordx4 v[4:5], v[44:47], off offset:96 sc0 sc1
	global_store_dwordx4 v[4:5], v[16:19], off offset:128 sc0 sc1
	global_store_dwordx4 v[4:5], v[20:23], off offset:160 sc0 sc1
	global_store_dwordx4 v[4:5], v[24:27], off offset:192 sc0 sc1
	global_store_dwordx4 v[4:5], v[28:31], off offset:224 sc0 sc1
	s_and_b64 exec, exec, s[14:15]
	s_cbranch_execz .LBB0_528
	s_waitcnt lgkmcnt(0)
	v_add_f32_e32 v0, v108, v0
	v_lshl_add_u64 v[2:3], v[2:3], 3, s[58:59]
	global_store_dword v[2:3], v0, off sc0 sc1
	s_branch .LBB0_528

; __device__ __forceinline__ unsigned pk2(float lo, float hi) { f32x2_t v = {lo, hi}; bf16x2_t b = __builtin_convertvector(v, bf16x2_t); return __builtin_bit_cast(unsigned, b); }
; __device__ __forceinline__ void store_o64(const f32x16 (&o)[2], float inv, bf16* orow, int h) {
; #pragma unroll
;     for (int db = 0; db < 2; ++db)
; #pragma unroll
;         for (int c = 0; c < 4; ++c) {
;             v2u w; w.x = pk2(o[db][4 * c] * inv, o[db][4 * c + 1] * inv); w.y = pk2(o[db][4 * c + 2] * inv, o[db][4 * c + 3] * inv);
;             *(v2u*)(orow + 32 * db + 8 * c + 4 * h) = w;
;         }
; }
; __device__ __forceinline__ void attention_phase(PPtr p, int layer, LAS unsigned char* L, unsigned* counter, const bool do_store) {
;     ...
;                 const float inv = 1.0f / (l + __shfl_xor(l, 32));
;                 if (do_store) store_o64(o, inv, QC + (size_t)(q0w_s + r) * 384, h);
.LBB0_568:
	ds_bpermute_b32 v0, v168, v172
	s_addk_i32 s2, 0xff00
	s_mov_b64 s[14:15], 0
	s_waitcnt lgkmcnt(0)
	v_add_f32_e32 v0, v172, v0
	v_div_scale_f32 v34, s[8:9], v0, v0, 1.0
	v_rcp_f32_e32 v35, v34
	s_nop 0
	v_fma_f32 v36, -v34, v35, 1.0
	v_fmac_f32_e32 v35, v36, v35
	v_div_scale_f32 v36, vcc, 1.0, v0, 1.0
	v_mul_f32_e32 v37, v36, v35
	v_fma_f32 v38, -v34, v37, v36
	v_fmac_f32_e32 v37, v38, v35
	v_fma_f32 v34, -v34, v37, v36
	v_div_fmas_f32 v34, v34, v35, v37
	v_div_fixup_f32 v0, v34, v0, 1.0
	v_or_b32_e32 v34, v171, v231
	v_pk_mul_f32 v[18:19], v[18:19], v[0:1] op_sel_hi:[1,0]
	v_pk_mul_f32 v[20:21], v[20:21], v[0:1] op_sel_hi:[1,0]
	v_pk_mul_f32 v[2:3], v[2:3], v[0:1] op_sel_hi:[1,0]
	v_pk_mul_f32 v[4:5], v[4:5], v[0:1] op_sel_hi:[1,0]
	v_mad_i64_i32 v[34:35], s[8:9], v34, s80, v[130:131]
	v_cvt_pk_bf16_f32 v18, v18, v19
	v_cvt_pk_bf16_f32 v19, v20, v21
	v_cvt_pk_bf16_f32 v2, v2, v3
	v_cvt_pk_bf16_f32 v3, v4, v5
	global_store_dwordx2 v[34:35], v[18:19], off sc0 sc1
	v_pk_mul_f32 v[18:19], v[22:23], v[0:1] op_sel_hi:[1,0]
	v_pk_mul_f32 v[20:21], v[24:25], v[0:1] op_sel_hi:[1,0]
	global_store_dwordx2 v[34:35], v[2:3], off offset:64 sc0 sc1
	v_pk_mul_f32 v[2:3], v[6:7], v[0:1] op_sel_hi:[1,0]
	v_pk_mul_f32 v[4:5], v[8:9], v[0:1] op_sel_hi:[1,0]
	v_cvt_pk_bf16_f32 v18, v18, v19
	v_cvt_pk_bf16_f32 v19, v20, v21
	v_cvt_pk_bf16_f32 v2, v2, v3
	v_cvt_pk_bf16_f32 v3, v4, v5
	global_store_dwordx2 v[34:35], v[18:19], off offset:16 sc0 sc1
	v_pk_mul_f32 v[18:19], v[26:27], v[0:1] op_sel_hi:[1,0]
	v_pk_mul_f32 v[20:21], v[28:29], v[0:1] op_sel_hi:[1,0]
	global_store_dwordx2 v[34:35], v[2:3], off offset:80 sc0 sc1
	v_pk_mul_f32 v[2:3], v[10:11], v[0:1] op_sel_hi:[1,0]
	v_pk_mul_f32 v[4:5], v[12:13], v[0:1] op_sel_hi:[1,0]
	v_cvt_pk_bf16_f32 v18, v18, v19
	v_cvt_pk_bf16_f32 v19, v20, v21
	v_cvt_pk_bf16_f32 v2, v2, v3
	v_cvt_pk_bf16_f32 v3, v4, v5
	global_store_dwordx2 v[34:35], v[18:19], off offset:32 sc0 sc1
	v_pk_mul_f32 v[18:19], v[30:31], v[0:1] op_sel_hi:[1,0]
	v_pk_mul_f32 v[20:21], v[32:33], v[0:1] op_sel_hi:[1,0]
	global_store_dwordx2 v[34:35], v[2:3], off offset:96 sc0 sc1
	v_pk_mul_f32 v[2:3], v[14:15], v[0:1] op_sel_hi:[1,0]
	v_pk_mul_f32 v[4:5], v[16:17], v[0:1] op_sel_hi:[1,0]
	v_cvt_pk_bf16_f32 v18, v18, v19
	v_cvt_pk_bf16_f32 v19, v20, v21
	v_cvt_pk_bf16_f32 v2, v2, v3
	v_cvt_pk_bf16_f32 v3, v4, v5
	s_mov_b32 s8, 1
	s_and_b64 vcc, exec, s[54:55]
	global_store_dwordx2 v[34:35], v[18:19], off offset:48 sc0 sc1
	global_store_dwordx2 v[34:35], v[2:3], off offset:112 sc0 sc1
	s_cbranch_vccnz .LBB0_606

; __device__ __forceinline__ unsigned pk2(float lo, float hi) { f32x2_t v = {lo, hi}; bf16x2_t b = __builtin_convertvector(v, bf16x2_t); return __builtin_bit_cast(unsigned, b); }
; __device__ __forceinline__ void store_o64(const f32x16 (&o)[2], float inv, bf16* orow, int h) {
; #pragma unroll
;     for (int db = 0; db < 2; ++db)
; #pragma unroll
;         for (int c = 0; c < 4; ++c) {
;             v2u w; w.x = pk2(o[db][4 * c] * inv, o[db][4 * c + 1] * inv); w.y = pk2(o[db][4 * c + 2] * inv, o[db][4 * c + 3] * inv);
;             *(v2u*)(orow + 32 * db + 8 * c + 4 * h) = w;
;         }
; }
; __device__ __forceinline__ void attention_phase(PPtr p, int layer, LAS unsigned char* L, unsigned* counter, const bool do_store) {
;     ...
;                 if (do_store) store_o64(o, 1.0f, QB + (size_t)(q0w_s + r) * 384, h);
.LBB0_609:
	v_or_b32_e32 v0, v137, v231
	v_mad_i64_i32 v[34:35], s[8:9], v0, s80, v[130:131]
	v_cvt_pk_bf16_f32 v18, v18, v19
	v_cvt_pk_bf16_f32 v19, v20, v21
	v_cvt_pk_bf16_f32 v2, v2, v3
	v_cvt_pk_bf16_f32 v3, v4, v5
	global_store_dwordx2 v[34:35], v[18:19], off sc0 sc1
	v_cvt_pk_bf16_f32 v18, v22, v23
	v_cvt_pk_bf16_f32 v19, v24, v25
	global_store_dwordx2 v[34:35], v[2:3], off offset:64 sc0 sc1
	v_cvt_pk_bf16_f32 v2, v6, v7
	v_cvt_pk_bf16_f32 v3, v8, v9
	global_store_dwordx2 v[34:35], v[18:19], off offset:16 sc0 sc1
	v_cvt_pk_bf16_f32 v18, v26, v27
	v_cvt_pk_bf16_f32 v19, v28, v29
	global_store_dwordx2 v[34:35], v[2:3], off offset:80 sc0 sc1
	v_cvt_pk_bf16_f32 v2, v10, v11
	v_cvt_pk_bf16_f32 v3, v12, v13
	global_store_dwordx2 v[34:35], v[18:19], off offset:32 sc0 sc1
	v_cvt_pk_bf16_f32 v18, v30, v31
	v_cvt_pk_bf16_f32 v19, v32, v33
	global_store_dwordx2 v[34:35], v[2:3], off offset:96 sc0 sc1
	v_cvt_pk_bf16_f32 v2, v14, v15
	v_cvt_pk_bf16_f32 v3, v16, v17
	s_mov_b32 s3, 1
	s_mov_b64 s[14:15], 0
	s_and_b64 vcc, exec, s[56:57]
	global_store_dwordx2 v[34:35], v[18:19], off offset:48 sc0 sc1
	global_store_dwordx2 v[34:35], v[2:3], off offset:112 sc0 sc1
	s_cbranch_vccnz .LBB0_639

; __device__ __forceinline__ unsigned pk2(float lo, float hi) { f32x2_t v = {lo, hi}; bf16x2_t b = __builtin_convertvector(v, bf16x2_t); return __builtin_bit_cast(unsigned, b); }
; __device__ __forceinline__ void dcombine_phase(float* dout, bf16* od) {
;     ...
;     for (int u = blockIdx.x * NTHREADS + tid; u < M * 32; u += gridDim.x * NTHREADS) {
;         const int tok = u >> 5, c0 = (u & 31) * 8;
;         v4u w = {0u, 0u, 0u, 0u};
;         if (c0 < 128) {
;             const int hs = c0 >> 6;
;             f32x4 a = {0.f, 0.f, 0.f, 0.f}, bq = a; float lsum = 0.f;
; #pragma unroll
;             for (int g = 0; g < 3; ++g) {
;                 const float* q = PO + ((size_t)g * M + tok) * 128 + c0;
;                 a = a + *(const f32x4*)q; bq = bq + *(const f32x4*)(q + 4);
;                 lsum += PL[((size_t)g * M + tok) * 2 + hs];
;             }
;             const float inv = 1.0f / lsum;
;             w.x = pk2(a[0] * inv, a[1] * inv); w.y = pk2(a[2] * inv, a[3] * inv); w.z = pk2(bq[0] * inv, bq[1] * inv); w.w = pk2(bq[2] * inv, bq[3] * inv);
;         }
;         *(v4u*)(od + (size_t)tok * 256 + c0) = w;
.LBB0_693:
	s_or_b64 exec, exec, s[12:13]
	v_add_u32_e32 v10, s64, v10
	s_mov_b32 s1, 0xfffff
	v_lshl_add_u64 v[6:7], s[6:7], 0, v[6:7]
	v_lshlrev_b32_e32 v0, 1, v12
	v_cmp_lt_i32_e32 vcc, s1, v10
	v_lshl_add_u64 v[6:7], v[6:7], 0, v[0:1]
	s_or_b64 s[10:11], vcc, s[10:11]
	v_add_u32_e32 v11, s68, v11
	global_store_dwordx4 v[6:7], v[2:5], off sc0 sc1
	s_andn2_b64 exec, exec, s[10:11]
	s_cbranch_execz .LBB0_698
